# GEMM K-loops: MFMA issue order changed so consecutive MFMAs share an operand (snake order)
# baseline (speedup 1.0000x reference)
; #define PG8_STAGE(bufoff, gbase, voff) do { _Pragma("unroll") for (int _i = 0; _i < 2; ++_i) \
;         __builtin_amdgcn_global_load_lds((const unsigned*)((const char*)(gbase) + (voff)[_i]), (LAS unsigned*)(lds + (bufoff) + ldsw + _i * 8192), 16, 0, 0); } while (0)
; #define PG8_LDA(dst, b, h) do { _Pragma("unroll") for (int m = 0; m < 4; ++m) _Pragma("unroll") for (int k = 0; k < 2; ++k) dst[m][k] = *(const LAS bf16x8*)(lds + PG8_SA(b, h) + aoff + m * 2048 + k * 1024); } while (0)
; #define PG8_LDB(dst, b, h) do { _Pragma("unroll") for (int n = 0; n < 2; ++n) _Pragma("unroll") for (int k = 0; k < 2; ++k) dst[n][k] = *(const LAS bf16x8*)(lds + PG8_SB(b, h) + boff + n * 2048 + k * 1024); } while (0)
; #define PG8_MMA(ai, bj, At, Bt) do { __builtin_amdgcn_s_setprio(1); _Pragma("unroll") for (int m = 0; m < 4; ++m) _Pragma("unroll") for (int n = 0; n < 2; ++n) _Pragma("unroll") for (int k = 0; k < 2; ++k) \
;         acc[ai][bj][m][n] = __builtin_amdgcn_mfma_f32_16x16x32_bf16(Bt[n][k], At[m][k], acc[ai][bj][m][n], 0, 0, 0); __builtin_amdgcn_s_setprio(0); } while (0)
; #define PG8_WAIT_V(n) asm volatile("s_waitcnt vmcnt(" #n ")" ::: "memory")
; #define PG8_WAIT_L(n) asm volatile("s_waitcnt lgkmcnt(" #n ")" ::: "memory")
; #define PG8_BAR __builtin_amdgcn_s_barrier()
; #define PG8_SCHED __builtin_amdgcn_sched_barrier(0)
; template <class Epi, bool ALIGN_EPI>
; __device__ __forceinline__ void gemm_phase(LAS unsigned char* lds, const Gemm g, const StaticOrder& S, const Epi& E, const int wave_s) {
;     ...
;         for (int t = 0; t < nt; t += 2) {
;             const bool last = (t == nt - 2);
;             const char* a1 = cA + (size_t)(t + 1) * kstep;
;             const char* a2 = last ? nA : cA + (size_t)(t + 2) * kstep; const char* b2 = last ? nB : cB + (size_t)(t + 2) * kstep;
;             const char* a3 = a2 + kstep; const char* b3 = b2 + kstep;
;             PG8_LDB(B0, 0, 0); PG8_LDB(B1, 0, 1); PG8_SCHED; PG8_LDA(At, 0, 0); PG8_STAGE(PG8_SA(1, 1), a1 + hstepA, voffA);
;             PG8_WAIT_V(8); PG8_WAIT_L(0); PG8_BAR; PG8_MMA(0, 0, At, B0); PG8_MMA(0, 1, At, B1); PG8_BAR; PG8_SCHED;
;             PG8_LDA(At, 0, 1); PG8_STAGE(PG8_SB(0, 0), b2, voffB); PG8_STAGE(PG8_SB(0, 1), b2 + hstepB, voffB); PG8_STAGE(PG8_SA(0, 0), a2, voffA);
;             PG8_WAIT_V(8); PG8_WAIT_L(0); PG8_BAR; PG8_MMA(1, 0, At, B0); PG8_MMA(1, 1, At, B1); PG8_BAR; PG8_SCHED;
.LBB0_108:
	s_add_i32 s55, s40, 2
	s_add_u32 s56, s38, 0x80
	s_addc_u32 s41, s39, 0
	s_add_i32 s58, 0, 0x10000
	s_cmp_eq_u32 s47, s40
	s_cselect_b32 s41, s29, s41
	s_cselect_b32 s40, s28, s56
	v_add_u32_e32 v138, s58, v141
	s_cselect_b32 s57, s37, s54
	s_cselect_b32 s56, s36, s53
	s_add_i32 s59, 0, 0x14000
	ds_read_b128 v[144:147], v138
	ds_read_b128 v[148:151], v138 offset:1024
	ds_read_b128 v[152:155], v138 offset:2048
	ds_read_b128 v[156:159], v138 offset:3072
	v_add_u32_e32 v138, s59, v141
	ds_read_b128 v[160:163], v138
	ds_read_b128 v[164:167], v138 offset:1024
	ds_read_b128 v[168:171], v138 offset:2048
	ds_read_b128 v[172:175], v138 offset:3072
	v_lshl_add_u64 v[138:139], s[38:39], 0, v[136:137]
	s_add_i32 m0, s24, 0xc000
	ds_read_b128 v[176:179], v143
	ds_read_b128 v[180:183], v143 offset:1024
	ds_read_b128 v[188:191], v143 offset:2048
	ds_read_b128 v[192:195], v143 offset:3072
	ds_read_b128 v[196:199], v143 offset:4096
	ds_read_b128 v[200:203], v143 offset:5120
	ds_read_b128 v[204:207], v143 offset:6144
	ds_read_b128 v[208:211], v143 offset:7168
	global_load_lds_dwordx4 v[138:139], off
	v_lshl_add_u64 v[138:139], s[38:39], 0, v[134:135]
	s_add_i32 m0, s24, 0xe000
	s_nop 0
	global_load_lds_dwordx4 v[138:139], off
	s_waitcnt vmcnt(8)
	s_waitcnt lgkmcnt(0)
	s_barrier
	s_setprio 1
	s_waitcnt lgkmcnt(0)
	v_mfma_f32_16x16x32_bf16 v[124:127], v[144:147], v[176:179], v[124:127]
	v_mfma_f32_16x16x32_bf16 v[120:123], v[152:155], v[176:179], v[120:123]
	v_mfma_f32_16x16x32_bf16 v[104:107], v[152:155], v[188:191], v[104:107]
	v_mfma_f32_16x16x32_bf16 v[108:111], v[144:147], v[188:191], v[108:111]
	v_mfma_f32_16x16x32_bf16 v[92:95], v[144:147], v[196:199], v[92:95]
	v_mfma_f32_16x16x32_bf16 v[88:91], v[152:155], v[196:199], v[88:91]
	v_mfma_f32_16x16x32_bf16 v[72:75], v[152:155], v[204:207], v[72:75]
	v_mfma_f32_16x16x32_bf16 v[76:79], v[144:147], v[204:207], v[76:79]
	v_mfma_f32_16x16x32_bf16 v[124:127], v[148:151], v[180:183], v[124:127]
	v_mfma_f32_16x16x32_bf16 v[120:123], v[156:159], v[180:183], v[120:123]
	v_mfma_f32_16x16x32_bf16 v[104:107], v[156:159], v[192:195], v[104:107]
	v_mfma_f32_16x16x32_bf16 v[108:111], v[148:151], v[192:195], v[108:111]
	v_mfma_f32_16x16x32_bf16 v[92:95], v[148:151], v[200:203], v[92:95]
	v_mfma_f32_16x16x32_bf16 v[88:91], v[156:159], v[200:203], v[88:91]
	v_mfma_f32_16x16x32_bf16 v[72:75], v[156:159], v[208:211], v[72:75]
	v_mfma_f32_16x16x32_bf16 v[76:79], v[148:151], v[208:211], v[76:79]
	s_setprio 0
	s_setprio 1
	v_mfma_f32_16x16x32_bf16 v[116:119], v[160:163], v[176:179], v[116:119]
	v_mfma_f32_16x16x32_bf16 v[112:115], v[168:171], v[176:179], v[112:115]
	v_mfma_f32_16x16x32_bf16 v[96:99], v[168:171], v[188:191], v[96:99]
	v_mfma_f32_16x16x32_bf16 v[100:103], v[160:163], v[188:191], v[100:103]
	v_mfma_f32_16x16x32_bf16 v[84:87], v[160:163], v[196:199], v[84:87]
	v_mfma_f32_16x16x32_bf16 v[80:83], v[168:171], v[196:199], v[80:83]
	v_mfma_f32_16x16x32_bf16 v[64:67], v[168:171], v[204:207], v[64:67]
	v_mfma_f32_16x16x32_bf16 v[68:71], v[160:163], v[204:207], v[68:71]
	v_mfma_f32_16x16x32_bf16 v[116:119], v[164:167], v[180:183], v[116:119]
	v_mfma_f32_16x16x32_bf16 v[112:115], v[172:175], v[180:183], v[112:115]
	v_mfma_f32_16x16x32_bf16 v[96:99], v[172:175], v[192:195], v[96:99]
	v_mfma_f32_16x16x32_bf16 v[100:103], v[164:167], v[192:195], v[100:103]
	v_mfma_f32_16x16x32_bf16 v[84:87], v[164:167], v[200:203], v[84:87]
	v_mfma_f32_16x16x32_bf16 v[80:83], v[172:175], v[200:203], v[80:83]
	v_mfma_f32_16x16x32_bf16 v[64:67], v[172:175], v[208:211], v[64:67]
	v_mfma_f32_16x16x32_bf16 v[68:71], v[164:167], v[208:211], v[68:71]
	s_setprio 0
	s_barrier
	s_add_i32 s58, s58, s4
	v_lshl_add_u64 v[138:139], s[56:57], 0, v[184:185]
	s_mov_b32 m0, s58
	ds_read_b128 v[176:179], v143 offset:16384
	ds_read_b128 v[180:183], v143 offset:17408
	ds_read_b128 v[188:191], v143 offset:18432
	ds_read_b128 v[192:195], v143 offset:19456
	ds_read_b128 v[196:199], v143 offset:20480
	ds_read_b128 v[200:203], v143 offset:21504
	ds_read_b128 v[204:207], v143 offset:22528
	ds_read_b128 v[208:211], v143 offset:23552
	global_load_lds_dwordx4 v[138:139], off
	s_add_i32 m0, s58, 0x2000
	v_lshl_add_u64 v[212:213], s[56:57], 0, v[128:129]
	s_add_u32 s56, s56, s10
	s_addc_u32 s57, s57, s11
	s_add_i32 s58, s59, s4
	global_load_lds_dwordx4 v[212:213], off
	v_lshl_add_u64 v[214:215], s[56:57], 0, v[184:185]
	s_mov_b32 m0, s58
	v_lshl_add_u64 v[216:217], s[56:57], 0, v[128:129]
	global_load_lds_dwordx4 v[214:215], off
	s_add_i32 m0, s58, 0x2000
	v_lshl_add_u64 v[218:219], s[40:41], 0, v[132:133]
	global_load_lds_dwordx4 v[216:217], off
	s_mov_b32 m0, s24
	v_lshl_add_u64 v[220:221], s[40:41], 0, v[130:131]
	global_load_lds_dwordx4 v[218:219], off
	s_mov_b32 m0, s25
	s_nop 0
	global_load_lds_dwordx4 v[220:221], off
	s_waitcnt vmcnt(8)
	s_waitcnt lgkmcnt(0)
	s_barrier
; #define PG8_STAGE(bufoff, gbase, voff) do { _Pragma("unroll") for (int _i = 0; _i < 2; ++_i) \
;         __builtin_amdgcn_global_load_lds((const unsigned*)((const char*)(gbase) + (voff)[_i]), (LAS unsigned*)(lds + (bufoff) + ldsw + _i * 8192), 16, 0, 0); } while (0)
; #define PG8_LDA(dst, b, h) do { _Pragma("unroll") for (int m = 0; m < 4; ++m) _Pragma("unroll") for (int k = 0; k < 2; ++k) dst[m][k] = *(const LAS bf16x8*)(lds + PG8_SA(b, h) + aoff + m * 2048 + k * 1024); } while (0)
; #define PG8_LDB(dst, b, h) do { _Pragma("unroll") for (int n = 0; n < 2; ++n) _Pragma("unroll") for (int k = 0; k < 2; ++k) dst[n][k] = *(const LAS bf16x8*)(lds + PG8_SB(b, h) + boff + n * 2048 + k * 1024); } while (0)
; #define PG8_MMA(ai, bj, At, Bt) do { __builtin_amdgcn_s_setprio(1); _Pragma("unroll") for (int m = 0; m < 4; ++m) _Pragma("unroll") for (int n = 0; n < 2; ++n) _Pragma("unroll") for (int k = 0; k < 2; ++k) \
;         acc[ai][bj][m][n] = __builtin_amdgcn_mfma_f32_16x16x32_bf16(Bt[n][k], At[m][k], acc[ai][bj][m][n], 0, 0, 0); __builtin_amdgcn_s_setprio(0); } while (0)
; #define PG8_WAIT_V(n) asm volatile("s_waitcnt vmcnt(" #n ")" ::: "memory")
; #define PG8_WAIT_L(n) asm volatile("s_waitcnt lgkmcnt(" #n ")" ::: "memory")
; #define PG8_BAR __builtin_amdgcn_s_barrier()
; #define PG8_SCHED __builtin_amdgcn_sched_barrier(0)
; template <class Epi, bool ALIGN_EPI>
; __device__ __forceinline__ void gemm_phase(LAS unsigned char* lds, const Gemm g, const StaticOrder& S, const Epi& E, const int wave_s) {
;     ...
;             PG8_WAIT_V(8); PG8_WAIT_L(0); PG8_BAR; PG8_MMA(1, 0, At, B0); PG8_MMA(1, 1, At, B1); PG8_BAR; PG8_SCHED;
;             PG8_LDB(B0, 1, 0); PG8_LDB(B1, 1, 1); PG8_SCHED; PG8_LDA(At, 1, 0); PG8_STAGE(PG8_SA(0, 1), a2 + hstepA, voffA);
;             PG8_WAIT_V(8); PG8_WAIT_L(0); PG8_BAR; PG8_MMA(0, 0, At, B0); PG8_MMA(0, 1, At, B1); PG8_BAR; PG8_SCHED;
	s_setprio 1
	s_waitcnt lgkmcnt(0)
	v_mfma_f32_16x16x32_bf16 v[60:63], v[144:147], v[176:179], v[60:63]
	v_mfma_f32_16x16x32_bf16 v[56:59], v[152:155], v[176:179], v[56:59]
	v_mfma_f32_16x16x32_bf16 v[40:43], v[152:155], v[188:191], v[40:43]
	v_mfma_f32_16x16x32_bf16 v[44:47], v[144:147], v[188:191], v[44:47]
	v_mfma_f32_16x16x32_bf16 v[28:31], v[144:147], v[196:199], v[28:31]
	v_mfma_f32_16x16x32_bf16 v[24:27], v[152:155], v[196:199], v[24:27]
	v_mfma_f32_16x16x32_bf16 v[8:11], v[152:155], v[204:207], v[8:11]
	v_mfma_f32_16x16x32_bf16 v[12:15], v[144:147], v[204:207], v[12:15]
	v_mfma_f32_16x16x32_bf16 v[60:63], v[148:151], v[180:183], v[60:63]
	v_mfma_f32_16x16x32_bf16 v[56:59], v[156:159], v[180:183], v[56:59]
	v_mfma_f32_16x16x32_bf16 v[40:43], v[156:159], v[192:195], v[40:43]
	v_mfma_f32_16x16x32_bf16 v[44:47], v[148:151], v[192:195], v[44:47]
	v_mfma_f32_16x16x32_bf16 v[28:31], v[148:151], v[200:203], v[28:31]
	v_mfma_f32_16x16x32_bf16 v[24:27], v[156:159], v[200:203], v[24:27]
	v_mfma_f32_16x16x32_bf16 v[8:11], v[156:159], v[208:211], v[8:11]
	v_mfma_f32_16x16x32_bf16 v[12:15], v[148:151], v[208:211], v[12:15]
	s_setprio 0
	s_setprio 1
	v_mfma_f32_16x16x32_bf16 v[52:55], v[160:163], v[176:179], v[52:55]
	v_mfma_f32_16x16x32_bf16 v[48:51], v[168:171], v[176:179], v[48:51]
	v_mfma_f32_16x16x32_bf16 v[32:35], v[168:171], v[188:191], v[32:35]
	v_mfma_f32_16x16x32_bf16 v[36:39], v[160:163], v[188:191], v[36:39]
	v_mfma_f32_16x16x32_bf16 v[20:23], v[160:163], v[196:199], v[20:23]
	v_mfma_f32_16x16x32_bf16 v[16:19], v[168:171], v[196:199], v[16:19]
	v_mfma_f32_16x16x32_bf16 v[0:3], v[168:171], v[204:207], v[0:3]
	v_mfma_f32_16x16x32_bf16 v[4:7], v[160:163], v[204:207], v[4:7]
	v_mfma_f32_16x16x32_bf16 v[52:55], v[164:167], v[180:183], v[52:55]
	v_mfma_f32_16x16x32_bf16 v[48:51], v[172:175], v[180:183], v[48:51]
	v_mfma_f32_16x16x32_bf16 v[32:35], v[172:175], v[192:195], v[32:35]
	v_mfma_f32_16x16x32_bf16 v[36:39], v[164:167], v[192:195], v[36:39]
	v_mfma_f32_16x16x32_bf16 v[20:23], v[164:167], v[200:203], v[20:23]
	v_mfma_f32_16x16x32_bf16 v[16:19], v[172:175], v[200:203], v[16:19]
	v_mfma_f32_16x16x32_bf16 v[0:3], v[172:175], v[208:211], v[0:3]
	v_mfma_f32_16x16x32_bf16 v[4:7], v[164:167], v[208:211], v[4:7]
	s_setprio 0
	s_barrier
	s_add_i32 s56, 0, 0x18000
	s_add_i32 s57, 0, 0x1c000
	v_add_u32_e32 v156, s56, v141
	v_add_u32_e32 v172, s57, v141
	ds_read_b128 v[144:147], v156
	ds_read_b128 v[148:151], v156 offset:1024
	ds_read_b128 v[152:155], v156 offset:2048
	ds_read_b128 v[156:159], v156 offset:3072
	ds_read_b128 v[160:163], v172
	ds_read_b128 v[164:167], v172 offset:1024
	ds_read_b128 v[168:171], v172 offset:2048
	ds_read_b128 v[172:175], v172 offset:3072
	s_add_u32 s40, s40, s8
	s_addc_u32 s41, s41, s9
	s_mov_b32 m0, s42
	v_lshl_add_u64 v[222:223], s[40:41], 0, v[132:133]
	ds_read_b128 v[176:179], v143 offset:32768
	ds_read_b128 v[180:183], v143 offset:33792
	ds_read_b128 v[188:191], v143 offset:34816
	ds_read_b128 v[192:195], v143 offset:35840
	ds_read_b128 v[196:199], v143 offset:36864
	ds_read_b128 v[200:203], v143 offset:37888
	ds_read_b128 v[204:207], v143 offset:38912
	ds_read_b128 v[208:211], v143 offset:39936
	global_load_lds_dwordx4 v[222:223], off
	v_lshl_add_u64 v[222:223], s[40:41], 0, v[130:131]
	s_mov_b32 m0, s43
	s_nop 0
	global_load_lds_dwordx4 v[222:223], off
	s_waitcnt vmcnt(8)
	s_waitcnt lgkmcnt(0)
	s_barrier
	s_setprio 1
	s_waitcnt lgkmcnt(0)
	v_mfma_f32_16x16x32_bf16 v[124:127], v[144:147], v[176:179], v[124:127]
	v_mfma_f32_16x16x32_bf16 v[120:123], v[152:155], v[176:179], v[120:123]
	v_mfma_f32_16x16x32_bf16 v[104:107], v[152:155], v[188:191], v[104:107]
	v_mfma_f32_16x16x32_bf16 v[108:111], v[144:147], v[188:191], v[108:111]
	v_mfma_f32_16x16x32_bf16 v[92:95], v[144:147], v[196:199], v[92:95]
	v_mfma_f32_16x16x32_bf16 v[88:91], v[152:155], v[196:199], v[88:91]
	v_mfma_f32_16x16x32_bf16 v[72:75], v[152:155], v[204:207], v[72:75]
	v_mfma_f32_16x16x32_bf16 v[76:79], v[144:147], v[204:207], v[76:79]
	v_mfma_f32_16x16x32_bf16 v[124:127], v[148:151], v[180:183], v[124:127]
	v_mfma_f32_16x16x32_bf16 v[120:123], v[156:159], v[180:183], v[120:123]
	v_mfma_f32_16x16x32_bf16 v[104:107], v[156:159], v[192:195], v[104:107]
	v_mfma_f32_16x16x32_bf16 v[108:111], v[148:151], v[192:195], v[108:111]
	v_mfma_f32_16x16x32_bf16 v[92:95], v[148:151], v[200:203], v[92:95]
	v_mfma_f32_16x16x32_bf16 v[88:91], v[156:159], v[200:203], v[88:91]
	v_mfma_f32_16x16x32_bf16 v[72:75], v[156:159], v[208:211], v[72:75]
	v_mfma_f32_16x16x32_bf16 v[76:79], v[148:151], v[208:211], v[76:79]
	s_setprio 0
	s_setprio 1
	v_mfma_f32_16x16x32_bf16 v[116:119], v[160:163], v[176:179], v[116:119]
	v_mfma_f32_16x16x32_bf16 v[112:115], v[168:171], v[176:179], v[112:115]
	v_mfma_f32_16x16x32_bf16 v[96:99], v[168:171], v[188:191], v[96:99]
	v_mfma_f32_16x16x32_bf16 v[100:103], v[160:163], v[188:191], v[100:103]
	v_mfma_f32_16x16x32_bf16 v[84:87], v[160:163], v[196:199], v[84:87]
	v_mfma_f32_16x16x32_bf16 v[80:83], v[168:171], v[196:199], v[80:83]
	v_mfma_f32_16x16x32_bf16 v[64:67], v[168:171], v[204:207], v[64:67]
	v_mfma_f32_16x16x32_bf16 v[68:71], v[160:163], v[204:207], v[68:71]
	v_mfma_f32_16x16x32_bf16 v[116:119], v[164:167], v[180:183], v[116:119]
	v_mfma_f32_16x16x32_bf16 v[112:115], v[172:175], v[180:183], v[112:115]
	v_mfma_f32_16x16x32_bf16 v[96:99], v[172:175], v[192:195], v[96:99]
	v_mfma_f32_16x16x32_bf16 v[100:103], v[164:167], v[192:195], v[100:103]
	v_mfma_f32_16x16x32_bf16 v[84:87], v[164:167], v[200:203], v[84:87]
	v_mfma_f32_16x16x32_bf16 v[80:83], v[172:175], v[200:203], v[80:83]
	v_mfma_f32_16x16x32_bf16 v[64:67], v[172:175], v[208:211], v[64:67]
	v_mfma_f32_16x16x32_bf16 v[68:71], v[164:167], v[208:211], v[68:71]
	s_setprio 0
	s_barrier
; #define PG8_STAGE(bufoff, gbase, voff) do { _Pragma("unroll") for (int _i = 0; _i < 2; ++_i) \
;         __builtin_amdgcn_global_load_lds((const unsigned*)((const char*)(gbase) + (voff)[_i]), (LAS unsigned*)(lds + (bufoff) + ldsw + _i * 8192), 16, 0, 0); } while (0)
; #define PG8_LDA(dst, b, h) do { _Pragma("unroll") for (int m = 0; m < 4; ++m) _Pragma("unroll") for (int k = 0; k < 2; ++k) dst[m][k] = *(const LAS bf16x8*)(lds + PG8_SA(b, h) + aoff + m * 2048 + k * 1024); } while (0)
; #define PG8_MMA(ai, bj, At, Bt) do { __builtin_amdgcn_s_setprio(1); _Pragma("unroll") for (int m = 0; m < 4; ++m) _Pragma("unroll") for (int n = 0; n < 2; ++n) _Pragma("unroll") for (int k = 0; k < 2; ++k) \
;         acc[ai][bj][m][n] = __builtin_amdgcn_mfma_f32_16x16x32_bf16(Bt[n][k], At[m][k], acc[ai][bj][m][n], 0, 0, 0); __builtin_amdgcn_s_setprio(0); } while (0)
; #define PG8_WAIT_V(n) asm volatile("s_waitcnt vmcnt(" #n ")" ::: "memory")
; #define PG8_WAIT_L(n) asm volatile("s_waitcnt lgkmcnt(" #n ")" ::: "memory")
; #define PG8_BAR __builtin_amdgcn_s_barrier()
; #define PG8_SCHED __builtin_amdgcn_sched_barrier(0)
; template <class Epi, bool ALIGN_EPI>
; __device__ __forceinline__ void gemm_phase(LAS unsigned char* lds, const Gemm g, const StaticOrder& S, const Epi& E, const int wave_s) {
;     ...
;             PG8_LDA(At, 1, 1); PG8_STAGE(PG8_SB(1, 0), b3, voffB); PG8_STAGE(PG8_SB(1, 1), b3 + hstepB, voffB); PG8_STAGE(PG8_SA(1, 0), a3, voffA);
;             PG8_WAIT_V(8); PG8_WAIT_L(0); PG8_BAR; PG8_MMA(1, 0, At, B0); PG8_MMA(1, 1, At, B1); PG8_BAR; PG8_SCHED;
;         }
	s_add_i32 s40, s56, s4
	v_lshl_add_u64 v[138:139], v[138:139], 0, s[64:65]
	s_mov_b32 m0, s40
	ds_read_b128 v[176:179], v143 offset:49152
	ds_read_b128 v[180:183], v143 offset:50176
	ds_read_b128 v[188:191], v143 offset:51200
	ds_read_b128 v[192:195], v143 offset:52224
	ds_read_b128 v[196:199], v143 offset:53248
	ds_read_b128 v[200:203], v143 offset:54272
	ds_read_b128 v[204:207], v143 offset:55296
	ds_read_b128 v[208:211], v143 offset:56320
	global_load_lds_dwordx4 v[138:139], off
	v_lshl_add_u64 v[138:139], v[212:213], 0, s[64:65]
	s_add_i32 m0, s40, 0x2000
	s_add_i32 s40, s57, s4
	global_load_lds_dwordx4 v[138:139], off
	v_lshl_add_u64 v[138:139], v[214:215], 0, s[64:65]
	s_mov_b32 m0, s40
	s_nop 0
	global_load_lds_dwordx4 v[138:139], off
	v_lshl_add_u64 v[138:139], v[216:217], 0, s[64:65]
	s_add_i32 m0, s40, 0x2000
	s_nop 0
	global_load_lds_dwordx4 v[138:139], off
	v_lshl_add_u64 v[138:139], v[218:219], 0, s[64:65]
	s_mov_b32 m0, s44
	s_nop 0
	global_load_lds_dwordx4 v[138:139], off
	v_lshl_add_u64 v[138:139], v[220:221], 0, s[64:65]
	s_mov_b32 m0, s45
	s_nop 0
	global_load_lds_dwordx4 v[138:139], off
	s_waitcnt vmcnt(8)
	s_waitcnt lgkmcnt(0)
	s_barrier
	s_setprio 1
	s_waitcnt lgkmcnt(0)
	v_mfma_f32_16x16x32_bf16 v[60:63], v[144:147], v[176:179], v[60:63]
	v_mfma_f32_16x16x32_bf16 v[56:59], v[152:155], v[176:179], v[56:59]
	v_mfma_f32_16x16x32_bf16 v[40:43], v[152:155], v[188:191], v[40:43]
	v_mfma_f32_16x16x32_bf16 v[44:47], v[144:147], v[188:191], v[44:47]
	v_mfma_f32_16x16x32_bf16 v[28:31], v[144:147], v[196:199], v[28:31]
	v_mfma_f32_16x16x32_bf16 v[24:27], v[152:155], v[196:199], v[24:27]
	v_mfma_f32_16x16x32_bf16 v[8:11], v[152:155], v[204:207], v[8:11]
	v_mfma_f32_16x16x32_bf16 v[12:15], v[144:147], v[204:207], v[12:15]
	v_mfma_f32_16x16x32_bf16 v[60:63], v[148:151], v[180:183], v[60:63]
	v_mfma_f32_16x16x32_bf16 v[56:59], v[156:159], v[180:183], v[56:59]
	v_mfma_f32_16x16x32_bf16 v[40:43], v[156:159], v[192:195], v[40:43]
	v_mfma_f32_16x16x32_bf16 v[44:47], v[148:151], v[192:195], v[44:47]
	v_mfma_f32_16x16x32_bf16 v[28:31], v[148:151], v[200:203], v[28:31]
	v_mfma_f32_16x16x32_bf16 v[24:27], v[156:159], v[200:203], v[24:27]
	v_mfma_f32_16x16x32_bf16 v[8:11], v[156:159], v[208:211], v[8:11]
	v_mfma_f32_16x16x32_bf16 v[12:15], v[148:151], v[208:211], v[12:15]
	s_setprio 0
	s_setprio 1
	v_mfma_f32_16x16x32_bf16 v[52:55], v[160:163], v[176:179], v[52:55]
	v_mfma_f32_16x16x32_bf16 v[48:51], v[168:171], v[176:179], v[48:51]
	v_mfma_f32_16x16x32_bf16 v[32:35], v[168:171], v[188:191], v[32:35]
	v_mfma_f32_16x16x32_bf16 v[36:39], v[160:163], v[188:191], v[36:39]
	v_mfma_f32_16x16x32_bf16 v[20:23], v[160:163], v[196:199], v[20:23]
	v_mfma_f32_16x16x32_bf16 v[16:19], v[168:171], v[196:199], v[16:19]
	v_mfma_f32_16x16x32_bf16 v[0:3], v[168:171], v[204:207], v[0:3]
	v_mfma_f32_16x16x32_bf16 v[4:7], v[160:163], v[204:207], v[4:7]
	v_mfma_f32_16x16x32_bf16 v[52:55], v[164:167], v[180:183], v[52:55]
	v_mfma_f32_16x16x32_bf16 v[48:51], v[172:175], v[180:183], v[48:51]
	v_mfma_f32_16x16x32_bf16 v[32:35], v[172:175], v[192:195], v[32:35]
	v_mfma_f32_16x16x32_bf16 v[36:39], v[164:167], v[192:195], v[36:39]
	v_mfma_f32_16x16x32_bf16 v[20:23], v[164:167], v[200:203], v[20:23]
	v_mfma_f32_16x16x32_bf16 v[16:19], v[172:175], v[200:203], v[16:19]
	v_mfma_f32_16x16x32_bf16 v[0:3], v[172:175], v[208:211], v[0:3]
	v_mfma_f32_16x16x32_bf16 v[4:7], v[164:167], v[208:211], v[4:7]
	s_setprio 0
	s_barrier
	s_add_u32 s53, s53, 0x100
	s_addc_u32 s54, s54, 0
	s_add_u32 s38, s38, 0x100
	s_addc_u32 s39, s39, 0
	s_cmp_ge_i32 s55, s46
	s_mov_b32 s40, s55
	s_cbranch_scc0 .LBB0_108
	s_and_b64 vcc, exec, s[20:21]
	s_cbranch_vccz .LBB0_111

; #define PG8_STAGE(bufoff, gbase, voff) do { _Pragma("unroll") for (int _i = 0; _i < 2; ++_i) \
;         __builtin_amdgcn_global_load_lds((const unsigned*)((const char*)(gbase) + (voff)[_i]), (LAS unsigned*)(lds + (bufoff) + ldsw + _i * 8192), 16, 0, 0); } while (0)
; #define PG8_LDA(dst, b, h) do { _Pragma("unroll") for (int m = 0; m < 4; ++m) _Pragma("unroll") for (int k = 0; k < 2; ++k) dst[m][k] = *(const LAS bf16x8*)(lds + PG8_SA(b, h) + aoff + m * 2048 + k * 1024); } while (0)
; #define PG8_LDB(dst, b, h) do { _Pragma("unroll") for (int n = 0; n < 2; ++n) _Pragma("unroll") for (int k = 0; k < 2; ++k) dst[n][k] = *(const LAS bf16x8*)(lds + PG8_SB(b, h) + boff + n * 2048 + k * 1024); } while (0)
; #define PG8_MMA(ai, bj, At, Bt) do { __builtin_amdgcn_s_setprio(1); _Pragma("unroll") for (int m = 0; m < 4; ++m) _Pragma("unroll") for (int n = 0; n < 2; ++n) _Pragma("unroll") for (int k = 0; k < 2; ++k) \
;         acc[ai][bj][m][n] = __builtin_amdgcn_mfma_f32_16x16x32_bf16(Bt[n][k], At[m][k], acc[ai][bj][m][n], 0, 0, 0); __builtin_amdgcn_s_setprio(0); } while (0)
; #define PG8_WAIT_V(n) asm volatile("s_waitcnt vmcnt(" #n ")" ::: "memory")
; #define PG8_WAIT_L(n) asm volatile("s_waitcnt lgkmcnt(" #n ")" ::: "memory")
; #define PG8_BAR __builtin_amdgcn_s_barrier()
; #define PG8_SCHED __builtin_amdgcn_sched_barrier(0)
; template <class Epi, bool ALIGN_EPI>
; __device__ __forceinline__ void gemm_phase(LAS unsigned char* lds, const Gemm g, const StaticOrder& S, const Epi& E, const int wave_s) {
;     ...
;         for (int t = 0; t < nt; t += 2) {
;             const bool last = (t == nt - 2);
;             const char* a1 = cA + (size_t)(t + 1) * kstep;
;             const char* a2 = last ? nA : cA + (size_t)(t + 2) * kstep; const char* b2 = last ? nB : cB + (size_t)(t + 2) * kstep;
;             const char* a3 = a2 + kstep; const char* b3 = b2 + kstep;
;             PG8_LDB(B0, 0, 0); PG8_LDB(B1, 0, 1); PG8_SCHED; PG8_LDA(At, 0, 0); PG8_STAGE(PG8_SA(1, 1), a1 + hstepA, voffA);
;             PG8_WAIT_V(8); PG8_WAIT_L(0); PG8_BAR; PG8_MMA(0, 0, At, B0); PG8_MMA(0, 1, At, B1); PG8_BAR; PG8_SCHED;
;             PG8_LDA(At, 0, 1); PG8_STAGE(PG8_SB(0, 0), b2, voffB); PG8_STAGE(PG8_SB(0, 1), b2 + hstepB, voffB); PG8_STAGE(PG8_SA(0, 0), a2, voffA);
;             PG8_WAIT_V(8); PG8_WAIT_L(0); PG8_BAR; PG8_MMA(1, 0, At, B0); PG8_MMA(1, 1, At, B1); PG8_BAR; PG8_SCHED;
.LBB0_138:
	s_add_i32 s55, s40, 2
	s_add_u32 s56, s38, 0x80
	s_addc_u32 s41, s39, 0
	s_add_i32 s58, 0, 0x10000
	s_cmp_eq_u32 s47, s40
	s_cselect_b32 s41, s1, s41
	s_cselect_b32 s40, s0, s56
	v_add_u32_e32 v142, s58, v145
	s_cselect_b32 s57, s29, s54
	s_cselect_b32 s56, s28, s53
	s_add_i32 s59, 0, 0x14000
	ds_read_b128 v[138:141], v142
	ds_read_b128 v[148:151], v142 offset:1024
	ds_read_b128 v[152:155], v142 offset:2048
	ds_read_b128 v[156:159], v142 offset:3072
	v_add_u32_e32 v142, s59, v145
	ds_read_b128 v[160:163], v142
	ds_read_b128 v[164:167], v142 offset:1024
	ds_read_b128 v[168:171], v142 offset:2048
	ds_read_b128 v[172:175], v142 offset:3072
	v_lshl_add_u64 v[142:143], s[38:39], 0, v[136:137]
	s_add_i32 m0, s24, 0xc000
	ds_read_b128 v[176:179], v147
	ds_read_b128 v[180:183], v147 offset:1024
	ds_read_b128 v[188:191], v147 offset:2048
	ds_read_b128 v[192:195], v147 offset:3072
	ds_read_b128 v[196:199], v147 offset:4096
	ds_read_b128 v[200:203], v147 offset:5120
	ds_read_b128 v[204:207], v147 offset:6144
	ds_read_b128 v[208:211], v147 offset:7168
	global_load_lds_dwordx4 v[142:143], off
	v_lshl_add_u64 v[142:143], s[38:39], 0, v[134:135]
	s_add_i32 m0, s24, 0xe000
	s_nop 0
	global_load_lds_dwordx4 v[142:143], off
	s_waitcnt vmcnt(8)
	s_waitcnt lgkmcnt(0)
	s_barrier
	s_setprio 1
	s_waitcnt lgkmcnt(0)
	v_mfma_f32_16x16x32_bf16 v[124:127], v[138:141], v[176:179], v[124:127]
	v_mfma_f32_16x16x32_bf16 v[120:123], v[152:155], v[176:179], v[120:123]
	v_mfma_f32_16x16x32_bf16 v[104:107], v[152:155], v[188:191], v[104:107]
	v_mfma_f32_16x16x32_bf16 v[108:111], v[138:141], v[188:191], v[108:111]
	v_mfma_f32_16x16x32_bf16 v[92:95], v[138:141], v[196:199], v[92:95]
	v_mfma_f32_16x16x32_bf16 v[88:91], v[152:155], v[196:199], v[88:91]
	v_mfma_f32_16x16x32_bf16 v[72:75], v[152:155], v[204:207], v[72:75]
	v_mfma_f32_16x16x32_bf16 v[76:79], v[138:141], v[204:207], v[76:79]
	v_mfma_f32_16x16x32_bf16 v[124:127], v[148:151], v[180:183], v[124:127]
	v_mfma_f32_16x16x32_bf16 v[120:123], v[156:159], v[180:183], v[120:123]
	v_mfma_f32_16x16x32_bf16 v[104:107], v[156:159], v[192:195], v[104:107]
	v_mfma_f32_16x16x32_bf16 v[108:111], v[148:151], v[192:195], v[108:111]
	v_mfma_f32_16x16x32_bf16 v[92:95], v[148:151], v[200:203], v[92:95]
	v_mfma_f32_16x16x32_bf16 v[88:91], v[156:159], v[200:203], v[88:91]
	v_mfma_f32_16x16x32_bf16 v[72:75], v[156:159], v[208:211], v[72:75]
	v_mfma_f32_16x16x32_bf16 v[76:79], v[148:151], v[208:211], v[76:79]
	s_setprio 0
	s_setprio 1
	v_mfma_f32_16x16x32_bf16 v[116:119], v[160:163], v[176:179], v[116:119]
	v_mfma_f32_16x16x32_bf16 v[112:115], v[168:171], v[176:179], v[112:115]
	v_mfma_f32_16x16x32_bf16 v[96:99], v[168:171], v[188:191], v[96:99]
	v_mfma_f32_16x16x32_bf16 v[100:103], v[160:163], v[188:191], v[100:103]
	v_mfma_f32_16x16x32_bf16 v[84:87], v[160:163], v[196:199], v[84:87]
	v_mfma_f32_16x16x32_bf16 v[80:83], v[168:171], v[196:199], v[80:83]
	v_mfma_f32_16x16x32_bf16 v[64:67], v[168:171], v[204:207], v[64:67]
	v_mfma_f32_16x16x32_bf16 v[68:71], v[160:163], v[204:207], v[68:71]
	v_mfma_f32_16x16x32_bf16 v[116:119], v[164:167], v[180:183], v[116:119]
	v_mfma_f32_16x16x32_bf16 v[112:115], v[172:175], v[180:183], v[112:115]
	v_mfma_f32_16x16x32_bf16 v[96:99], v[172:175], v[192:195], v[96:99]
	v_mfma_f32_16x16x32_bf16 v[100:103], v[164:167], v[192:195], v[100:103]
	v_mfma_f32_16x16x32_bf16 v[84:87], v[164:167], v[200:203], v[84:87]
	v_mfma_f32_16x16x32_bf16 v[80:83], v[172:175], v[200:203], v[80:83]
	v_mfma_f32_16x16x32_bf16 v[64:67], v[172:175], v[208:211], v[64:67]
	v_mfma_f32_16x16x32_bf16 v[68:71], v[164:167], v[208:211], v[68:71]
	s_setprio 0
	s_barrier
	s_add_i32 s58, s58, s4
	v_lshl_add_u64 v[142:143], s[56:57], 0, v[184:185]
	s_mov_b32 m0, s58
	ds_read_b128 v[176:179], v147 offset:16384
	ds_read_b128 v[180:183], v147 offset:17408
	ds_read_b128 v[188:191], v147 offset:18432
	ds_read_b128 v[192:195], v147 offset:19456
	ds_read_b128 v[196:199], v147 offset:20480
	ds_read_b128 v[200:203], v147 offset:21504
	ds_read_b128 v[204:207], v147 offset:22528
	ds_read_b128 v[208:211], v147 offset:23552
	global_load_lds_dwordx4 v[142:143], off
	s_add_i32 m0, s58, 0x2000
	v_lshl_add_u64 v[212:213], s[56:57], 0, v[128:129]
	s_add_u32 s56, s56, s10
	s_addc_u32 s57, s57, s11
	s_add_i32 s58, s59, s4
	global_load_lds_dwordx4 v[212:213], off
	v_lshl_add_u64 v[214:215], s[56:57], 0, v[184:185]
	s_mov_b32 m0, s58
	v_lshl_add_u64 v[216:217], s[56:57], 0, v[128:129]
	global_load_lds_dwordx4 v[214:215], off
	s_add_i32 m0, s58, 0x2000
	v_lshl_add_u64 v[218:219], s[40:41], 0, v[132:133]
	global_load_lds_dwordx4 v[216:217], off
	s_mov_b32 m0, s24
	v_lshl_add_u64 v[220:221], s[40:41], 0, v[130:131]
	global_load_lds_dwordx4 v[218:219], off
	s_mov_b32 m0, s25
	s_nop 0
	global_load_lds_dwordx4 v[220:221], off
	s_waitcnt vmcnt(8)
	s_waitcnt lgkmcnt(0)
	s_barrier
; #define PG8_STAGE(bufoff, gbase, voff) do { _Pragma("unroll") for (int _i = 0; _i < 2; ++_i) \
;         __builtin_amdgcn_global_load_lds((const unsigned*)((const char*)(gbase) + (voff)[_i]), (LAS unsigned*)(lds + (bufoff) + ldsw + _i * 8192), 16, 0, 0); } while (0)
; #define PG8_LDA(dst, b, h) do { _Pragma("unroll") for (int m = 0; m < 4; ++m) _Pragma("unroll") for (int k = 0; k < 2; ++k) dst[m][k] = *(const LAS bf16x8*)(lds + PG8_SA(b, h) + aoff + m * 2048 + k * 1024); } while (0)
; #define PG8_LDB(dst, b, h) do { _Pragma("unroll") for (int n = 0; n < 2; ++n) _Pragma("unroll") for (int k = 0; k < 2; ++k) dst[n][k] = *(const LAS bf16x8*)(lds + PG8_SB(b, h) + boff + n * 2048 + k * 1024); } while (0)
; #define PG8_MMA(ai, bj, At, Bt) do { __builtin_amdgcn_s_setprio(1); _Pragma("unroll") for (int m = 0; m < 4; ++m) _Pragma("unroll") for (int n = 0; n < 2; ++n) _Pragma("unroll") for (int k = 0; k < 2; ++k) \
;         acc[ai][bj][m][n] = __builtin_amdgcn_mfma_f32_16x16x32_bf16(Bt[n][k], At[m][k], acc[ai][bj][m][n], 0, 0, 0); __builtin_amdgcn_s_setprio(0); } while (0)
; #define PG8_WAIT_V(n) asm volatile("s_waitcnt vmcnt(" #n ")" ::: "memory")
; #define PG8_WAIT_L(n) asm volatile("s_waitcnt lgkmcnt(" #n ")" ::: "memory")
; #define PG8_BAR __builtin_amdgcn_s_barrier()
; #define PG8_SCHED __builtin_amdgcn_sched_barrier(0)
; template <class Epi, bool ALIGN_EPI>
; __device__ __forceinline__ void gemm_phase(LAS unsigned char* lds, const Gemm g, const StaticOrder& S, const Epi& E, const int wave_s) {
;     ...
;             PG8_WAIT_V(8); PG8_WAIT_L(0); PG8_BAR; PG8_MMA(1, 0, At, B0); PG8_MMA(1, 1, At, B1); PG8_BAR; PG8_SCHED;
;             PG8_LDB(B0, 1, 0); PG8_LDB(B1, 1, 1); PG8_SCHED; PG8_LDA(At, 1, 0); PG8_STAGE(PG8_SA(0, 1), a2 + hstepA, voffA);
;             PG8_WAIT_V(8); PG8_WAIT_L(0); PG8_BAR; PG8_MMA(0, 0, At, B0); PG8_MMA(0, 1, At, B1); PG8_BAR; PG8_SCHED;
	s_setprio 1
	s_waitcnt lgkmcnt(0)
	v_mfma_f32_16x16x32_bf16 v[60:63], v[138:141], v[176:179], v[60:63]
	v_mfma_f32_16x16x32_bf16 v[56:59], v[152:155], v[176:179], v[56:59]
	v_mfma_f32_16x16x32_bf16 v[40:43], v[152:155], v[188:191], v[40:43]
	v_mfma_f32_16x16x32_bf16 v[44:47], v[138:141], v[188:191], v[44:47]
	v_mfma_f32_16x16x32_bf16 v[28:31], v[138:141], v[196:199], v[28:31]
	v_mfma_f32_16x16x32_bf16 v[24:27], v[152:155], v[196:199], v[24:27]
	v_mfma_f32_16x16x32_bf16 v[8:11], v[152:155], v[204:207], v[8:11]
	v_mfma_f32_16x16x32_bf16 v[12:15], v[138:141], v[204:207], v[12:15]
	v_mfma_f32_16x16x32_bf16 v[60:63], v[148:151], v[180:183], v[60:63]
	v_mfma_f32_16x16x32_bf16 v[56:59], v[156:159], v[180:183], v[56:59]
	v_mfma_f32_16x16x32_bf16 v[40:43], v[156:159], v[192:195], v[40:43]
	v_mfma_f32_16x16x32_bf16 v[44:47], v[148:151], v[192:195], v[44:47]
	v_mfma_f32_16x16x32_bf16 v[28:31], v[148:151], v[200:203], v[28:31]
	v_mfma_f32_16x16x32_bf16 v[24:27], v[156:159], v[200:203], v[24:27]
	v_mfma_f32_16x16x32_bf16 v[8:11], v[156:159], v[208:211], v[8:11]
	v_mfma_f32_16x16x32_bf16 v[12:15], v[148:151], v[208:211], v[12:15]
	s_setprio 0
	s_setprio 1
	v_mfma_f32_16x16x32_bf16 v[52:55], v[160:163], v[176:179], v[52:55]
	v_mfma_f32_16x16x32_bf16 v[48:51], v[168:171], v[176:179], v[48:51]
	v_mfma_f32_16x16x32_bf16 v[32:35], v[168:171], v[188:191], v[32:35]
	v_mfma_f32_16x16x32_bf16 v[36:39], v[160:163], v[188:191], v[36:39]
	v_mfma_f32_16x16x32_bf16 v[20:23], v[160:163], v[196:199], v[20:23]
	v_mfma_f32_16x16x32_bf16 v[16:19], v[168:171], v[196:199], v[16:19]
	v_mfma_f32_16x16x32_bf16 v[0:3], v[168:171], v[204:207], v[0:3]
	v_mfma_f32_16x16x32_bf16 v[4:7], v[160:163], v[204:207], v[4:7]
	v_mfma_f32_16x16x32_bf16 v[52:55], v[164:167], v[180:183], v[52:55]
	v_mfma_f32_16x16x32_bf16 v[48:51], v[172:175], v[180:183], v[48:51]
	v_mfma_f32_16x16x32_bf16 v[32:35], v[172:175], v[192:195], v[32:35]
	v_mfma_f32_16x16x32_bf16 v[36:39], v[164:167], v[192:195], v[36:39]
	v_mfma_f32_16x16x32_bf16 v[20:23], v[164:167], v[200:203], v[20:23]
	v_mfma_f32_16x16x32_bf16 v[16:19], v[172:175], v[200:203], v[16:19]
	v_mfma_f32_16x16x32_bf16 v[0:3], v[172:175], v[208:211], v[0:3]
	v_mfma_f32_16x16x32_bf16 v[4:7], v[164:167], v[208:211], v[4:7]
	s_setprio 0
	s_barrier
	s_add_i32 s56, 0, 0x18000
	s_add_i32 s57, 0, 0x1c000
	v_add_u32_e32 v156, s56, v145
	v_add_u32_e32 v172, s57, v145
	ds_read_b128 v[138:141], v156
	ds_read_b128 v[148:151], v156 offset:1024
	ds_read_b128 v[152:155], v156 offset:2048
	ds_read_b128 v[156:159], v156 offset:3072
	ds_read_b128 v[160:163], v172
	ds_read_b128 v[164:167], v172 offset:1024
	ds_read_b128 v[168:171], v172 offset:2048
	ds_read_b128 v[172:175], v172 offset:3072
	s_add_u32 s40, s40, s8
	s_addc_u32 s41, s41, s9
	s_mov_b32 m0, s42
	v_lshl_add_u64 v[222:223], s[40:41], 0, v[132:133]
	ds_read_b128 v[176:179], v147 offset:32768
	ds_read_b128 v[180:183], v147 offset:33792
	ds_read_b128 v[188:191], v147 offset:34816
	ds_read_b128 v[192:195], v147 offset:35840
	ds_read_b128 v[196:199], v147 offset:36864
	ds_read_b128 v[200:203], v147 offset:37888
	ds_read_b128 v[204:207], v147 offset:38912
	ds_read_b128 v[208:211], v147 offset:39936
	global_load_lds_dwordx4 v[222:223], off
	v_lshl_add_u64 v[222:223], s[40:41], 0, v[130:131]
	s_mov_b32 m0, s43
	s_nop 0
	global_load_lds_dwordx4 v[222:223], off
	s_waitcnt vmcnt(8)
	s_waitcnt lgkmcnt(0)
	s_barrier
	s_setprio 1
	s_waitcnt lgkmcnt(0)
	v_mfma_f32_16x16x32_bf16 v[124:127], v[138:141], v[176:179], v[124:127]
	v_mfma_f32_16x16x32_bf16 v[120:123], v[152:155], v[176:179], v[120:123]
	v_mfma_f32_16x16x32_bf16 v[104:107], v[152:155], v[188:191], v[104:107]
	v_mfma_f32_16x16x32_bf16 v[108:111], v[138:141], v[188:191], v[108:111]
	v_mfma_f32_16x16x32_bf16 v[92:95], v[138:141], v[196:199], v[92:95]
	v_mfma_f32_16x16x32_bf16 v[88:91], v[152:155], v[196:199], v[88:91]
	v_mfma_f32_16x16x32_bf16 v[72:75], v[152:155], v[204:207], v[72:75]
	v_mfma_f32_16x16x32_bf16 v[76:79], v[138:141], v[204:207], v[76:79]
	v_mfma_f32_16x16x32_bf16 v[124:127], v[148:151], v[180:183], v[124:127]
	v_mfma_f32_16x16x32_bf16 v[120:123], v[156:159], v[180:183], v[120:123]
	v_mfma_f32_16x16x32_bf16 v[104:107], v[156:159], v[192:195], v[104:107]
	v_mfma_f32_16x16x32_bf16 v[108:111], v[148:151], v[192:195], v[108:111]
	v_mfma_f32_16x16x32_bf16 v[92:95], v[148:151], v[200:203], v[92:95]
	v_mfma_f32_16x16x32_bf16 v[88:91], v[156:159], v[200:203], v[88:91]
	v_mfma_f32_16x16x32_bf16 v[72:75], v[156:159], v[208:211], v[72:75]
	v_mfma_f32_16x16x32_bf16 v[76:79], v[148:151], v[208:211], v[76:79]
	s_setprio 0
	s_setprio 1
	v_mfma_f32_16x16x32_bf16 v[116:119], v[160:163], v[176:179], v[116:119]
	v_mfma_f32_16x16x32_bf16 v[112:115], v[168:171], v[176:179], v[112:115]
	v_mfma_f32_16x16x32_bf16 v[96:99], v[168:171], v[188:191], v[96:99]
	v_mfma_f32_16x16x32_bf16 v[100:103], v[160:163], v[188:191], v[100:103]
	v_mfma_f32_16x16x32_bf16 v[84:87], v[160:163], v[196:199], v[84:87]
	v_mfma_f32_16x16x32_bf16 v[80:83], v[168:171], v[196:199], v[80:83]
	v_mfma_f32_16x16x32_bf16 v[64:67], v[168:171], v[204:207], v[64:67]
	v_mfma_f32_16x16x32_bf16 v[68:71], v[160:163], v[204:207], v[68:71]
	v_mfma_f32_16x16x32_bf16 v[116:119], v[164:167], v[180:183], v[116:119]
	v_mfma_f32_16x16x32_bf16 v[112:115], v[172:175], v[180:183], v[112:115]
	v_mfma_f32_16x16x32_bf16 v[96:99], v[172:175], v[192:195], v[96:99]
	v_mfma_f32_16x16x32_bf16 v[100:103], v[164:167], v[192:195], v[100:103]
	v_mfma_f32_16x16x32_bf16 v[84:87], v[164:167], v[200:203], v[84:87]
	v_mfma_f32_16x16x32_bf16 v[80:83], v[172:175], v[200:203], v[80:83]
	v_mfma_f32_16x16x32_bf16 v[64:67], v[172:175], v[208:211], v[64:67]
	v_mfma_f32_16x16x32_bf16 v[68:71], v[164:167], v[208:211], v[68:71]
	s_setprio 0
	s_barrier
; #define PG8_STAGE(bufoff, gbase, voff) do { _Pragma("unroll") for (int _i = 0; _i < 2; ++_i) \
;         __builtin_amdgcn_global_load_lds((const unsigned*)((const char*)(gbase) + (voff)[_i]), (LAS unsigned*)(lds + (bufoff) + ldsw + _i * 8192), 16, 0, 0); } while (0)
; #define PG8_LDA(dst, b, h) do { _Pragma("unroll") for (int m = 0; m < 4; ++m) _Pragma("unroll") for (int k = 0; k < 2; ++k) dst[m][k] = *(const LAS bf16x8*)(lds + PG8_SA(b, h) + aoff + m * 2048 + k * 1024); } while (0)
; #define PG8_MMA(ai, bj, At, Bt) do { __builtin_amdgcn_s_setprio(1); _Pragma("unroll") for (int m = 0; m < 4; ++m) _Pragma("unroll") for (int n = 0; n < 2; ++n) _Pragma("unroll") for (int k = 0; k < 2; ++k) \
;         acc[ai][bj][m][n] = __builtin_amdgcn_mfma_f32_16x16x32_bf16(Bt[n][k], At[m][k], acc[ai][bj][m][n], 0, 0, 0); __builtin_amdgcn_s_setprio(0); } while (0)
; #define PG8_WAIT_V(n) asm volatile("s_waitcnt vmcnt(" #n ")" ::: "memory")
; #define PG8_WAIT_L(n) asm volatile("s_waitcnt lgkmcnt(" #n ")" ::: "memory")
; #define PG8_BAR __builtin_amdgcn_s_barrier()
; #define PG8_SCHED __builtin_amdgcn_sched_barrier(0)
; template <class Epi, bool ALIGN_EPI>
; __device__ __forceinline__ void gemm_phase(LAS unsigned char* lds, const Gemm g, const StaticOrder& S, const Epi& E, const int wave_s) {
;     ...
;             PG8_LDA(At, 1, 1); PG8_STAGE(PG8_SB(1, 0), b3, voffB); PG8_STAGE(PG8_SB(1, 1), b3 + hstepB, voffB); PG8_STAGE(PG8_SA(1, 0), a3, voffA);
;             PG8_WAIT_V(8); PG8_WAIT_L(0); PG8_BAR; PG8_MMA(1, 0, At, B0); PG8_MMA(1, 1, At, B1); PG8_BAR; PG8_SCHED;
;         }
	s_add_i32 s40, s56, s4
	v_lshl_add_u64 v[142:143], v[142:143], 0, s[64:65]
	s_mov_b32 m0, s40
	ds_read_b128 v[176:179], v147 offset:49152
	ds_read_b128 v[180:183], v147 offset:50176
	ds_read_b128 v[188:191], v147 offset:51200
	ds_read_b128 v[192:195], v147 offset:52224
	ds_read_b128 v[196:199], v147 offset:53248
	ds_read_b128 v[200:203], v147 offset:54272
	ds_read_b128 v[204:207], v147 offset:55296
	ds_read_b128 v[208:211], v147 offset:56320
	global_load_lds_dwordx4 v[142:143], off
	v_lshl_add_u64 v[142:143], v[212:213], 0, s[64:65]
	s_add_i32 m0, s40, 0x2000
	s_add_i32 s40, s57, s4
	global_load_lds_dwordx4 v[142:143], off
	v_lshl_add_u64 v[142:143], v[214:215], 0, s[64:65]
	s_mov_b32 m0, s40
	s_nop 0
	global_load_lds_dwordx4 v[142:143], off
	v_lshl_add_u64 v[142:143], v[216:217], 0, s[64:65]
	s_add_i32 m0, s40, 0x2000
	s_nop 0
	global_load_lds_dwordx4 v[142:143], off
	v_lshl_add_u64 v[142:143], v[218:219], 0, s[64:65]
	s_mov_b32 m0, s44
	s_nop 0
	global_load_lds_dwordx4 v[142:143], off
	v_lshl_add_u64 v[142:143], v[220:221], 0, s[64:65]
	s_mov_b32 m0, s45
	s_nop 0
	global_load_lds_dwordx4 v[142:143], off
	s_waitcnt vmcnt(8)
	s_waitcnt lgkmcnt(0)
	s_barrier
	s_setprio 1
	s_waitcnt lgkmcnt(0)
	v_mfma_f32_16x16x32_bf16 v[60:63], v[138:141], v[176:179], v[60:63]
	v_mfma_f32_16x16x32_bf16 v[56:59], v[152:155], v[176:179], v[56:59]
	v_mfma_f32_16x16x32_bf16 v[40:43], v[152:155], v[188:191], v[40:43]
	v_mfma_f32_16x16x32_bf16 v[44:47], v[138:141], v[188:191], v[44:47]
	v_mfma_f32_16x16x32_bf16 v[28:31], v[138:141], v[196:199], v[28:31]
	v_mfma_f32_16x16x32_bf16 v[24:27], v[152:155], v[196:199], v[24:27]
	v_mfma_f32_16x16x32_bf16 v[8:11], v[152:155], v[204:207], v[8:11]
	v_mfma_f32_16x16x32_bf16 v[12:15], v[138:141], v[204:207], v[12:15]
	v_mfma_f32_16x16x32_bf16 v[60:63], v[148:151], v[180:183], v[60:63]
	v_mfma_f32_16x16x32_bf16 v[56:59], v[156:159], v[180:183], v[56:59]
	v_mfma_f32_16x16x32_bf16 v[40:43], v[156:159], v[192:195], v[40:43]
	v_mfma_f32_16x16x32_bf16 v[44:47], v[148:151], v[192:195], v[44:47]
	v_mfma_f32_16x16x32_bf16 v[28:31], v[148:151], v[200:203], v[28:31]
	v_mfma_f32_16x16x32_bf16 v[24:27], v[156:159], v[200:203], v[24:27]
	v_mfma_f32_16x16x32_bf16 v[8:11], v[156:159], v[208:211], v[8:11]
	v_mfma_f32_16x16x32_bf16 v[12:15], v[148:151], v[208:211], v[12:15]
	s_setprio 0
	s_setprio 1
	v_mfma_f32_16x16x32_bf16 v[52:55], v[160:163], v[176:179], v[52:55]
	v_mfma_f32_16x16x32_bf16 v[48:51], v[168:171], v[176:179], v[48:51]
	v_mfma_f32_16x16x32_bf16 v[32:35], v[168:171], v[188:191], v[32:35]
	v_mfma_f32_16x16x32_bf16 v[36:39], v[160:163], v[188:191], v[36:39]
	v_mfma_f32_16x16x32_bf16 v[20:23], v[160:163], v[196:199], v[20:23]
	v_mfma_f32_16x16x32_bf16 v[16:19], v[168:171], v[196:199], v[16:19]
	v_mfma_f32_16x16x32_bf16 v[0:3], v[168:171], v[204:207], v[0:3]
	v_mfma_f32_16x16x32_bf16 v[4:7], v[160:163], v[204:207], v[4:7]
	v_mfma_f32_16x16x32_bf16 v[52:55], v[164:167], v[180:183], v[52:55]
	v_mfma_f32_16x16x32_bf16 v[48:51], v[172:175], v[180:183], v[48:51]
	v_mfma_f32_16x16x32_bf16 v[32:35], v[172:175], v[192:195], v[32:35]
	v_mfma_f32_16x16x32_bf16 v[36:39], v[164:167], v[192:195], v[36:39]
	v_mfma_f32_16x16x32_bf16 v[20:23], v[164:167], v[200:203], v[20:23]
	v_mfma_f32_16x16x32_bf16 v[16:19], v[172:175], v[200:203], v[16:19]
	v_mfma_f32_16x16x32_bf16 v[0:3], v[172:175], v[208:211], v[0:3]
	v_mfma_f32_16x16x32_bf16 v[4:7], v[164:167], v[208:211], v[4:7]
	s_setprio 0
	s_barrier
	s_add_u32 s53, s53, 0x100
	s_addc_u32 s54, s54, 0
	s_add_u32 s38, s38, 0x100
	s_addc_u32 s39, s39, 0
	s_cmp_ge_i32 s55, s46
	s_mov_b32 s40, s55
	s_cbranch_scc0 .LBB0_138
	s_and_b64 vcc, exec, s[20:21]
	s_cbranch_vccz .LBB0_141

; #define PG8_STAGE(bufoff, gbase, voff) do { _Pragma("unroll") for (int _i = 0; _i < 2; ++_i) \
;         __builtin_amdgcn_global_load_lds((const unsigned*)((const char*)(gbase) + (voff)[_i]), (LAS unsigned*)(lds + (bufoff) + ldsw + _i * 8192), 16, 0, 0); } while (0)
; #define PG8_LDA(dst, b, h) do { _Pragma("unroll") for (int m = 0; m < 4; ++m) _Pragma("unroll") for (int k = 0; k < 2; ++k) dst[m][k] = *(const LAS bf16x8*)(lds + PG8_SA(b, h) + aoff + m * 2048 + k * 1024); } while (0)
; #define PG8_LDB(dst, b, h) do { _Pragma("unroll") for (int n = 0; n < 2; ++n) _Pragma("unroll") for (int k = 0; k < 2; ++k) dst[n][k] = *(const LAS bf16x8*)(lds + PG8_SB(b, h) + boff + n * 2048 + k * 1024); } while (0)
; #define PG8_MMA(ai, bj, At, Bt) do { __builtin_amdgcn_s_setprio(1); _Pragma("unroll") for (int m = 0; m < 4; ++m) _Pragma("unroll") for (int n = 0; n < 2; ++n) _Pragma("unroll") for (int k = 0; k < 2; ++k) \
;         acc[ai][bj][m][n] = __builtin_amdgcn_mfma_f32_16x16x32_bf16(Bt[n][k], At[m][k], acc[ai][bj][m][n], 0, 0, 0); __builtin_amdgcn_s_setprio(0); } while (0)
; #define PG8_WAIT_V(n) asm volatile("s_waitcnt vmcnt(" #n ")" ::: "memory")
; #define PG8_WAIT_L(n) asm volatile("s_waitcnt lgkmcnt(" #n ")" ::: "memory")
; #define PG8_BAR __builtin_amdgcn_s_barrier()
; #define PG8_SCHED __builtin_amdgcn_sched_barrier(0)
; template <class Epi, bool ALIGN_EPI>
; __device__ __forceinline__ void gemm_phase(LAS unsigned char* lds, const Gemm g, const StaticOrder& S, const Epi& E, const int wave_s) {
;     ...
;         for (int t = 0; t < nt; t += 2) {
;             const bool last = (t == nt - 2);
;             const char* a1 = cA + (size_t)(t + 1) * kstep;
;             const char* a2 = last ? nA : cA + (size_t)(t + 2) * kstep; const char* b2 = last ? nB : cB + (size_t)(t + 2) * kstep;
;             const char* a3 = a2 + kstep; const char* b3 = b2 + kstep;
;             PG8_LDB(B0, 0, 0); PG8_LDB(B1, 0, 1); PG8_SCHED; PG8_LDA(At, 0, 0); PG8_STAGE(PG8_SA(1, 1), a1 + hstepA, voffA);
;             PG8_WAIT_V(8); PG8_WAIT_L(0); PG8_BAR; PG8_MMA(0, 0, At, B0); PG8_MMA(0, 1, At, B1); PG8_BAR; PG8_SCHED;
;             PG8_LDA(At, 0, 1); PG8_STAGE(PG8_SB(0, 0), b2, voffB); PG8_STAGE(PG8_SB(0, 1), b2 + hstepB, voffB); PG8_STAGE(PG8_SA(0, 0), a2, voffA);
;             PG8_WAIT_V(8); PG8_WAIT_L(0); PG8_BAR; PG8_MMA(1, 0, At, B0); PG8_MMA(1, 1, At, B1); PG8_BAR; PG8_SCHED;
.LBB0_180:
	s_add_i32 s40, s38, 2
	s_add_u32 s41, s0, 0x80
	s_addc_u32 s39, s1, 0
	s_add_i32 s45, 0, 0x10000
	s_cmp_eq_u32 s93, s38
	s_cselect_b32 s39, s69, s39
	s_cselect_b32 s38, s68, s41
	v_add_u32_e32 v20, s45, v212
	s_cselect_b32 s49, s71, s44
	s_cselect_b32 s48, s70, s43
	s_add_i32 s41, 0, 0x14000
	ds_read_b128 v[96:99], v20
	ds_read_b128 v[100:103], v20 offset:1024
	ds_read_b128 v[104:107], v20 offset:2048
	ds_read_b128 v[140:143], v20 offset:3072
	v_add_u32_e32 v20, s41, v212
	ds_read_b128 v[152:155], v20
	ds_read_b128 v[156:159], v20 offset:1024
	ds_read_b128 v[170:173], v20 offset:2048
	ds_read_b128 v[174:177], v20 offset:3072
	v_lshl_add_u64 v[20:21], s[0:1], 0, v[168:169]
	s_add_i32 m0, s82, 0xc000
	ds_read_b128 v[178:181], v213
	ds_read_b128 v[188:191], v213 offset:1024
	ds_read_b128 v[192:195], v213 offset:2048
	ds_read_b128 v[196:199], v213 offset:3072
	ds_read_b128 v[200:203], v213 offset:4096
	ds_read_b128 v[204:207], v213 offset:5120
	ds_read_b128 v[214:217], v213 offset:6144
	ds_read_b128 v[218:221], v213 offset:7168
	global_load_lds_dwordx4 v[20:21], off
	v_lshl_add_u64 v[20:21], s[0:1], 0, v[166:167]
	s_add_i32 m0, s82, 0xe000
	s_nop 0
	global_load_lds_dwordx4 v[20:21], off
	s_waitcnt vmcnt(8)
	s_waitcnt lgkmcnt(0)
	s_barrier
	s_setprio 1
	s_waitcnt lgkmcnt(0)
	v_mfma_f32_16x16x32_bf16 v[148:151], v[96:99], v[178:181], v[148:151]
	v_mfma_f32_16x16x32_bf16 v[52:55], v[104:107], v[178:181], v[54:57]
	v_mfma_f32_16x16x32_bf16 v[66:69], v[104:107], v[192:195], v[66:69]
	v_mfma_f32_16x16x32_bf16 v[144:147], v[96:99], v[192:195], v[144:147]
	v_mfma_f32_16x16x32_bf16 v[132:135], v[96:99], v[200:203], v[132:135]
	v_mfma_f32_16x16x32_bf16 v[56:59], v[104:107], v[200:203], v[58:61]
	v_mfma_f32_16x16x32_bf16 v[42:45], v[104:107], v[214:217], v[44:47]
	v_mfma_f32_16x16x32_bf16 v[124:127], v[96:99], v[214:217], v[124:127]
	v_mfma_f32_16x16x32_bf16 v[148:151], v[100:103], v[188:191], v[148:151]
	v_mfma_f32_16x16x32_bf16 v[52:55], v[140:143], v[188:191], v[52:55]
	v_mfma_f32_16x16x32_bf16 v[66:69], v[140:143], v[196:199], v[66:69]
	v_mfma_f32_16x16x32_bf16 v[144:147], v[100:103], v[196:199], v[144:147]
	v_mfma_f32_16x16x32_bf16 v[132:135], v[100:103], v[204:207], v[132:135]
	v_mfma_f32_16x16x32_bf16 v[58:61], v[140:143], v[204:207], v[56:59]
	v_mfma_f32_16x16x32_bf16 v[42:45], v[140:143], v[218:221], v[42:45]
	v_mfma_f32_16x16x32_bf16 v[124:127], v[100:103], v[218:221], v[124:127]
	s_setprio 0
	s_setprio 1
	v_mfma_f32_16x16x32_bf16 v[136:139], v[152:155], v[178:181], v[136:139]
	v_mfma_f32_16x16x32_bf16 v[62:65], v[170:173], v[178:181], v[62:65]
	v_mfma_f32_16x16x32_bf16 v[46:49], v[170:173], v[192:195], v[48:51]
	v_mfma_f32_16x16x32_bf16 v[128:131], v[152:155], v[192:195], v[128:131]
	v_mfma_f32_16x16x32_bf16 v[120:123], v[152:155], v[200:203], v[120:123]
	v_mfma_f32_16x16x32_bf16 v[38:41], v[170:173], v[200:203], v[38:41]
	v_mfma_f32_16x16x32_bf16 v[34:37], v[170:173], v[214:217], v[34:37]
	v_mfma_f32_16x16x32_bf16 v[116:119], v[152:155], v[214:217], v[116:119]
	v_mfma_f32_16x16x32_bf16 v[136:139], v[156:159], v[188:191], v[136:139]
	v_mfma_f32_16x16x32_bf16 v[62:65], v[174:177], v[188:191], v[62:65]
	v_mfma_f32_16x16x32_bf16 v[48:51], v[174:177], v[196:199], v[46:49]
	v_mfma_f32_16x16x32_bf16 v[128:131], v[156:159], v[196:199], v[128:131]
	v_mfma_f32_16x16x32_bf16 v[120:123], v[156:159], v[204:207], v[120:123]
	v_mfma_f32_16x16x32_bf16 v[38:41], v[174:177], v[204:207], v[38:41]
	v_mfma_f32_16x16x32_bf16 v[34:37], v[174:177], v[218:221], v[34:37]
	v_mfma_f32_16x16x32_bf16 v[116:119], v[156:159], v[218:221], v[116:119]
	s_setprio 0
	s_barrier
	s_add_i32 s45, s45, s4
	v_lshl_add_u64 v[182:183], s[48:49], 0, v[184:185]
	s_mov_b32 m0, s45
	ds_read_b128 v[178:181], v213 offset:16384
	ds_read_b128 v[188:191], v213 offset:17408
	ds_read_b128 v[192:195], v213 offset:18432
	ds_read_b128 v[196:199], v213 offset:19456
	ds_read_b128 v[200:203], v213 offset:20480
	ds_read_b128 v[204:207], v213 offset:21504
	ds_read_b128 v[214:217], v213 offset:22528
	ds_read_b128 v[218:221], v213 offset:23552
	global_load_lds_dwordx4 v[182:183], off
	s_add_i32 m0, s45, 0x2000
	v_lshl_add_u64 v[208:209], s[48:49], 0, v[160:161]
	s_add_u32 s48, s48, s16
	s_addc_u32 s49, s49, s17
	s_add_i32 s41, s41, s4
	global_load_lds_dwordx4 v[208:209], off
	v_lshl_add_u64 v[222:223], s[48:49], 0, v[184:185]
	s_mov_b32 m0, s41
	v_lshl_add_u64 v[224:225], s[48:49], 0, v[160:161]
	global_load_lds_dwordx4 v[222:223], off
	s_add_i32 m0, s41, 0x2000
	v_lshl_add_u64 v[226:227], s[38:39], 0, v[164:165]
	global_load_lds_dwordx4 v[224:225], off
	s_mov_b32 m0, s82
	v_lshl_add_u64 v[228:229], s[38:39], 0, v[162:163]
	global_load_lds_dwordx4 v[226:227], off
	s_mov_b32 m0, s95
	s_nop 0
	global_load_lds_dwordx4 v[228:229], off
	s_waitcnt vmcnt(8)
	s_waitcnt lgkmcnt(0)
	s_barrier
; #define PG8_STAGE(bufoff, gbase, voff) do { _Pragma("unroll") for (int _i = 0; _i < 2; ++_i) \
;         __builtin_amdgcn_global_load_lds((const unsigned*)((const char*)(gbase) + (voff)[_i]), (LAS unsigned*)(lds + (bufoff) + ldsw + _i * 8192), 16, 0, 0); } while (0)
; #define PG8_LDA(dst, b, h) do { _Pragma("unroll") for (int m = 0; m < 4; ++m) _Pragma("unroll") for (int k = 0; k < 2; ++k) dst[m][k] = *(const LAS bf16x8*)(lds + PG8_SA(b, h) + aoff + m * 2048 + k * 1024); } while (0)
; #define PG8_LDB(dst, b, h) do { _Pragma("unroll") for (int n = 0; n < 2; ++n) _Pragma("unroll") for (int k = 0; k < 2; ++k) dst[n][k] = *(const LAS bf16x8*)(lds + PG8_SB(b, h) + boff + n * 2048 + k * 1024); } while (0)
; #define PG8_MMA(ai, bj, At, Bt) do { __builtin_amdgcn_s_setprio(1); _Pragma("unroll") for (int m = 0; m < 4; ++m) _Pragma("unroll") for (int n = 0; n < 2; ++n) _Pragma("unroll") for (int k = 0; k < 2; ++k) \
;         acc[ai][bj][m][n] = __builtin_amdgcn_mfma_f32_16x16x32_bf16(Bt[n][k], At[m][k], acc[ai][bj][m][n], 0, 0, 0); __builtin_amdgcn_s_setprio(0); } while (0)
; #define PG8_WAIT_V(n) asm volatile("s_waitcnt vmcnt(" #n ")" ::: "memory")
; #define PG8_WAIT_L(n) asm volatile("s_waitcnt lgkmcnt(" #n ")" ::: "memory")
; #define PG8_BAR __builtin_amdgcn_s_barrier()
; #define PG8_SCHED __builtin_amdgcn_sched_barrier(0)
; template <class Epi, bool ALIGN_EPI>
; __device__ __forceinline__ void gemm_phase(LAS unsigned char* lds, const Gemm g, const StaticOrder& S, const Epi& E, const int wave_s) {
;     ...
;             PG8_WAIT_V(8); PG8_WAIT_L(0); PG8_BAR; PG8_MMA(1, 0, At, B0); PG8_MMA(1, 1, At, B1); PG8_BAR; PG8_SCHED;
;             PG8_LDB(B0, 1, 0); PG8_LDB(B1, 1, 1); PG8_SCHED; PG8_LDA(At, 1, 0); PG8_STAGE(PG8_SA(0, 1), a2 + hstepA, voffA);
;             PG8_WAIT_V(8); PG8_WAIT_L(0); PG8_BAR; PG8_MMA(0, 0, At, B0); PG8_MMA(0, 1, At, B1); PG8_BAR; PG8_SCHED;
	s_setprio 1
	s_waitcnt lgkmcnt(0)
	v_mfma_f32_16x16x32_bf16 v[112:115], v[96:99], v[178:181], v[112:115]
	v_mfma_f32_16x16x32_bf16 v[30:33], v[104:107], v[178:181], v[30:33]
	v_mfma_f32_16x16x32_bf16 v[26:29], v[104:107], v[192:195], v[26:29]
	v_mfma_f32_16x16x32_bf16 v[108:111], v[96:99], v[192:195], v[108:111]
	v_mfma_f32_16x16x32_bf16 v[88:91], v[96:99], v[200:203], v[88:91]
	v_mfma_f32_16x16x32_bf16 v[16:19], v[104:107], v[200:203], v[16:19]
	v_mfma_f32_16x16x32_bf16 v[8:11], v[104:107], v[214:217], v[8:11]
	v_mfma_f32_16x16x32_bf16 v[78:81], v[96:99], v[214:217], v[80:83]
	v_mfma_f32_16x16x32_bf16 v[112:115], v[100:103], v[188:191], v[112:115]
	v_mfma_f32_16x16x32_bf16 v[30:33], v[140:143], v[188:191], v[30:33]
	v_mfma_f32_16x16x32_bf16 v[26:29], v[140:143], v[196:199], v[26:29]
	v_mfma_f32_16x16x32_bf16 v[108:111], v[100:103], v[196:199], v[108:111]
	v_mfma_f32_16x16x32_bf16 v[88:91], v[100:103], v[204:207], v[88:91]
	v_mfma_f32_16x16x32_bf16 v[16:19], v[140:143], v[204:207], v[16:19]
	v_mfma_f32_16x16x32_bf16 v[8:11], v[140:143], v[218:221], v[8:11]
	v_mfma_f32_16x16x32_bf16 v[78:81], v[100:103], v[218:221], v[78:81]
	s_setprio 0
	s_setprio 1
	v_mfma_f32_16x16x32_bf16 v[92:95], v[152:155], v[178:181], v[92:95]
	v_mfma_f32_16x16x32_bf16 v[20:23], v[170:173], v[178:181], v[22:25]
	v_mfma_f32_16x16x32_bf16 v[12:15], v[170:173], v[192:195], v[12:15]
	v_mfma_f32_16x16x32_bf16 v[82:85], v[152:155], v[192:195], v[84:87]
	v_mfma_f32_16x16x32_bf16 v[74:77], v[152:155], v[200:203], v[74:77]
	v_mfma_f32_16x16x32_bf16 v[4:7], v[170:173], v[200:203], v[4:7]
	v_mfma_f32_16x16x32_bf16 v[0:3], v[170:173], v[214:217], v[0:3]
	v_mfma_f32_16x16x32_bf16 v[70:73], v[152:155], v[214:217], v[70:73]
	v_mfma_f32_16x16x32_bf16 v[92:95], v[156:159], v[188:191], v[92:95]
	v_mfma_f32_16x16x32_bf16 v[20:23], v[174:177], v[188:191], v[20:23]
	v_mfma_f32_16x16x32_bf16 v[12:15], v[174:177], v[196:199], v[12:15]
	v_mfma_f32_16x16x32_bf16 v[84:87], v[156:159], v[196:199], v[82:85]
	v_mfma_f32_16x16x32_bf16 v[74:77], v[156:159], v[204:207], v[74:77]
	v_mfma_f32_16x16x32_bf16 v[4:7], v[174:177], v[204:207], v[4:7]
	v_mfma_f32_16x16x32_bf16 v[0:3], v[174:177], v[218:221], v[0:3]
	v_mfma_f32_16x16x32_bf16 v[70:73], v[156:159], v[218:221], v[70:73]
	s_setprio 0
	s_barrier
	s_add_i32 s41, 0, 0x18000
	v_add_u32_e32 v24, s41, v212
	s_add_i32 s45, 0, 0x1c000
	ds_read_b128 v[96:99], v24
	ds_read_b128 v[100:103], v24 offset:1024
	ds_read_b128 v[104:107], v24 offset:2048
	ds_read_b128 v[140:143], v24 offset:3072
	v_add_u32_e32 v24, s45, v212
	ds_read_b128 v[152:155], v24
	ds_read_b128 v[156:159], v24 offset:1024
	ds_read_b128 v[170:173], v24 offset:2048
	ds_read_b128 v[174:177], v24 offset:3072
	s_add_u32 s38, s38, s14
	s_addc_u32 s39, s39, s15
	s_mov_b32 m0, s87
	v_lshl_add_u64 v[24:25], s[38:39], 0, v[164:165]
	ds_read_b128 v[178:181], v213 offset:32768
	ds_read_b128 v[188:191], v213 offset:33792
	ds_read_b128 v[192:195], v213 offset:34816
	ds_read_b128 v[196:199], v213 offset:35840
	ds_read_b128 v[200:203], v213 offset:36864
	ds_read_b128 v[204:207], v213 offset:37888
	ds_read_b128 v[214:217], v213 offset:38912
	ds_read_b128 v[218:221], v213 offset:39936
	global_load_lds_dwordx4 v[24:25], off
	v_lshl_add_u64 v[24:25], s[38:39], 0, v[162:163]
	s_mov_b32 m0, s24
	s_nop 0
	global_load_lds_dwordx4 v[24:25], off
	s_waitcnt vmcnt(8)
	s_waitcnt lgkmcnt(0)
	s_barrier
	s_setprio 1
	s_waitcnt lgkmcnt(0)
	v_mfma_f32_16x16x32_bf16 v[148:151], v[96:99], v[178:181], v[148:151]
	v_mfma_f32_16x16x32_bf16 v[52:55], v[104:107], v[178:181], v[52:55]
	v_mfma_f32_16x16x32_bf16 v[66:69], v[104:107], v[192:195], v[66:69]
	v_mfma_f32_16x16x32_bf16 v[144:147], v[96:99], v[192:195], v[144:147]
	v_mfma_f32_16x16x32_bf16 v[132:135], v[96:99], v[200:203], v[132:135]
	v_mfma_f32_16x16x32_bf16 v[58:61], v[104:107], v[200:203], v[58:61]
	v_mfma_f32_16x16x32_bf16 v[42:45], v[104:107], v[214:217], v[42:45]
	v_mfma_f32_16x16x32_bf16 v[124:127], v[96:99], v[214:217], v[124:127]
	v_mfma_f32_16x16x32_bf16 v[148:151], v[100:103], v[188:191], v[148:151]
	v_mfma_f32_16x16x32_bf16 v[54:57], v[140:143], v[188:191], v[52:55]
	v_mfma_f32_16x16x32_bf16 v[66:69], v[140:143], v[196:199], v[66:69]
	v_mfma_f32_16x16x32_bf16 v[144:147], v[100:103], v[196:199], v[144:147]
	v_mfma_f32_16x16x32_bf16 v[132:135], v[100:103], v[204:207], v[132:135]
	v_mfma_f32_16x16x32_bf16 v[58:61], v[140:143], v[204:207], v[58:61]
	v_mfma_f32_16x16x32_bf16 v[44:47], v[140:143], v[218:221], v[42:45]
	v_mfma_f32_16x16x32_bf16 v[124:127], v[100:103], v[218:221], v[124:127]
	s_setprio 0
	s_setprio 1
	v_mfma_f32_16x16x32_bf16 v[136:139], v[152:155], v[178:181], v[136:139]
	v_mfma_f32_16x16x32_bf16 v[62:65], v[170:173], v[178:181], v[62:65]
	v_mfma_f32_16x16x32_bf16 v[48:51], v[170:173], v[192:195], v[48:51]
	v_mfma_f32_16x16x32_bf16 v[128:131], v[152:155], v[192:195], v[128:131]
	v_mfma_f32_16x16x32_bf16 v[120:123], v[152:155], v[200:203], v[120:123]
	v_mfma_f32_16x16x32_bf16 v[38:41], v[170:173], v[200:203], v[38:41]
	v_mfma_f32_16x16x32_bf16 v[34:37], v[170:173], v[214:217], v[34:37]
	v_mfma_f32_16x16x32_bf16 v[116:119], v[152:155], v[214:217], v[116:119]
	v_mfma_f32_16x16x32_bf16 v[136:139], v[156:159], v[188:191], v[136:139]
	v_mfma_f32_16x16x32_bf16 v[62:65], v[174:177], v[188:191], v[62:65]
	v_mfma_f32_16x16x32_bf16 v[48:51], v[174:177], v[196:199], v[48:51]
	v_mfma_f32_16x16x32_bf16 v[128:131], v[156:159], v[196:199], v[128:131]
	v_mfma_f32_16x16x32_bf16 v[120:123], v[156:159], v[204:207], v[120:123]
	v_mfma_f32_16x16x32_bf16 v[38:41], v[174:177], v[204:207], v[38:41]
	v_mfma_f32_16x16x32_bf16 v[34:37], v[174:177], v[218:221], v[34:37]
	v_mfma_f32_16x16x32_bf16 v[116:119], v[156:159], v[218:221], v[116:119]
	s_setprio 0
	s_barrier
; #define PG8_STAGE(bufoff, gbase, voff) do { _Pragma("unroll") for (int _i = 0; _i < 2; ++_i) \
;         __builtin_amdgcn_global_load_lds((const unsigned*)((const char*)(gbase) + (voff)[_i]), (LAS unsigned*)(lds + (bufoff) + ldsw + _i * 8192), 16, 0, 0); } while (0)
; #define PG8_LDA(dst, b, h) do { _Pragma("unroll") for (int m = 0; m < 4; ++m) _Pragma("unroll") for (int k = 0; k < 2; ++k) dst[m][k] = *(const LAS bf16x8*)(lds + PG8_SA(b, h) + aoff + m * 2048 + k * 1024); } while (0)
; #define PG8_MMA(ai, bj, At, Bt) do { __builtin_amdgcn_s_setprio(1); _Pragma("unroll") for (int m = 0; m < 4; ++m) _Pragma("unroll") for (int n = 0; n < 2; ++n) _Pragma("unroll") for (int k = 0; k < 2; ++k) \
;         acc[ai][bj][m][n] = __builtin_amdgcn_mfma_f32_16x16x32_bf16(Bt[n][k], At[m][k], acc[ai][bj][m][n], 0, 0, 0); __builtin_amdgcn_s_setprio(0); } while (0)
; #define PG8_WAIT_V(n) asm volatile("s_waitcnt vmcnt(" #n ")" ::: "memory")
; #define PG8_WAIT_L(n) asm volatile("s_waitcnt lgkmcnt(" #n ")" ::: "memory")
; #define PG8_BAR __builtin_amdgcn_s_barrier()
; #define PG8_SCHED __builtin_amdgcn_sched_barrier(0)
; template <class Epi, bool ALIGN_EPI>
; __device__ __forceinline__ void gemm_phase(LAS unsigned char* lds, const Gemm g, const StaticOrder& S, const Epi& E, const int wave_s) {
;     ...
;             PG8_LDA(At, 1, 1); PG8_STAGE(PG8_SB(1, 0), b3, voffB); PG8_STAGE(PG8_SB(1, 1), b3 + hstepB, voffB); PG8_STAGE(PG8_SA(1, 0), a3, voffA);
;             PG8_WAIT_V(8); PG8_WAIT_L(0); PG8_BAR; PG8_MMA(1, 0, At, B0); PG8_MMA(1, 1, At, B1); PG8_BAR; PG8_SCHED;
;         }
	s_add_i32 s38, s41, s4
	v_lshl_add_u64 v[24:25], v[182:183], 0, s[64:65]
	s_mov_b32 m0, s38
	ds_read_b128 v[178:181], v213 offset:49152
	ds_read_b128 v[188:191], v213 offset:50176
	ds_read_b128 v[192:195], v213 offset:51200
	ds_read_b128 v[196:199], v213 offset:52224
	ds_read_b128 v[200:203], v213 offset:53248
	ds_read_b128 v[204:207], v213 offset:54272
	ds_read_b128 v[214:217], v213 offset:55296
	ds_read_b128 v[218:221], v213 offset:56320
	global_load_lds_dwordx4 v[24:25], off
	v_lshl_add_u64 v[24:25], v[208:209], 0, s[64:65]
	s_add_i32 m0, s38, 0x2000
	s_add_i32 s38, s45, s4
	global_load_lds_dwordx4 v[24:25], off
	v_lshl_add_u64 v[24:25], v[222:223], 0, s[64:65]
	s_mov_b32 m0, s38
	s_nop 0
	global_load_lds_dwordx4 v[24:25], off
	v_lshl_add_u64 v[24:25], v[224:225], 0, s[64:65]
	s_add_i32 m0, s38, 0x2000
	s_nop 0
	global_load_lds_dwordx4 v[24:25], off
	v_lshl_add_u64 v[24:25], v[226:227], 0, s[64:65]
	s_mov_b32 m0, s25
	s_nop 0
	global_load_lds_dwordx4 v[24:25], off
	v_lshl_add_u64 v[24:25], v[228:229], 0, s[64:65]
	s_mov_b32 m0, s86
	s_nop 0
	global_load_lds_dwordx4 v[24:25], off
	s_waitcnt vmcnt(8)
	s_waitcnt lgkmcnt(0)
	s_barrier
	s_setprio 1
	s_waitcnt lgkmcnt(0)
	v_mfma_f32_16x16x32_bf16 v[112:115], v[96:99], v[178:181], v[112:115]
	v_mfma_f32_16x16x32_bf16 v[30:33], v[104:107], v[178:181], v[30:33]
	v_mfma_f32_16x16x32_bf16 v[24:27], v[104:107], v[192:195], v[26:29]
	v_mfma_f32_16x16x32_bf16 v[108:111], v[96:99], v[192:195], v[108:111]
	v_mfma_f32_16x16x32_bf16 v[88:91], v[96:99], v[200:203], v[88:91]
	v_mfma_f32_16x16x32_bf16 v[16:19], v[104:107], v[200:203], v[16:19]
	v_mfma_f32_16x16x32_bf16 v[8:11], v[104:107], v[214:217], v[8:11]
	v_mfma_f32_16x16x32_bf16 v[78:81], v[96:99], v[214:217], v[78:81]
	v_mfma_f32_16x16x32_bf16 v[112:115], v[100:103], v[188:191], v[112:115]
	v_mfma_f32_16x16x32_bf16 v[30:33], v[140:143], v[188:191], v[30:33]
	v_mfma_f32_16x16x32_bf16 v[26:29], v[140:143], v[196:199], v[24:27]
	v_mfma_f32_16x16x32_bf16 v[108:111], v[100:103], v[196:199], v[108:111]
	v_mfma_f32_16x16x32_bf16 v[88:91], v[100:103], v[204:207], v[88:91]
	v_mfma_f32_16x16x32_bf16 v[16:19], v[140:143], v[204:207], v[16:19]
	v_mfma_f32_16x16x32_bf16 v[8:11], v[140:143], v[218:221], v[8:11]
	v_mfma_f32_16x16x32_bf16 v[80:83], v[100:103], v[218:221], v[78:81]
	s_setprio 0
	s_setprio 1
	v_mfma_f32_16x16x32_bf16 v[92:95], v[152:155], v[178:181], v[92:95]
	v_mfma_f32_16x16x32_bf16 v[20:23], v[170:173], v[178:181], v[20:23]
	v_mfma_f32_16x16x32_bf16 v[12:15], v[170:173], v[192:195], v[12:15]
	v_mfma_f32_16x16x32_bf16 v[84:87], v[152:155], v[192:195], v[84:87]
	v_mfma_f32_16x16x32_bf16 v[74:77], v[152:155], v[200:203], v[74:77]
	v_mfma_f32_16x16x32_bf16 v[4:7], v[170:173], v[200:203], v[4:7]
	v_mfma_f32_16x16x32_bf16 v[0:3], v[170:173], v[214:217], v[0:3]
	v_mfma_f32_16x16x32_bf16 v[70:73], v[152:155], v[214:217], v[70:73]
	v_mfma_f32_16x16x32_bf16 v[92:95], v[156:159], v[188:191], v[92:95]
	v_mfma_f32_16x16x32_bf16 v[22:25], v[174:177], v[188:191], v[20:23]
	v_mfma_f32_16x16x32_bf16 v[12:15], v[174:177], v[196:199], v[12:15]
	v_mfma_f32_16x16x32_bf16 v[84:87], v[156:159], v[196:199], v[84:87]
	v_mfma_f32_16x16x32_bf16 v[74:77], v[156:159], v[204:207], v[74:77]
	v_mfma_f32_16x16x32_bf16 v[4:7], v[174:177], v[204:207], v[4:7]
	v_mfma_f32_16x16x32_bf16 v[0:3], v[174:177], v[218:221], v[0:3]
	v_mfma_f32_16x16x32_bf16 v[70:73], v[156:159], v[218:221], v[70:73]
	s_setprio 0
	s_barrier
	s_add_u32 s43, s43, 0x100
	s_addc_u32 s44, s44, 0
	s_add_u32 s0, s0, 0x100
	s_addc_u32 s1, s1, 0
	s_cmp_ge_i32 s40, s63
	s_mov_b32 s38, s40
	s_cbranch_scc0 .LBB0_180
	s_branch .LBB0_182

; #define PG8_STAGE(bufoff, gbase, voff) do { _Pragma("unroll") for (int _i = 0; _i < 2; ++_i) \
;         __builtin_amdgcn_global_load_lds((const unsigned*)((const char*)(gbase) + (voff)[_i]), (LAS unsigned*)(lds + (bufoff) + ldsw + _i * 8192), 16, 0, 0); } while (0)
; #define PG8_LDA(dst, b, h) do { _Pragma("unroll") for (int m = 0; m < 4; ++m) _Pragma("unroll") for (int k = 0; k < 2; ++k) dst[m][k] = *(const LAS bf16x8*)(lds + PG8_SA(b, h) + aoff + m * 2048 + k * 1024); } while (0)
; #define PG8_LDB(dst, b, h) do { _Pragma("unroll") for (int n = 0; n < 2; ++n) _Pragma("unroll") for (int k = 0; k < 2; ++k) dst[n][k] = *(const LAS bf16x8*)(lds + PG8_SB(b, h) + boff + n * 2048 + k * 1024); } while (0)
; #define PG8_MMA(ai, bj, At, Bt) do { __builtin_amdgcn_s_setprio(1); _Pragma("unroll") for (int m = 0; m < 4; ++m) _Pragma("unroll") for (int n = 0; n < 2; ++n) _Pragma("unroll") for (int k = 0; k < 2; ++k) \
;         acc[ai][bj][m][n] = __builtin_amdgcn_mfma_f32_16x16x32_bf16(Bt[n][k], At[m][k], acc[ai][bj][m][n], 0, 0, 0); __builtin_amdgcn_s_setprio(0); } while (0)
; #define PG8_WAIT_V(n) asm volatile("s_waitcnt vmcnt(" #n ")" ::: "memory")
; #define PG8_WAIT_L(n) asm volatile("s_waitcnt lgkmcnt(" #n ")" ::: "memory")
; #define PG8_BAR __builtin_amdgcn_s_barrier()
; #define PG8_SCHED __builtin_amdgcn_sched_barrier(0)
; template <class Epi, bool ALIGN_EPI>
; __device__ __forceinline__ void gemm_phase(LAS unsigned char* lds, const Gemm g, const StaticOrder& S, const Epi& E, const int wave_s) {
;     ...
;         for (int t = 0; t < nt; t += 2) {
;             const bool last = (t == nt - 2);
;             const char* a1 = cA + (size_t)(t + 1) * kstep;
;             const char* a2 = last ? nA : cA + (size_t)(t + 2) * kstep; const char* b2 = last ? nB : cB + (size_t)(t + 2) * kstep;
;             const char* a3 = a2 + kstep; const char* b3 = b2 + kstep;
;             PG8_LDB(B0, 0, 0); PG8_LDB(B1, 0, 1); PG8_SCHED; PG8_LDA(At, 0, 0); PG8_STAGE(PG8_SA(1, 1), a1 + hstepA, voffA);
;             PG8_WAIT_V(8); PG8_WAIT_L(0); PG8_BAR; PG8_MMA(0, 0, At, B0); PG8_MMA(0, 1, At, B1); PG8_BAR; PG8_SCHED;
;             PG8_LDA(At, 0, 1); PG8_STAGE(PG8_SB(0, 0), b2, voffB); PG8_STAGE(PG8_SB(0, 1), b2 + hstepB, voffB); PG8_STAGE(PG8_SA(0, 0), a2, voffA);
;             PG8_WAIT_V(8); PG8_WAIT_L(0); PG8_BAR; PG8_MMA(1, 0, At, B0); PG8_MMA(1, 1, At, B1); PG8_BAR; PG8_SCHED;
.LBB0_355:
	s_add_i32 s57, s42, 2
	s_add_u32 s58, s40, 0x80
	s_addc_u32 s43, s41, 0
	s_add_i32 s60, 0, 0x10000
	s_cmp_eq_u32 s49, s42
	s_cselect_b32 s43, s1, s43
	s_cselect_b32 s42, s0, s58
	s_cselect_b32 s59, s29, s56
	s_cselect_b32 s58, s28, s55
	s_add_i32 s61, 0, 0x14000
	v_add_u32_e32 v150, s60, v161
	v_add_u32_e32 v158, s61, v161
	ds_read_b128 v[128:131], v150
	ds_read_b128 v[132:135], v150 offset:1024
	ds_read_b128 v[146:149], v150 offset:2048
	ds_read_b128 v[150:153], v150 offset:3072
	ds_read_b128 v[154:157], v158
	ds_read_b128 v[166:169], v158 offset:1024
	ds_read_b128 v[170:173], v158 offset:2048
	ds_read_b128 v[174:177], v158 offset:3072
	v_lshl_add_u64 v[158:159], s[40:41], 0, v[144:145]
	s_add_i32 m0, s24, 0xc000
	ds_read_b128 v[178:181], v165
	ds_read_b128 v[188:191], v165 offset:1024
	ds_read_b128 v[192:195], v165 offset:2048
	ds_read_b128 v[196:199], v165 offset:3072
	ds_read_b128 v[200:203], v165 offset:4096
	ds_read_b128 v[204:207], v165 offset:5120
	ds_read_b128 v[208:211], v165 offset:6144
	ds_read_b128 v[212:215], v165 offset:7168
	global_load_lds_dwordx4 v[158:159], off
	v_lshl_add_u64 v[158:159], s[40:41], 0, v[142:143]
	s_add_i32 m0, s24, 0xe000
	s_nop 0
	global_load_lds_dwordx4 v[158:159], off
	s_waitcnt vmcnt(8)
	s_waitcnt lgkmcnt(0)
	s_barrier
	s_setprio 1
	s_waitcnt lgkmcnt(0)
	v_mfma_f32_16x16x32_bf16 v[124:127], v[128:131], v[178:181], v[124:127]
	v_mfma_f32_16x16x32_bf16 v[120:123], v[146:149], v[178:181], v[120:123]
	v_mfma_f32_16x16x32_bf16 v[104:107], v[146:149], v[192:195], v[104:107]
	v_mfma_f32_16x16x32_bf16 v[108:111], v[128:131], v[192:195], v[108:111]
	v_mfma_f32_16x16x32_bf16 v[92:95], v[128:131], v[200:203], v[92:95]
	v_mfma_f32_16x16x32_bf16 v[88:91], v[146:149], v[200:203], v[88:91]
	v_mfma_f32_16x16x32_bf16 v[72:75], v[146:149], v[208:211], v[72:75]
	v_mfma_f32_16x16x32_bf16 v[76:79], v[128:131], v[208:211], v[76:79]
	v_mfma_f32_16x16x32_bf16 v[124:127], v[132:135], v[188:191], v[124:127]
	v_mfma_f32_16x16x32_bf16 v[120:123], v[150:153], v[188:191], v[120:123]
	v_mfma_f32_16x16x32_bf16 v[104:107], v[150:153], v[196:199], v[104:107]
	v_mfma_f32_16x16x32_bf16 v[108:111], v[132:135], v[196:199], v[108:111]
	v_mfma_f32_16x16x32_bf16 v[92:95], v[132:135], v[204:207], v[92:95]
	v_mfma_f32_16x16x32_bf16 v[88:91], v[150:153], v[204:207], v[88:91]
	v_mfma_f32_16x16x32_bf16 v[72:75], v[150:153], v[212:215], v[72:75]
	v_mfma_f32_16x16x32_bf16 v[76:79], v[132:135], v[212:215], v[76:79]
	s_setprio 0
	s_setprio 1
	v_mfma_f32_16x16x32_bf16 v[116:119], v[154:157], v[178:181], v[116:119]
	v_mfma_f32_16x16x32_bf16 v[112:115], v[170:173], v[178:181], v[112:115]
	v_mfma_f32_16x16x32_bf16 v[96:99], v[170:173], v[192:195], v[96:99]
	v_mfma_f32_16x16x32_bf16 v[100:103], v[154:157], v[192:195], v[100:103]
	v_mfma_f32_16x16x32_bf16 v[84:87], v[154:157], v[200:203], v[84:87]
	v_mfma_f32_16x16x32_bf16 v[80:83], v[170:173], v[200:203], v[80:83]
	v_mfma_f32_16x16x32_bf16 v[64:67], v[170:173], v[208:211], v[64:67]
	v_mfma_f32_16x16x32_bf16 v[68:71], v[154:157], v[208:211], v[68:71]
	v_mfma_f32_16x16x32_bf16 v[116:119], v[166:169], v[188:191], v[116:119]
	v_mfma_f32_16x16x32_bf16 v[112:115], v[174:177], v[188:191], v[112:115]
	v_mfma_f32_16x16x32_bf16 v[96:99], v[174:177], v[196:199], v[96:99]
	v_mfma_f32_16x16x32_bf16 v[100:103], v[166:169], v[196:199], v[100:103]
	v_mfma_f32_16x16x32_bf16 v[84:87], v[166:169], v[204:207], v[84:87]
	v_mfma_f32_16x16x32_bf16 v[80:83], v[174:177], v[204:207], v[80:83]
	v_mfma_f32_16x16x32_bf16 v[64:67], v[174:177], v[212:215], v[64:67]
	v_mfma_f32_16x16x32_bf16 v[68:71], v[166:169], v[212:215], v[68:71]
	s_setprio 0
	s_barrier
	s_add_i32 s60, s60, s4
	v_lshl_add_u64 v[158:159], s[58:59], 0, v[184:185]
	s_mov_b32 m0, s60
	ds_read_b128 v[178:181], v165 offset:16384
	ds_read_b128 v[188:191], v165 offset:17408
	ds_read_b128 v[192:195], v165 offset:18432
	ds_read_b128 v[196:199], v165 offset:19456
	ds_read_b128 v[200:203], v165 offset:20480
	ds_read_b128 v[204:207], v165 offset:21504
	ds_read_b128 v[208:211], v165 offset:22528
	ds_read_b128 v[212:215], v165 offset:23552
	global_load_lds_dwordx4 v[158:159], off
	s_add_i32 m0, s60, 0x2000
	v_lshl_add_u64 v[182:183], s[58:59], 0, v[136:137]
	s_add_u32 s58, s58, s10
	s_addc_u32 s59, s59, s11
	s_add_i32 s60, s61, s4
	global_load_lds_dwordx4 v[182:183], off
	v_lshl_add_u64 v[216:217], s[58:59], 0, v[184:185]
	s_mov_b32 m0, s60
	v_lshl_add_u64 v[218:219], s[58:59], 0, v[136:137]
	global_load_lds_dwordx4 v[216:217], off
	s_add_i32 m0, s60, 0x2000
	v_lshl_add_u64 v[220:221], s[42:43], 0, v[140:141]
	global_load_lds_dwordx4 v[218:219], off
	s_mov_b32 m0, s24
	v_lshl_add_u64 v[222:223], s[42:43], 0, v[138:139]
	global_load_lds_dwordx4 v[220:221], off
	s_mov_b32 m0, s25
	s_nop 0
	global_load_lds_dwordx4 v[222:223], off
	s_waitcnt vmcnt(8)
	s_waitcnt lgkmcnt(0)
	s_barrier
; #define PG8_STAGE(bufoff, gbase, voff) do { _Pragma("unroll") for (int _i = 0; _i < 2; ++_i) \
;         __builtin_amdgcn_global_load_lds((const unsigned*)((const char*)(gbase) + (voff)[_i]), (LAS unsigned*)(lds + (bufoff) + ldsw + _i * 8192), 16, 0, 0); } while (0)
; #define PG8_LDA(dst, b, h) do { _Pragma("unroll") for (int m = 0; m < 4; ++m) _Pragma("unroll") for (int k = 0; k < 2; ++k) dst[m][k] = *(const LAS bf16x8*)(lds + PG8_SA(b, h) + aoff + m * 2048 + k * 1024); } while (0)
; #define PG8_LDB(dst, b, h) do { _Pragma("unroll") for (int n = 0; n < 2; ++n) _Pragma("unroll") for (int k = 0; k < 2; ++k) dst[n][k] = *(const LAS bf16x8*)(lds + PG8_SB(b, h) + boff + n * 2048 + k * 1024); } while (0)
; #define PG8_MMA(ai, bj, At, Bt) do { __builtin_amdgcn_s_setprio(1); _Pragma("unroll") for (int m = 0; m < 4; ++m) _Pragma("unroll") for (int n = 0; n < 2; ++n) _Pragma("unroll") for (int k = 0; k < 2; ++k) \
;         acc[ai][bj][m][n] = __builtin_amdgcn_mfma_f32_16x16x32_bf16(Bt[n][k], At[m][k], acc[ai][bj][m][n], 0, 0, 0); __builtin_amdgcn_s_setprio(0); } while (0)
; #define PG8_WAIT_V(n) asm volatile("s_waitcnt vmcnt(" #n ")" ::: "memory")
; #define PG8_WAIT_L(n) asm volatile("s_waitcnt lgkmcnt(" #n ")" ::: "memory")
; #define PG8_BAR __builtin_amdgcn_s_barrier()
; #define PG8_SCHED __builtin_amdgcn_sched_barrier(0)
; template <class Epi, bool ALIGN_EPI>
; __device__ __forceinline__ void gemm_phase(LAS unsigned char* lds, const Gemm g, const StaticOrder& S, const Epi& E, const int wave_s) {
;     ...
;             PG8_WAIT_V(8); PG8_WAIT_L(0); PG8_BAR; PG8_MMA(1, 0, At, B0); PG8_MMA(1, 1, At, B1); PG8_BAR; PG8_SCHED;
;             PG8_LDB(B0, 1, 0); PG8_LDB(B1, 1, 1); PG8_SCHED; PG8_LDA(At, 1, 0); PG8_STAGE(PG8_SA(0, 1), a2 + hstepA, voffA);
;             PG8_WAIT_V(8); PG8_WAIT_L(0); PG8_BAR; PG8_MMA(0, 0, At, B0); PG8_MMA(0, 1, At, B1); PG8_BAR; PG8_SCHED;
	s_setprio 1
	s_waitcnt lgkmcnt(0)
	v_mfma_f32_16x16x32_bf16 v[60:63], v[128:131], v[178:181], v[60:63]
	v_mfma_f32_16x16x32_bf16 v[56:59], v[146:149], v[178:181], v[56:59]
	v_mfma_f32_16x16x32_bf16 v[40:43], v[146:149], v[192:195], v[40:43]
	v_mfma_f32_16x16x32_bf16 v[44:47], v[128:131], v[192:195], v[44:47]
	v_mfma_f32_16x16x32_bf16 v[28:31], v[128:131], v[200:203], v[28:31]
	v_mfma_f32_16x16x32_bf16 v[24:27], v[146:149], v[200:203], v[24:27]
	v_mfma_f32_16x16x32_bf16 v[8:11], v[146:149], v[208:211], v[8:11]
	v_mfma_f32_16x16x32_bf16 v[12:15], v[128:131], v[208:211], v[12:15]
	v_mfma_f32_16x16x32_bf16 v[60:63], v[132:135], v[188:191], v[60:63]
	v_mfma_f32_16x16x32_bf16 v[56:59], v[150:153], v[188:191], v[56:59]
	v_mfma_f32_16x16x32_bf16 v[40:43], v[150:153], v[196:199], v[40:43]
	v_mfma_f32_16x16x32_bf16 v[44:47], v[132:135], v[196:199], v[44:47]
	v_mfma_f32_16x16x32_bf16 v[28:31], v[132:135], v[204:207], v[28:31]
	v_mfma_f32_16x16x32_bf16 v[24:27], v[150:153], v[204:207], v[24:27]
	v_mfma_f32_16x16x32_bf16 v[8:11], v[150:153], v[212:215], v[8:11]
	v_mfma_f32_16x16x32_bf16 v[12:15], v[132:135], v[212:215], v[12:15]
	s_setprio 0
	s_setprio 1
	v_mfma_f32_16x16x32_bf16 v[52:55], v[154:157], v[178:181], v[52:55]
	v_mfma_f32_16x16x32_bf16 v[48:51], v[170:173], v[178:181], v[48:51]
	v_mfma_f32_16x16x32_bf16 v[32:35], v[170:173], v[192:195], v[32:35]
	v_mfma_f32_16x16x32_bf16 v[36:39], v[154:157], v[192:195], v[36:39]
	v_mfma_f32_16x16x32_bf16 v[20:23], v[154:157], v[200:203], v[20:23]
	v_mfma_f32_16x16x32_bf16 v[16:19], v[170:173], v[200:203], v[16:19]
	v_mfma_f32_16x16x32_bf16 v[0:3], v[170:173], v[208:211], v[0:3]
	v_mfma_f32_16x16x32_bf16 v[4:7], v[154:157], v[208:211], v[4:7]
	v_mfma_f32_16x16x32_bf16 v[52:55], v[166:169], v[188:191], v[52:55]
	v_mfma_f32_16x16x32_bf16 v[48:51], v[174:177], v[188:191], v[48:51]
	v_mfma_f32_16x16x32_bf16 v[32:35], v[174:177], v[196:199], v[32:35]
	v_mfma_f32_16x16x32_bf16 v[36:39], v[166:169], v[196:199], v[36:39]
	v_mfma_f32_16x16x32_bf16 v[20:23], v[166:169], v[204:207], v[20:23]
	v_mfma_f32_16x16x32_bf16 v[16:19], v[174:177], v[204:207], v[16:19]
	v_mfma_f32_16x16x32_bf16 v[0:3], v[174:177], v[212:215], v[0:3]
	v_mfma_f32_16x16x32_bf16 v[4:7], v[166:169], v[212:215], v[4:7]
	s_setprio 0
	s_barrier
	s_add_i32 s58, 0, 0x18000
	s_add_i32 s59, 0, 0x1c000
	v_add_u32_e32 v150, s58, v161
	v_add_u32_e32 v174, s59, v161
	ds_read_b128 v[128:131], v150
	ds_read_b128 v[132:135], v150 offset:1024
	ds_read_b128 v[146:149], v150 offset:2048
	ds_read_b128 v[150:153], v150 offset:3072
	ds_read_b128 v[154:157], v174
	ds_read_b128 v[166:169], v174 offset:1024
	ds_read_b128 v[170:173], v174 offset:2048
	ds_read_b128 v[174:177], v174 offset:3072
	s_add_u32 s42, s42, s8
	s_addc_u32 s43, s43, s9
	s_mov_b32 m0, s44
	v_lshl_add_u64 v[224:225], s[42:43], 0, v[140:141]
	ds_read_b128 v[178:181], v165 offset:32768
	ds_read_b128 v[188:191], v165 offset:33792
	ds_read_b128 v[192:195], v165 offset:34816
	ds_read_b128 v[196:199], v165 offset:35840
	ds_read_b128 v[200:203], v165 offset:36864
	ds_read_b128 v[204:207], v165 offset:37888
	ds_read_b128 v[208:211], v165 offset:38912
	ds_read_b128 v[212:215], v165 offset:39936
	global_load_lds_dwordx4 v[224:225], off
	v_lshl_add_u64 v[224:225], s[42:43], 0, v[138:139]
	s_mov_b32 m0, s45
	s_nop 0
	global_load_lds_dwordx4 v[224:225], off
	s_waitcnt vmcnt(8)
	s_waitcnt lgkmcnt(0)
	s_barrier
	s_setprio 1
	s_waitcnt lgkmcnt(0)
	v_mfma_f32_16x16x32_bf16 v[124:127], v[128:131], v[178:181], v[124:127]
	v_mfma_f32_16x16x32_bf16 v[120:123], v[146:149], v[178:181], v[120:123]
	v_mfma_f32_16x16x32_bf16 v[104:107], v[146:149], v[192:195], v[104:107]
	v_mfma_f32_16x16x32_bf16 v[108:111], v[128:131], v[192:195], v[108:111]
	v_mfma_f32_16x16x32_bf16 v[92:95], v[128:131], v[200:203], v[92:95]
	v_mfma_f32_16x16x32_bf16 v[88:91], v[146:149], v[200:203], v[88:91]
	v_mfma_f32_16x16x32_bf16 v[72:75], v[146:149], v[208:211], v[72:75]
	v_mfma_f32_16x16x32_bf16 v[76:79], v[128:131], v[208:211], v[76:79]
	v_mfma_f32_16x16x32_bf16 v[124:127], v[132:135], v[188:191], v[124:127]
	v_mfma_f32_16x16x32_bf16 v[120:123], v[150:153], v[188:191], v[120:123]
	v_mfma_f32_16x16x32_bf16 v[104:107], v[150:153], v[196:199], v[104:107]
	v_mfma_f32_16x16x32_bf16 v[108:111], v[132:135], v[196:199], v[108:111]
	v_mfma_f32_16x16x32_bf16 v[92:95], v[132:135], v[204:207], v[92:95]
	v_mfma_f32_16x16x32_bf16 v[88:91], v[150:153], v[204:207], v[88:91]
	v_mfma_f32_16x16x32_bf16 v[72:75], v[150:153], v[212:215], v[72:75]
	v_mfma_f32_16x16x32_bf16 v[76:79], v[132:135], v[212:215], v[76:79]
	s_setprio 0
	s_setprio 1
	v_mfma_f32_16x16x32_bf16 v[116:119], v[154:157], v[178:181], v[116:119]
	v_mfma_f32_16x16x32_bf16 v[112:115], v[170:173], v[178:181], v[112:115]
	v_mfma_f32_16x16x32_bf16 v[96:99], v[170:173], v[192:195], v[96:99]
	v_mfma_f32_16x16x32_bf16 v[100:103], v[154:157], v[192:195], v[100:103]
	v_mfma_f32_16x16x32_bf16 v[84:87], v[154:157], v[200:203], v[84:87]
	v_mfma_f32_16x16x32_bf16 v[80:83], v[170:173], v[200:203], v[80:83]
	v_mfma_f32_16x16x32_bf16 v[64:67], v[170:173], v[208:211], v[64:67]
	v_mfma_f32_16x16x32_bf16 v[68:71], v[154:157], v[208:211], v[68:71]
	v_mfma_f32_16x16x32_bf16 v[116:119], v[166:169], v[188:191], v[116:119]
	v_mfma_f32_16x16x32_bf16 v[112:115], v[174:177], v[188:191], v[112:115]
	v_mfma_f32_16x16x32_bf16 v[96:99], v[174:177], v[196:199], v[96:99]
	v_mfma_f32_16x16x32_bf16 v[100:103], v[166:169], v[196:199], v[100:103]
	v_mfma_f32_16x16x32_bf16 v[84:87], v[166:169], v[204:207], v[84:87]
	v_mfma_f32_16x16x32_bf16 v[80:83], v[174:177], v[204:207], v[80:83]
	v_mfma_f32_16x16x32_bf16 v[64:67], v[174:177], v[212:215], v[64:67]
	v_mfma_f32_16x16x32_bf16 v[68:71], v[166:169], v[212:215], v[68:71]
	s_setprio 0
	s_barrier
; #define PG8_STAGE(bufoff, gbase, voff) do { _Pragma("unroll") for (int _i = 0; _i < 2; ++_i) \
;         __builtin_amdgcn_global_load_lds((const unsigned*)((const char*)(gbase) + (voff)[_i]), (LAS unsigned*)(lds + (bufoff) + ldsw + _i * 8192), 16, 0, 0); } while (0)
; #define PG8_LDA(dst, b, h) do { _Pragma("unroll") for (int m = 0; m < 4; ++m) _Pragma("unroll") for (int k = 0; k < 2; ++k) dst[m][k] = *(const LAS bf16x8*)(lds + PG8_SA(b, h) + aoff + m * 2048 + k * 1024); } while (0)
; #define PG8_MMA(ai, bj, At, Bt) do { __builtin_amdgcn_s_setprio(1); _Pragma("unroll") for (int m = 0; m < 4; ++m) _Pragma("unroll") for (int n = 0; n < 2; ++n) _Pragma("unroll") for (int k = 0; k < 2; ++k) \
;         acc[ai][bj][m][n] = __builtin_amdgcn_mfma_f32_16x16x32_bf16(Bt[n][k], At[m][k], acc[ai][bj][m][n], 0, 0, 0); __builtin_amdgcn_s_setprio(0); } while (0)
; #define PG8_WAIT_V(n) asm volatile("s_waitcnt vmcnt(" #n ")" ::: "memory")
; #define PG8_WAIT_L(n) asm volatile("s_waitcnt lgkmcnt(" #n ")" ::: "memory")
; #define PG8_BAR __builtin_amdgcn_s_barrier()
; #define PG8_SCHED __builtin_amdgcn_sched_barrier(0)
; template <class Epi, bool ALIGN_EPI>
; __device__ __forceinline__ void gemm_phase(LAS unsigned char* lds, const Gemm g, const StaticOrder& S, const Epi& E, const int wave_s) {
;     ...
;             PG8_LDA(At, 1, 1); PG8_STAGE(PG8_SB(1, 0), b3, voffB); PG8_STAGE(PG8_SB(1, 1), b3 + hstepB, voffB); PG8_STAGE(PG8_SA(1, 0), a3, voffA);
;             PG8_WAIT_V(8); PG8_WAIT_L(0); PG8_BAR; PG8_MMA(1, 0, At, B0); PG8_MMA(1, 1, At, B1); PG8_BAR; PG8_SCHED;
;         }
	s_add_i32 s42, s58, s4
	v_lshl_add_u64 v[158:159], v[158:159], 0, s[64:65]
	s_mov_b32 m0, s42
	ds_read_b128 v[178:181], v165 offset:49152
	ds_read_b128 v[188:191], v165 offset:50176
	ds_read_b128 v[192:195], v165 offset:51200
	ds_read_b128 v[196:199], v165 offset:52224
	ds_read_b128 v[200:203], v165 offset:53248
	ds_read_b128 v[204:207], v165 offset:54272
	ds_read_b128 v[208:211], v165 offset:55296
	ds_read_b128 v[212:215], v165 offset:56320
	global_load_lds_dwordx4 v[158:159], off
	v_lshl_add_u64 v[158:159], v[182:183], 0, s[64:65]
	s_add_i32 m0, s42, 0x2000
	s_add_i32 s42, s59, s4
	global_load_lds_dwordx4 v[158:159], off
	v_lshl_add_u64 v[158:159], v[216:217], 0, s[64:65]
	s_mov_b32 m0, s42
	s_nop 0
	global_load_lds_dwordx4 v[158:159], off
	v_lshl_add_u64 v[158:159], v[218:219], 0, s[64:65]
	s_add_i32 m0, s42, 0x2000
	s_nop 0
	global_load_lds_dwordx4 v[158:159], off
	v_lshl_add_u64 v[158:159], v[220:221], 0, s[64:65]
	s_mov_b32 m0, s46
	s_nop 0
	global_load_lds_dwordx4 v[158:159], off
	v_lshl_add_u64 v[158:159], v[222:223], 0, s[64:65]
	s_mov_b32 m0, s47
	s_nop 0
	global_load_lds_dwordx4 v[158:159], off
	s_waitcnt vmcnt(8)
	s_waitcnt lgkmcnt(0)
	s_barrier
	s_setprio 1
	s_waitcnt lgkmcnt(0)
	v_mfma_f32_16x16x32_bf16 v[60:63], v[128:131], v[178:181], v[60:63]
	v_mfma_f32_16x16x32_bf16 v[56:59], v[146:149], v[178:181], v[56:59]
	v_mfma_f32_16x16x32_bf16 v[40:43], v[146:149], v[192:195], v[40:43]
	v_mfma_f32_16x16x32_bf16 v[44:47], v[128:131], v[192:195], v[44:47]
	v_mfma_f32_16x16x32_bf16 v[28:31], v[128:131], v[200:203], v[28:31]
	v_mfma_f32_16x16x32_bf16 v[24:27], v[146:149], v[200:203], v[24:27]
	v_mfma_f32_16x16x32_bf16 v[8:11], v[146:149], v[208:211], v[8:11]
	v_mfma_f32_16x16x32_bf16 v[12:15], v[128:131], v[208:211], v[12:15]
	v_mfma_f32_16x16x32_bf16 v[60:63], v[132:135], v[188:191], v[60:63]
	v_mfma_f32_16x16x32_bf16 v[56:59], v[150:153], v[188:191], v[56:59]
	v_mfma_f32_16x16x32_bf16 v[40:43], v[150:153], v[196:199], v[40:43]
	v_mfma_f32_16x16x32_bf16 v[44:47], v[132:135], v[196:199], v[44:47]
	v_mfma_f32_16x16x32_bf16 v[28:31], v[132:135], v[204:207], v[28:31]
	v_mfma_f32_16x16x32_bf16 v[24:27], v[150:153], v[204:207], v[24:27]
	v_mfma_f32_16x16x32_bf16 v[8:11], v[150:153], v[212:215], v[8:11]
	v_mfma_f32_16x16x32_bf16 v[12:15], v[132:135], v[212:215], v[12:15]
	s_setprio 0
	s_setprio 1
	v_mfma_f32_16x16x32_bf16 v[52:55], v[154:157], v[178:181], v[52:55]
	v_mfma_f32_16x16x32_bf16 v[48:51], v[170:173], v[178:181], v[48:51]
	v_mfma_f32_16x16x32_bf16 v[32:35], v[170:173], v[192:195], v[32:35]
	v_mfma_f32_16x16x32_bf16 v[36:39], v[154:157], v[192:195], v[36:39]
	v_mfma_f32_16x16x32_bf16 v[20:23], v[154:157], v[200:203], v[20:23]
	v_mfma_f32_16x16x32_bf16 v[16:19], v[170:173], v[200:203], v[16:19]
	v_mfma_f32_16x16x32_bf16 v[0:3], v[170:173], v[208:211], v[0:3]
	v_mfma_f32_16x16x32_bf16 v[4:7], v[154:157], v[208:211], v[4:7]
	v_mfma_f32_16x16x32_bf16 v[52:55], v[166:169], v[188:191], v[52:55]
	v_mfma_f32_16x16x32_bf16 v[48:51], v[174:177], v[188:191], v[48:51]
	v_mfma_f32_16x16x32_bf16 v[32:35], v[174:177], v[196:199], v[32:35]
	v_mfma_f32_16x16x32_bf16 v[36:39], v[166:169], v[196:199], v[36:39]
	v_mfma_f32_16x16x32_bf16 v[20:23], v[166:169], v[204:207], v[20:23]
	v_mfma_f32_16x16x32_bf16 v[16:19], v[174:177], v[204:207], v[16:19]
	v_mfma_f32_16x16x32_bf16 v[0:3], v[174:177], v[212:215], v[0:3]
	v_mfma_f32_16x16x32_bf16 v[4:7], v[166:169], v[212:215], v[4:7]
	s_setprio 0
	s_barrier
	s_add_u32 s55, s55, 0x100
	s_addc_u32 s56, s56, 0
	s_add_u32 s40, s40, 0x100
	s_addc_u32 s41, s41, 0
	s_cmp_ge_i32 s57, s48
	s_mov_b32 s42, s57
	s_cbranch_scc0 .LBB0_355
	v_readlane_b32 s58, v252, 12
	s_and_b64 vcc, exec, s[20:21]
	s_cbranch_vccnz .LBB0_360
	s_branch .LBB0_361

; #define PG8_STAGE(bufoff, gbase, voff) do { _Pragma("unroll") for (int _i = 0; _i < 2; ++_i) \
;         __builtin_amdgcn_global_load_lds((const unsigned*)((const char*)(gbase) + (voff)[_i]), (LAS unsigned*)(lds + (bufoff) + ldsw + _i * 8192), 16, 0, 0); } while (0)
; #define PG8_LDA(dst, b, h) do { _Pragma("unroll") for (int m = 0; m < 4; ++m) _Pragma("unroll") for (int k = 0; k < 2; ++k) dst[m][k] = *(const LAS bf16x8*)(lds + PG8_SA(b, h) + aoff + m * 2048 + k * 1024); } while (0)
; #define PG8_LDB(dst, b, h) do { _Pragma("unroll") for (int n = 0; n < 2; ++n) _Pragma("unroll") for (int k = 0; k < 2; ++k) dst[n][k] = *(const LAS bf16x8*)(lds + PG8_SB(b, h) + boff + n * 2048 + k * 1024); } while (0)
; #define PG8_MMA(ai, bj, At, Bt) do { __builtin_amdgcn_s_setprio(1); _Pragma("unroll") for (int m = 0; m < 4; ++m) _Pragma("unroll") for (int n = 0; n < 2; ++n) _Pragma("unroll") for (int k = 0; k < 2; ++k) \
;         acc[ai][bj][m][n] = __builtin_amdgcn_mfma_f32_16x16x32_bf16(Bt[n][k], At[m][k], acc[ai][bj][m][n], 0, 0, 0); __builtin_amdgcn_s_setprio(0); } while (0)
; #define PG8_WAIT_V(n) asm volatile("s_waitcnt vmcnt(" #n ")" ::: "memory")
; #define PG8_WAIT_L(n) asm volatile("s_waitcnt lgkmcnt(" #n ")" ::: "memory")
; #define PG8_BAR __builtin_amdgcn_s_barrier()
; #define PG8_SCHED __builtin_amdgcn_sched_barrier(0)
; template <class Epi, bool ALIGN_EPI>
; __device__ __forceinline__ void gemm_phase(LAS unsigned char* lds, const Gemm g, const StaticOrder& S, const Epi& E, const int wave_s) {
;     ...
;         for (int t = 0; t < nt; t += 2) {
;             const bool last = (t == nt - 2);
;             const char* a1 = cA + (size_t)(t + 1) * kstep;
;             const char* a2 = last ? nA : cA + (size_t)(t + 2) * kstep; const char* b2 = last ? nB : cB + (size_t)(t + 2) * kstep;
;             const char* a3 = a2 + kstep; const char* b3 = b2 + kstep;
;             PG8_LDB(B0, 0, 0); PG8_LDB(B1, 0, 1); PG8_SCHED; PG8_LDA(At, 0, 0); PG8_STAGE(PG8_SA(1, 1), a1 + hstepA, voffA);
;             PG8_WAIT_V(8); PG8_WAIT_L(0); PG8_BAR; PG8_MMA(0, 0, At, B0); PG8_MMA(0, 1, At, B1); PG8_BAR; PG8_SCHED;
;             PG8_LDA(At, 0, 1); PG8_STAGE(PG8_SB(0, 0), b2, voffB); PG8_STAGE(PG8_SB(0, 1), b2 + hstepB, voffB); PG8_STAGE(PG8_SA(0, 0), a2, voffA);
;             PG8_WAIT_V(8); PG8_WAIT_L(0); PG8_BAR; PG8_MMA(1, 0, At, B0); PG8_MMA(1, 1, At, B1); PG8_BAR; PG8_SCHED;
.LBB0_540:
	s_add_i32 s69, s50, 2
	s_add_u32 s70, s38, 0x80
	s_addc_u32 s51, s39, 0
	s_add_i32 s72, 0, 0x10000
	s_cmp_eq_u32 s58, s50
	s_cselect_b32 s51, s1, s51
	s_cselect_b32 s50, s0, s70
	v_add_u32_e32 v155, s72, v151
	s_cselect_b32 s71, s49, s68
	s_cselect_b32 s70, s48, s67
	s_add_i32 s73, 0, 0x14000
	ds_read_b128 v[138:141], v155
	ds_read_b128 v[142:145], v155 offset:1024
	ds_read_b128 v[146:149], v155 offset:2048
	ds_read_b128 v[156:159], v155 offset:3072
	v_add_u32_e32 v155, s73, v151
	ds_read_b128 v[160:163], v155
	ds_read_b128 v[164:167], v155 offset:1024
	ds_read_b128 v[168:171], v155 offset:2048
	ds_read_b128 v[172:175], v155 offset:3072
	v_lshl_add_u64 v[188:189], s[38:39], 0, v[136:137]
	s_add_i32 m0, s24, 0xc000
	ds_read_b128 v[176:179], v154
	ds_read_b128 v[180:183], v154 offset:1024
	ds_read_b128 v[192:195], v154 offset:2048
	ds_read_b128 v[196:199], v154 offset:3072
	ds_read_b128 v[200:203], v154 offset:4096
	ds_read_b128 v[204:207], v154 offset:5120
	ds_read_b128 v[210:213], v154 offset:6144
	ds_read_b128 v[214:217], v154 offset:7168
	global_load_lds_dwordx4 v[188:189], off
	v_lshl_add_u64 v[188:189], s[38:39], 0, v[134:135]
	s_add_i32 m0, s24, 0xe000
	s_nop 0
	global_load_lds_dwordx4 v[188:189], off
	s_waitcnt vmcnt(8)
	s_waitcnt lgkmcnt(0)
	s_barrier
	s_setprio 1
	s_waitcnt lgkmcnt(0)
	v_mfma_f32_16x16x32_bf16 v[124:127], v[138:141], v[176:179], v[124:127]
	v_mfma_f32_16x16x32_bf16 v[120:123], v[146:149], v[176:179], v[120:123]
	v_mfma_f32_16x16x32_bf16 v[112:115], v[146:149], v[192:195], v[112:115]
	v_mfma_f32_16x16x32_bf16 v[116:119], v[138:141], v[192:195], v[116:119]
	v_mfma_f32_16x16x32_bf16 v[108:111], v[138:141], v[200:203], v[108:111]
	v_mfma_f32_16x16x32_bf16 v[104:107], v[146:149], v[200:203], v[104:107]
	v_mfma_f32_16x16x32_bf16 v[96:99], v[146:149], v[210:213], v[96:99]
	v_mfma_f32_16x16x32_bf16 v[100:103], v[138:141], v[210:213], v[100:103]
	v_mfma_f32_16x16x32_bf16 v[124:127], v[142:145], v[180:183], v[124:127]
	v_mfma_f32_16x16x32_bf16 v[120:123], v[156:159], v[180:183], v[120:123]
	v_mfma_f32_16x16x32_bf16 v[112:115], v[156:159], v[196:199], v[112:115]
	v_mfma_f32_16x16x32_bf16 v[116:119], v[142:145], v[196:199], v[116:119]
	v_mfma_f32_16x16x32_bf16 v[108:111], v[142:145], v[204:207], v[108:111]
	v_mfma_f32_16x16x32_bf16 v[104:107], v[156:159], v[204:207], v[104:107]
	v_mfma_f32_16x16x32_bf16 v[96:99], v[156:159], v[214:217], v[96:99]
	v_mfma_f32_16x16x32_bf16 v[100:103], v[142:145], v[214:217], v[100:103]
	s_setprio 0
	s_setprio 1
	v_mfma_f32_16x16x32_bf16 v[60:63], v[160:163], v[176:179], v[60:63]
	v_mfma_f32_16x16x32_bf16 v[56:59], v[168:171], v[176:179], v[56:59]
	v_mfma_f32_16x16x32_bf16 v[48:51], v[168:171], v[192:195], v[48:51]
	v_mfma_f32_16x16x32_bf16 v[52:55], v[160:163], v[192:195], v[52:55]
	v_mfma_f32_16x16x32_bf16 v[44:47], v[160:163], v[200:203], v[44:47]
	v_mfma_f32_16x16x32_bf16 v[40:43], v[168:171], v[200:203], v[40:43]
	v_mfma_f32_16x16x32_bf16 v[32:35], v[168:171], v[210:213], v[32:35]
	v_mfma_f32_16x16x32_bf16 v[36:39], v[160:163], v[210:213], v[36:39]
	v_mfma_f32_16x16x32_bf16 v[60:63], v[164:167], v[180:183], v[60:63]
	v_mfma_f32_16x16x32_bf16 v[56:59], v[172:175], v[180:183], v[56:59]
	v_mfma_f32_16x16x32_bf16 v[48:51], v[172:175], v[196:199], v[48:51]
	v_mfma_f32_16x16x32_bf16 v[52:55], v[164:167], v[196:199], v[52:55]
	v_mfma_f32_16x16x32_bf16 v[44:47], v[164:167], v[204:207], v[44:47]
	v_mfma_f32_16x16x32_bf16 v[40:43], v[172:175], v[204:207], v[40:43]
	v_mfma_f32_16x16x32_bf16 v[32:35], v[172:175], v[214:217], v[32:35]
	v_mfma_f32_16x16x32_bf16 v[36:39], v[164:167], v[214:217], v[36:39]
	s_setprio 0
	s_barrier
	s_add_i32 s72, s72, s4
	v_lshl_add_u64 v[188:189], s[70:71], 0, v[184:185]
	s_mov_b32 m0, s72
	ds_read_b128 v[176:179], v154 offset:16384
	ds_read_b128 v[180:183], v154 offset:17408
	ds_read_b128 v[192:195], v154 offset:18432
	ds_read_b128 v[196:199], v154 offset:19456
	ds_read_b128 v[200:203], v154 offset:20480
	ds_read_b128 v[204:207], v154 offset:21504
	ds_read_b128 v[210:213], v154 offset:22528
	ds_read_b128 v[214:217], v154 offset:23552
	global_load_lds_dwordx4 v[188:189], off
	s_add_i32 m0, s72, 0x2000
	v_lshl_add_u64 v[190:191], s[70:71], 0, v[128:129]
	s_add_u32 s70, s70, s8
	s_addc_u32 s71, s71, s9
	s_add_i32 s72, s73, s4
	global_load_lds_dwordx4 v[190:191], off
	v_lshl_add_u64 v[208:209], s[70:71], 0, v[184:185]
	s_mov_b32 m0, s72
	v_lshl_add_u64 v[218:219], s[70:71], 0, v[128:129]
	global_load_lds_dwordx4 v[208:209], off
	s_add_i32 m0, s72, 0x2000
	v_lshl_add_u64 v[220:221], s[50:51], 0, v[132:133]
	global_load_lds_dwordx4 v[218:219], off
	s_mov_b32 m0, s24
	v_lshl_add_u64 v[222:223], s[50:51], 0, v[130:131]
	global_load_lds_dwordx4 v[220:221], off
	s_mov_b32 m0, s25
	s_nop 0
	global_load_lds_dwordx4 v[222:223], off
	s_waitcnt vmcnt(8)
	s_waitcnt lgkmcnt(0)
	s_barrier
; #define PG8_STAGE(bufoff, gbase, voff) do { _Pragma("unroll") for (int _i = 0; _i < 2; ++_i) \
;         __builtin_amdgcn_global_load_lds((const unsigned*)((const char*)(gbase) + (voff)[_i]), (LAS unsigned*)(lds + (bufoff) + ldsw + _i * 8192), 16, 0, 0); } while (0)
; #define PG8_LDA(dst, b, h) do { _Pragma("unroll") for (int m = 0; m < 4; ++m) _Pragma("unroll") for (int k = 0; k < 2; ++k) dst[m][k] = *(const LAS bf16x8*)(lds + PG8_SA(b, h) + aoff + m * 2048 + k * 1024); } while (0)
; #define PG8_LDB(dst, b, h) do { _Pragma("unroll") for (int n = 0; n < 2; ++n) _Pragma("unroll") for (int k = 0; k < 2; ++k) dst[n][k] = *(const LAS bf16x8*)(lds + PG8_SB(b, h) + boff + n * 2048 + k * 1024); } while (0)
; #define PG8_MMA(ai, bj, At, Bt) do { __builtin_amdgcn_s_setprio(1); _Pragma("unroll") for (int m = 0; m < 4; ++m) _Pragma("unroll") for (int n = 0; n < 2; ++n) _Pragma("unroll") for (int k = 0; k < 2; ++k) \
;         acc[ai][bj][m][n] = __builtin_amdgcn_mfma_f32_16x16x32_bf16(Bt[n][k], At[m][k], acc[ai][bj][m][n], 0, 0, 0); __builtin_amdgcn_s_setprio(0); } while (0)
; #define PG8_WAIT_V(n) asm volatile("s_waitcnt vmcnt(" #n ")" ::: "memory")
; #define PG8_WAIT_L(n) asm volatile("s_waitcnt lgkmcnt(" #n ")" ::: "memory")
; #define PG8_BAR __builtin_amdgcn_s_barrier()
; #define PG8_SCHED __builtin_amdgcn_sched_barrier(0)
; template <class Epi, bool ALIGN_EPI>
; __device__ __forceinline__ void gemm_phase(LAS unsigned char* lds, const Gemm g, const StaticOrder& S, const Epi& E, const int wave_s) {
;     ...
;             PG8_WAIT_V(8); PG8_WAIT_L(0); PG8_BAR; PG8_MMA(1, 0, At, B0); PG8_MMA(1, 1, At, B1); PG8_BAR; PG8_SCHED;
;             PG8_LDB(B0, 1, 0); PG8_LDB(B1, 1, 1); PG8_SCHED; PG8_LDA(At, 1, 0); PG8_STAGE(PG8_SA(0, 1), a2 + hstepA, voffA);
;             PG8_WAIT_V(8); PG8_WAIT_L(0); PG8_BAR; PG8_MMA(0, 0, At, B0); PG8_MMA(0, 1, At, B1); PG8_BAR; PG8_SCHED;
	s_setprio 1
	s_waitcnt lgkmcnt(0)
	v_mfma_f32_16x16x32_bf16 v[92:95], v[138:141], v[176:179], v[92:95]
	v_mfma_f32_16x16x32_bf16 v[88:91], v[146:149], v[176:179], v[88:91]
	v_mfma_f32_16x16x32_bf16 v[80:83], v[146:149], v[192:195], v[80:83]
	v_mfma_f32_16x16x32_bf16 v[84:87], v[138:141], v[192:195], v[84:87]
	v_mfma_f32_16x16x32_bf16 v[76:79], v[138:141], v[200:203], v[76:79]
	v_mfma_f32_16x16x32_bf16 v[72:75], v[146:149], v[200:203], v[72:75]
	v_mfma_f32_16x16x32_bf16 v[64:67], v[146:149], v[210:213], v[64:67]
	v_mfma_f32_16x16x32_bf16 v[68:71], v[138:141], v[210:213], v[68:71]
	v_mfma_f32_16x16x32_bf16 v[92:95], v[142:145], v[180:183], v[92:95]
	v_mfma_f32_16x16x32_bf16 v[88:91], v[156:159], v[180:183], v[88:91]
	v_mfma_f32_16x16x32_bf16 v[80:83], v[156:159], v[196:199], v[80:83]
	v_mfma_f32_16x16x32_bf16 v[84:87], v[142:145], v[196:199], v[84:87]
	v_mfma_f32_16x16x32_bf16 v[76:79], v[142:145], v[204:207], v[76:79]
	v_mfma_f32_16x16x32_bf16 v[72:75], v[156:159], v[204:207], v[72:75]
	v_mfma_f32_16x16x32_bf16 v[64:67], v[156:159], v[214:217], v[64:67]
	v_mfma_f32_16x16x32_bf16 v[68:71], v[142:145], v[214:217], v[68:71]
	s_setprio 0
	s_setprio 1
	v_mfma_f32_16x16x32_bf16 v[28:31], v[160:163], v[176:179], v[28:31]
	v_mfma_f32_16x16x32_bf16 v[24:27], v[168:171], v[176:179], v[24:27]
	v_mfma_f32_16x16x32_bf16 v[16:19], v[168:171], v[192:195], v[16:19]
	v_mfma_f32_16x16x32_bf16 v[20:23], v[160:163], v[192:195], v[20:23]
	v_mfma_f32_16x16x32_bf16 v[12:15], v[160:163], v[200:203], v[12:15]
	v_mfma_f32_16x16x32_bf16 v[8:11], v[168:171], v[200:203], v[8:11]
	v_mfma_f32_16x16x32_bf16 v[0:3], v[168:171], v[210:213], v[0:3]
	v_mfma_f32_16x16x32_bf16 v[4:7], v[160:163], v[210:213], v[4:7]
	v_mfma_f32_16x16x32_bf16 v[28:31], v[164:167], v[180:183], v[28:31]
	v_mfma_f32_16x16x32_bf16 v[24:27], v[172:175], v[180:183], v[24:27]
	v_mfma_f32_16x16x32_bf16 v[16:19], v[172:175], v[196:199], v[16:19]
	v_mfma_f32_16x16x32_bf16 v[20:23], v[164:167], v[196:199], v[20:23]
	v_mfma_f32_16x16x32_bf16 v[12:15], v[164:167], v[204:207], v[12:15]
	v_mfma_f32_16x16x32_bf16 v[8:11], v[172:175], v[204:207], v[8:11]
	v_mfma_f32_16x16x32_bf16 v[0:3], v[172:175], v[214:217], v[0:3]
	v_mfma_f32_16x16x32_bf16 v[4:7], v[164:167], v[214:217], v[4:7]
	s_setprio 0
	s_barrier
	s_add_i32 s70, 0, 0x18000
	v_add_u32_e32 v155, s70, v151
	s_add_i32 s71, 0, 0x1c000
	ds_read_b128 v[138:141], v155
	ds_read_b128 v[142:145], v155 offset:1024
	ds_read_b128 v[146:149], v155 offset:2048
	ds_read_b128 v[156:159], v155 offset:3072
	v_add_u32_e32 v155, s71, v151
	ds_read_b128 v[160:163], v155
	ds_read_b128 v[164:167], v155 offset:1024
	ds_read_b128 v[168:171], v155 offset:2048
	ds_read_b128 v[172:175], v155 offset:3072
	s_add_u32 s50, s50, s6
	s_addc_u32 s51, s51, s7
	s_mov_b32 m0, s52
	v_lshl_add_u64 v[224:225], s[50:51], 0, v[132:133]
	ds_read_b128 v[176:179], v154 offset:32768
	ds_read_b128 v[180:183], v154 offset:33792
	ds_read_b128 v[192:195], v154 offset:34816
	ds_read_b128 v[196:199], v154 offset:35840
	ds_read_b128 v[200:203], v154 offset:36864
	ds_read_b128 v[204:207], v154 offset:37888
	ds_read_b128 v[210:213], v154 offset:38912
	ds_read_b128 v[214:217], v154 offset:39936
	global_load_lds_dwordx4 v[224:225], off
	v_lshl_add_u64 v[224:225], s[50:51], 0, v[130:131]
	s_mov_b32 m0, s53
	s_nop 0
	global_load_lds_dwordx4 v[224:225], off
	s_waitcnt vmcnt(8)
	s_waitcnt lgkmcnt(0)
	s_barrier
	s_setprio 1
	s_waitcnt lgkmcnt(0)
	v_mfma_f32_16x16x32_bf16 v[124:127], v[138:141], v[176:179], v[124:127]
	v_mfma_f32_16x16x32_bf16 v[120:123], v[146:149], v[176:179], v[120:123]
	v_mfma_f32_16x16x32_bf16 v[112:115], v[146:149], v[192:195], v[112:115]
	v_mfma_f32_16x16x32_bf16 v[116:119], v[138:141], v[192:195], v[116:119]
	v_mfma_f32_16x16x32_bf16 v[108:111], v[138:141], v[200:203], v[108:111]
	v_mfma_f32_16x16x32_bf16 v[104:107], v[146:149], v[200:203], v[104:107]
	v_mfma_f32_16x16x32_bf16 v[96:99], v[146:149], v[210:213], v[96:99]
	v_mfma_f32_16x16x32_bf16 v[100:103], v[138:141], v[210:213], v[100:103]
	v_mfma_f32_16x16x32_bf16 v[124:127], v[142:145], v[180:183], v[124:127]
	v_mfma_f32_16x16x32_bf16 v[120:123], v[156:159], v[180:183], v[120:123]
	v_mfma_f32_16x16x32_bf16 v[112:115], v[156:159], v[196:199], v[112:115]
	v_mfma_f32_16x16x32_bf16 v[116:119], v[142:145], v[196:199], v[116:119]
	v_mfma_f32_16x16x32_bf16 v[108:111], v[142:145], v[204:207], v[108:111]
	v_mfma_f32_16x16x32_bf16 v[104:107], v[156:159], v[204:207], v[104:107]
	v_mfma_f32_16x16x32_bf16 v[96:99], v[156:159], v[214:217], v[96:99]
	v_mfma_f32_16x16x32_bf16 v[100:103], v[142:145], v[214:217], v[100:103]
	s_setprio 0
	s_setprio 1
	v_mfma_f32_16x16x32_bf16 v[60:63], v[160:163], v[176:179], v[60:63]
	v_mfma_f32_16x16x32_bf16 v[56:59], v[168:171], v[176:179], v[56:59]
	v_mfma_f32_16x16x32_bf16 v[48:51], v[168:171], v[192:195], v[48:51]
	v_mfma_f32_16x16x32_bf16 v[52:55], v[160:163], v[192:195], v[52:55]
	v_mfma_f32_16x16x32_bf16 v[44:47], v[160:163], v[200:203], v[44:47]
	v_mfma_f32_16x16x32_bf16 v[40:43], v[168:171], v[200:203], v[40:43]
	v_mfma_f32_16x16x32_bf16 v[32:35], v[168:171], v[210:213], v[32:35]
	v_mfma_f32_16x16x32_bf16 v[36:39], v[160:163], v[210:213], v[36:39]
	v_mfma_f32_16x16x32_bf16 v[60:63], v[164:167], v[180:183], v[60:63]
	v_mfma_f32_16x16x32_bf16 v[56:59], v[172:175], v[180:183], v[56:59]
	v_mfma_f32_16x16x32_bf16 v[48:51], v[172:175], v[196:199], v[48:51]
	v_mfma_f32_16x16x32_bf16 v[52:55], v[164:167], v[196:199], v[52:55]
	v_mfma_f32_16x16x32_bf16 v[44:47], v[164:167], v[204:207], v[44:47]
	v_mfma_f32_16x16x32_bf16 v[40:43], v[172:175], v[204:207], v[40:43]
	v_mfma_f32_16x16x32_bf16 v[32:35], v[172:175], v[214:217], v[32:35]
	v_mfma_f32_16x16x32_bf16 v[36:39], v[164:167], v[214:217], v[36:39]
	s_setprio 0
	s_barrier
; #define PG8_STAGE(bufoff, gbase, voff) do { _Pragma("unroll") for (int _i = 0; _i < 2; ++_i) \
;         __builtin_amdgcn_global_load_lds((const unsigned*)((const char*)(gbase) + (voff)[_i]), (LAS unsigned*)(lds + (bufoff) + ldsw + _i * 8192), 16, 0, 0); } while (0)
; #define PG8_LDA(dst, b, h) do { _Pragma("unroll") for (int m = 0; m < 4; ++m) _Pragma("unroll") for (int k = 0; k < 2; ++k) dst[m][k] = *(const LAS bf16x8*)(lds + PG8_SA(b, h) + aoff + m * 2048 + k * 1024); } while (0)
; #define PG8_MMA(ai, bj, At, Bt) do { __builtin_amdgcn_s_setprio(1); _Pragma("unroll") for (int m = 0; m < 4; ++m) _Pragma("unroll") for (int n = 0; n < 2; ++n) _Pragma("unroll") for (int k = 0; k < 2; ++k) \
;         acc[ai][bj][m][n] = __builtin_amdgcn_mfma_f32_16x16x32_bf16(Bt[n][k], At[m][k], acc[ai][bj][m][n], 0, 0, 0); __builtin_amdgcn_s_setprio(0); } while (0)
; #define PG8_WAIT_V(n) asm volatile("s_waitcnt vmcnt(" #n ")" ::: "memory")
; #define PG8_WAIT_L(n) asm volatile("s_waitcnt lgkmcnt(" #n ")" ::: "memory")
; #define PG8_BAR __builtin_amdgcn_s_barrier()
; #define PG8_SCHED __builtin_amdgcn_sched_barrier(0)
; template <class Epi, bool ALIGN_EPI>
; __device__ __forceinline__ void gemm_phase(LAS unsigned char* lds, const Gemm g, const StaticOrder& S, const Epi& E, const int wave_s) {
;     ...
;             PG8_LDA(At, 1, 1); PG8_STAGE(PG8_SB(1, 0), b3, voffB); PG8_STAGE(PG8_SB(1, 1), b3 + hstepB, voffB); PG8_STAGE(PG8_SA(1, 0), a3, voffA);
;             PG8_WAIT_V(8); PG8_WAIT_L(0); PG8_BAR; PG8_MMA(1, 0, At, B0); PG8_MMA(1, 1, At, B1); PG8_BAR; PG8_SCHED;
;         }
	s_add_i32 s50, s70, s4
	v_lshl_add_u64 v[188:189], v[188:189], 0, s[64:65]
	s_mov_b32 m0, s50
	ds_read_b128 v[176:179], v154 offset:49152
	ds_read_b128 v[180:183], v154 offset:50176
	ds_read_b128 v[192:195], v154 offset:51200
	ds_read_b128 v[196:199], v154 offset:52224
	ds_read_b128 v[200:203], v154 offset:53248
	ds_read_b128 v[204:207], v154 offset:54272
	ds_read_b128 v[210:213], v154 offset:55296
	ds_read_b128 v[214:217], v154 offset:56320
	global_load_lds_dwordx4 v[188:189], off
	v_lshl_add_u64 v[188:189], v[190:191], 0, s[64:65]
	s_add_i32 m0, s50, 0x2000
	s_add_i32 s50, s71, s4
	global_load_lds_dwordx4 v[188:189], off
	v_lshl_add_u64 v[188:189], v[208:209], 0, s[64:65]
	s_mov_b32 m0, s50
	s_nop 0
	global_load_lds_dwordx4 v[188:189], off
	v_lshl_add_u64 v[188:189], v[218:219], 0, s[64:65]
	s_add_i32 m0, s50, 0x2000
	s_nop 0
	global_load_lds_dwordx4 v[188:189], off
	v_lshl_add_u64 v[188:189], v[220:221], 0, s[64:65]
	s_mov_b32 m0, s56
	s_nop 0
	global_load_lds_dwordx4 v[188:189], off
	v_lshl_add_u64 v[188:189], v[222:223], 0, s[64:65]
	s_mov_b32 m0, s57
	s_nop 0
	global_load_lds_dwordx4 v[188:189], off
	s_waitcnt vmcnt(8)
	s_waitcnt lgkmcnt(0)
	s_barrier
	s_setprio 1
	s_waitcnt lgkmcnt(0)
	v_mfma_f32_16x16x32_bf16 v[92:95], v[138:141], v[176:179], v[92:95]
	v_mfma_f32_16x16x32_bf16 v[88:91], v[146:149], v[176:179], v[88:91]
	v_mfma_f32_16x16x32_bf16 v[80:83], v[146:149], v[192:195], v[80:83]
	v_mfma_f32_16x16x32_bf16 v[84:87], v[138:141], v[192:195], v[84:87]
	v_mfma_f32_16x16x32_bf16 v[76:79], v[138:141], v[200:203], v[76:79]
	v_mfma_f32_16x16x32_bf16 v[72:75], v[146:149], v[200:203], v[72:75]
	v_mfma_f32_16x16x32_bf16 v[64:67], v[146:149], v[210:213], v[64:67]
	v_mfma_f32_16x16x32_bf16 v[68:71], v[138:141], v[210:213], v[68:71]
	v_mfma_f32_16x16x32_bf16 v[92:95], v[142:145], v[180:183], v[92:95]
	v_mfma_f32_16x16x32_bf16 v[88:91], v[156:159], v[180:183], v[88:91]
	v_mfma_f32_16x16x32_bf16 v[80:83], v[156:159], v[196:199], v[80:83]
	v_mfma_f32_16x16x32_bf16 v[84:87], v[142:145], v[196:199], v[84:87]
	v_mfma_f32_16x16x32_bf16 v[76:79], v[142:145], v[204:207], v[76:79]
	v_mfma_f32_16x16x32_bf16 v[72:75], v[156:159], v[204:207], v[72:75]
	v_mfma_f32_16x16x32_bf16 v[64:67], v[156:159], v[214:217], v[64:67]
	v_mfma_f32_16x16x32_bf16 v[68:71], v[142:145], v[214:217], v[68:71]
	s_setprio 0
	s_setprio 1
	v_mfma_f32_16x16x32_bf16 v[28:31], v[160:163], v[176:179], v[28:31]
	v_mfma_f32_16x16x32_bf16 v[24:27], v[168:171], v[176:179], v[24:27]
	v_mfma_f32_16x16x32_bf16 v[16:19], v[168:171], v[192:195], v[16:19]
	v_mfma_f32_16x16x32_bf16 v[20:23], v[160:163], v[192:195], v[20:23]
	v_mfma_f32_16x16x32_bf16 v[12:15], v[160:163], v[200:203], v[12:15]
	v_mfma_f32_16x16x32_bf16 v[8:11], v[168:171], v[200:203], v[8:11]
	v_mfma_f32_16x16x32_bf16 v[0:3], v[168:171], v[210:213], v[0:3]
	v_mfma_f32_16x16x32_bf16 v[4:7], v[160:163], v[210:213], v[4:7]
	v_mfma_f32_16x16x32_bf16 v[28:31], v[164:167], v[180:183], v[28:31]
	v_mfma_f32_16x16x32_bf16 v[24:27], v[172:175], v[180:183], v[24:27]
	v_mfma_f32_16x16x32_bf16 v[16:19], v[172:175], v[196:199], v[16:19]
	v_mfma_f32_16x16x32_bf16 v[20:23], v[164:167], v[196:199], v[20:23]
	v_mfma_f32_16x16x32_bf16 v[12:15], v[164:167], v[204:207], v[12:15]
	v_mfma_f32_16x16x32_bf16 v[8:11], v[172:175], v[204:207], v[8:11]
	v_mfma_f32_16x16x32_bf16 v[0:3], v[172:175], v[214:217], v[0:3]
	v_mfma_f32_16x16x32_bf16 v[4:7], v[164:167], v[214:217], v[4:7]
	s_setprio 0
	s_barrier
	s_add_u32 s67, s67, 0x100
	s_addc_u32 s68, s68, 0
	s_add_u32 s38, s38, 0x100
	s_addc_u32 s39, s39, 0
	s_cmp_ge_i32 s69, s54
	s_mov_b32 s50, s69
	s_cbranch_scc0 .LBB0_540
	s_and_b64 vcc, exec, s[28:29]
	s_cbranch_vccz .LBB0_543

; #define PG8_STAGE(bufoff, gbase, voff) do { _Pragma("unroll") for (int _i = 0; _i < 2; ++_i) \
;         __builtin_amdgcn_global_load_lds((const unsigned*)((const char*)(gbase) + (voff)[_i]), (LAS unsigned*)(lds + (bufoff) + ldsw + _i * 8192), 16, 0, 0); } while (0)
; #define PG8_LDA(dst, b, h) do { _Pragma("unroll") for (int m = 0; m < 4; ++m) _Pragma("unroll") for (int k = 0; k < 2; ++k) dst[m][k] = *(const LAS bf16x8*)(lds + PG8_SA(b, h) + aoff + m * 2048 + k * 1024); } while (0)
; #define PG8_LDB(dst, b, h) do { _Pragma("unroll") for (int n = 0; n < 2; ++n) _Pragma("unroll") for (int k = 0; k < 2; ++k) dst[n][k] = *(const LAS bf16x8*)(lds + PG8_SB(b, h) + boff + n * 2048 + k * 1024); } while (0)
; #define PG8_MMA(ai, bj, At, Bt) do { __builtin_amdgcn_s_setprio(1); _Pragma("unroll") for (int m = 0; m < 4; ++m) _Pragma("unroll") for (int n = 0; n < 2; ++n) _Pragma("unroll") for (int k = 0; k < 2; ++k) \
;         acc[ai][bj][m][n] = __builtin_amdgcn_mfma_f32_16x16x32_bf16(Bt[n][k], At[m][k], acc[ai][bj][m][n], 0, 0, 0); __builtin_amdgcn_s_setprio(0); } while (0)
; #define PG8_WAIT_V(n) asm volatile("s_waitcnt vmcnt(" #n ")" ::: "memory")
; #define PG8_WAIT_L(n) asm volatile("s_waitcnt lgkmcnt(" #n ")" ::: "memory")
; #define PG8_BAR __builtin_amdgcn_s_barrier()
; #define PG8_SCHED __builtin_amdgcn_sched_barrier(0)
; template <class Epi, bool ALIGN_EPI>
; __device__ __forceinline__ void gemm_phase(LAS unsigned char* lds, const Gemm g, const StaticOrder& S, const Epi& E, const int wave_s) {
;     ...
;         for (int t = 0; t < nt; t += 2) {
;             const bool last = (t == nt - 2);
;             const char* a1 = cA + (size_t)(t + 1) * kstep;
;             const char* a2 = last ? nA : cA + (size_t)(t + 2) * kstep; const char* b2 = last ? nB : cB + (size_t)(t + 2) * kstep;
;             const char* a3 = a2 + kstep; const char* b3 = b2 + kstep;
;             PG8_LDB(B0, 0, 0); PG8_LDB(B1, 0, 1); PG8_SCHED; PG8_LDA(At, 0, 0); PG8_STAGE(PG8_SA(1, 1), a1 + hstepA, voffA);
;             PG8_WAIT_V(8); PG8_WAIT_L(0); PG8_BAR; PG8_MMA(0, 0, At, B0); PG8_MMA(0, 1, At, B1); PG8_BAR; PG8_SCHED;
;             PG8_LDA(At, 0, 1); PG8_STAGE(PG8_SB(0, 0), b2, voffB); PG8_STAGE(PG8_SB(0, 1), b2 + hstepB, voffB); PG8_STAGE(PG8_SA(0, 0), a2, voffA);
;             PG8_WAIT_V(8); PG8_WAIT_L(0); PG8_BAR; PG8_MMA(1, 0, At, B0); PG8_MMA(1, 1, At, B1); PG8_BAR; PG8_SCHED;
.LBB0_598:
	s_add_i32 s66, s46, 2
	s_add_u32 s67, s38, 0x80
	s_addc_u32 s47, s39, 0
	s_add_i32 s70, 0, 0x10000
	s_cmp_eq_u32 s55, s46
	s_cselect_b32 s47, s1, s47
	s_cselect_b32 s46, s0, s67
	s_cselect_b32 s69, s29, s63
	s_cselect_b32 s68, s28, s61
	s_add_i32 s67, 0, 0x14000
	v_add_u32_e32 v154, s70, v147
	v_add_u32_e32 v170, s67, v147
	ds_read_b128 v[138:141], v154
	ds_read_b128 v[142:145], v154 offset:1024
	ds_read_b128 v[150:153], v154 offset:2048
	ds_read_b128 v[154:157], v154 offset:3072
	ds_read_b128 v[158:161], v170
	ds_read_b128 v[162:165], v170 offset:1024
	ds_read_b128 v[166:169], v170 offset:2048
	ds_read_b128 v[170:173], v170 offset:3072
	v_lshl_add_u64 v[182:183], s[38:39], 0, v[136:137]
	s_add_i32 m0, s48, 0xc000
	ds_read_b128 v[174:177], v149
	ds_read_b128 v[178:181], v149 offset:1024
	ds_read_b128 v[192:195], v149 offset:2048
	ds_read_b128 v[196:199], v149 offset:3072
	ds_read_b128 v[200:203], v149 offset:4096
	ds_read_b128 v[204:207], v149 offset:5120
	ds_read_b128 v[210:213], v149 offset:6144
	ds_read_b128 v[214:217], v149 offset:7168
	global_load_lds_dwordx4 v[182:183], off
	v_lshl_add_u64 v[182:183], s[38:39], 0, v[134:135]
	s_add_i32 m0, s48, 0xe000
	s_nop 0
	global_load_lds_dwordx4 v[182:183], off
	s_waitcnt vmcnt(8)
	s_waitcnt lgkmcnt(0)
	s_barrier
	s_setprio 1
	s_waitcnt lgkmcnt(0)
	v_mfma_f32_16x16x32_bf16 v[124:127], v[138:141], v[174:177], v[124:127]
	v_mfma_f32_16x16x32_bf16 v[120:123], v[150:153], v[174:177], v[120:123]
	v_mfma_f32_16x16x32_bf16 v[104:107], v[150:153], v[192:195], v[104:107]
	v_mfma_f32_16x16x32_bf16 v[108:111], v[138:141], v[192:195], v[108:111]
	v_mfma_f32_16x16x32_bf16 v[92:95], v[138:141], v[200:203], v[92:95]
	v_mfma_f32_16x16x32_bf16 v[88:91], v[150:153], v[200:203], v[88:91]
	v_mfma_f32_16x16x32_bf16 v[72:75], v[150:153], v[210:213], v[72:75]
	v_mfma_f32_16x16x32_bf16 v[76:79], v[138:141], v[210:213], v[76:79]
	v_mfma_f32_16x16x32_bf16 v[124:127], v[142:145], v[178:181], v[124:127]
	v_mfma_f32_16x16x32_bf16 v[120:123], v[154:157], v[178:181], v[120:123]
	v_mfma_f32_16x16x32_bf16 v[104:107], v[154:157], v[196:199], v[104:107]
	v_mfma_f32_16x16x32_bf16 v[108:111], v[142:145], v[196:199], v[108:111]
	v_mfma_f32_16x16x32_bf16 v[92:95], v[142:145], v[204:207], v[92:95]
	v_mfma_f32_16x16x32_bf16 v[88:91], v[154:157], v[204:207], v[88:91]
	v_mfma_f32_16x16x32_bf16 v[72:75], v[154:157], v[214:217], v[72:75]
	v_mfma_f32_16x16x32_bf16 v[76:79], v[142:145], v[214:217], v[76:79]
	s_setprio 0
	s_setprio 1
	v_mfma_f32_16x16x32_bf16 v[116:119], v[158:161], v[174:177], v[116:119]
	v_mfma_f32_16x16x32_bf16 v[112:115], v[166:169], v[174:177], v[112:115]
	v_mfma_f32_16x16x32_bf16 v[96:99], v[166:169], v[192:195], v[96:99]
	v_mfma_f32_16x16x32_bf16 v[100:103], v[158:161], v[192:195], v[100:103]
	v_mfma_f32_16x16x32_bf16 v[84:87], v[158:161], v[200:203], v[84:87]
	v_mfma_f32_16x16x32_bf16 v[80:83], v[166:169], v[200:203], v[80:83]
	v_mfma_f32_16x16x32_bf16 v[64:67], v[166:169], v[210:213], v[64:67]
	v_mfma_f32_16x16x32_bf16 v[68:71], v[158:161], v[210:213], v[68:71]
	v_mfma_f32_16x16x32_bf16 v[116:119], v[162:165], v[178:181], v[116:119]
	v_mfma_f32_16x16x32_bf16 v[112:115], v[170:173], v[178:181], v[112:115]
	v_mfma_f32_16x16x32_bf16 v[96:99], v[170:173], v[196:199], v[96:99]
	v_mfma_f32_16x16x32_bf16 v[100:103], v[162:165], v[196:199], v[100:103]
	v_mfma_f32_16x16x32_bf16 v[84:87], v[162:165], v[204:207], v[84:87]
	v_mfma_f32_16x16x32_bf16 v[80:83], v[170:173], v[204:207], v[80:83]
	v_mfma_f32_16x16x32_bf16 v[64:67], v[170:173], v[214:217], v[64:67]
	v_mfma_f32_16x16x32_bf16 v[68:71], v[162:165], v[214:217], v[68:71]
	s_setprio 0
	s_barrier
	s_add_i32 s70, s70, s25
	v_lshl_add_u64 v[182:183], s[68:69], 0, v[184:185]
	s_mov_b32 m0, s70
	ds_read_b128 v[174:177], v149 offset:16384
	ds_read_b128 v[178:181], v149 offset:17408
	ds_read_b128 v[192:195], v149 offset:18432
	ds_read_b128 v[196:199], v149 offset:19456
	ds_read_b128 v[200:203], v149 offset:20480
	ds_read_b128 v[204:207], v149 offset:21504
	ds_read_b128 v[210:213], v149 offset:22528
	ds_read_b128 v[214:217], v149 offset:23552
	global_load_lds_dwordx4 v[182:183], off
	s_add_i32 m0, s70, 0x2000
	v_lshl_add_u64 v[188:189], s[68:69], 0, v[128:129]
	s_add_u32 s68, s68, s8
	s_addc_u32 s69, s69, s9
	s_add_i32 s67, s67, s25
	global_load_lds_dwordx4 v[188:189], off
	v_lshl_add_u64 v[190:191], s[68:69], 0, v[184:185]
	s_mov_b32 m0, s67
	v_lshl_add_u64 v[208:209], s[68:69], 0, v[128:129]
	global_load_lds_dwordx4 v[190:191], off
	s_add_i32 m0, s67, 0x2000
	v_lshl_add_u64 v[218:219], s[46:47], 0, v[132:133]
	global_load_lds_dwordx4 v[208:209], off
	s_mov_b32 m0, s48
	v_lshl_add_u64 v[220:221], s[46:47], 0, v[130:131]
	global_load_lds_dwordx4 v[218:219], off
	s_mov_b32 m0, s49
	s_nop 0
	global_load_lds_dwordx4 v[220:221], off
	s_waitcnt vmcnt(8)
	s_waitcnt lgkmcnt(0)
	s_barrier
; #define PG8_STAGE(bufoff, gbase, voff) do { _Pragma("unroll") for (int _i = 0; _i < 2; ++_i) \
;         __builtin_amdgcn_global_load_lds((const unsigned*)((const char*)(gbase) + (voff)[_i]), (LAS unsigned*)(lds + (bufoff) + ldsw + _i * 8192), 16, 0, 0); } while (0)
; #define PG8_LDA(dst, b, h) do { _Pragma("unroll") for (int m = 0; m < 4; ++m) _Pragma("unroll") for (int k = 0; k < 2; ++k) dst[m][k] = *(const LAS bf16x8*)(lds + PG8_SA(b, h) + aoff + m * 2048 + k * 1024); } while (0)
; #define PG8_LDB(dst, b, h) do { _Pragma("unroll") for (int n = 0; n < 2; ++n) _Pragma("unroll") for (int k = 0; k < 2; ++k) dst[n][k] = *(const LAS bf16x8*)(lds + PG8_SB(b, h) + boff + n * 2048 + k * 1024); } while (0)
; #define PG8_MMA(ai, bj, At, Bt) do { __builtin_amdgcn_s_setprio(1); _Pragma("unroll") for (int m = 0; m < 4; ++m) _Pragma("unroll") for (int n = 0; n < 2; ++n) _Pragma("unroll") for (int k = 0; k < 2; ++k) \
;         acc[ai][bj][m][n] = __builtin_amdgcn_mfma_f32_16x16x32_bf16(Bt[n][k], At[m][k], acc[ai][bj][m][n], 0, 0, 0); __builtin_amdgcn_s_setprio(0); } while (0)
; #define PG8_WAIT_V(n) asm volatile("s_waitcnt vmcnt(" #n ")" ::: "memory")
; #define PG8_WAIT_L(n) asm volatile("s_waitcnt lgkmcnt(" #n ")" ::: "memory")
; #define PG8_BAR __builtin_amdgcn_s_barrier()
; #define PG8_SCHED __builtin_amdgcn_sched_barrier(0)
; template <class Epi, bool ALIGN_EPI>
; __device__ __forceinline__ void gemm_phase(LAS unsigned char* lds, const Gemm g, const StaticOrder& S, const Epi& E, const int wave_s) {
;     ...
;             PG8_WAIT_V(8); PG8_WAIT_L(0); PG8_BAR; PG8_MMA(1, 0, At, B0); PG8_MMA(1, 1, At, B1); PG8_BAR; PG8_SCHED;
;             PG8_LDB(B0, 1, 0); PG8_LDB(B1, 1, 1); PG8_SCHED; PG8_LDA(At, 1, 0); PG8_STAGE(PG8_SA(0, 1), a2 + hstepA, voffA);
;             PG8_WAIT_V(8); PG8_WAIT_L(0); PG8_BAR; PG8_MMA(0, 0, At, B0); PG8_MMA(0, 1, At, B1); PG8_BAR; PG8_SCHED;
	s_setprio 1
	s_waitcnt lgkmcnt(0)
	v_mfma_f32_16x16x32_bf16 v[60:63], v[138:141], v[174:177], v[60:63]
	v_mfma_f32_16x16x32_bf16 v[56:59], v[150:153], v[174:177], v[56:59]
	v_mfma_f32_16x16x32_bf16 v[40:43], v[150:153], v[192:195], v[40:43]
	v_mfma_f32_16x16x32_bf16 v[44:47], v[138:141], v[192:195], v[44:47]
	v_mfma_f32_16x16x32_bf16 v[28:31], v[138:141], v[200:203], v[28:31]
	v_mfma_f32_16x16x32_bf16 v[24:27], v[150:153], v[200:203], v[24:27]
	v_mfma_f32_16x16x32_bf16 v[8:11], v[150:153], v[210:213], v[8:11]
	v_mfma_f32_16x16x32_bf16 v[12:15], v[138:141], v[210:213], v[12:15]
	v_mfma_f32_16x16x32_bf16 v[60:63], v[142:145], v[178:181], v[60:63]
	v_mfma_f32_16x16x32_bf16 v[56:59], v[154:157], v[178:181], v[56:59]
	v_mfma_f32_16x16x32_bf16 v[40:43], v[154:157], v[196:199], v[40:43]
	v_mfma_f32_16x16x32_bf16 v[44:47], v[142:145], v[196:199], v[44:47]
	v_mfma_f32_16x16x32_bf16 v[28:31], v[142:145], v[204:207], v[28:31]
	v_mfma_f32_16x16x32_bf16 v[24:27], v[154:157], v[204:207], v[24:27]
	v_mfma_f32_16x16x32_bf16 v[8:11], v[154:157], v[214:217], v[8:11]
	v_mfma_f32_16x16x32_bf16 v[12:15], v[142:145], v[214:217], v[12:15]
	s_setprio 0
	s_setprio 1
	v_mfma_f32_16x16x32_bf16 v[52:55], v[158:161], v[174:177], v[52:55]
	v_mfma_f32_16x16x32_bf16 v[48:51], v[166:169], v[174:177], v[48:51]
	v_mfma_f32_16x16x32_bf16 v[32:35], v[166:169], v[192:195], v[32:35]
	v_mfma_f32_16x16x32_bf16 v[36:39], v[158:161], v[192:195], v[36:39]
	v_mfma_f32_16x16x32_bf16 v[20:23], v[158:161], v[200:203], v[20:23]
	v_mfma_f32_16x16x32_bf16 v[16:19], v[166:169], v[200:203], v[16:19]
	v_mfma_f32_16x16x32_bf16 v[0:3], v[166:169], v[210:213], v[0:3]
	v_mfma_f32_16x16x32_bf16 v[4:7], v[158:161], v[210:213], v[4:7]
	v_mfma_f32_16x16x32_bf16 v[52:55], v[162:165], v[178:181], v[52:55]
	v_mfma_f32_16x16x32_bf16 v[48:51], v[170:173], v[178:181], v[48:51]
	v_mfma_f32_16x16x32_bf16 v[32:35], v[170:173], v[196:199], v[32:35]
	v_mfma_f32_16x16x32_bf16 v[36:39], v[162:165], v[196:199], v[36:39]
	v_mfma_f32_16x16x32_bf16 v[20:23], v[162:165], v[204:207], v[20:23]
	v_mfma_f32_16x16x32_bf16 v[16:19], v[170:173], v[204:207], v[16:19]
	v_mfma_f32_16x16x32_bf16 v[0:3], v[170:173], v[214:217], v[0:3]
	v_mfma_f32_16x16x32_bf16 v[4:7], v[162:165], v[214:217], v[4:7]
	s_setprio 0
	s_barrier
	s_add_i32 s67, 0, 0x18000
	s_add_i32 s68, 0, 0x1c000
	v_add_u32_e32 v154, s67, v147
	v_add_u32_e32 v170, s68, v147
	ds_read_b128 v[138:141], v154
	ds_read_b128 v[142:145], v154 offset:1024
	ds_read_b128 v[150:153], v154 offset:2048
	ds_read_b128 v[154:157], v154 offset:3072
	ds_read_b128 v[158:161], v170
	ds_read_b128 v[162:165], v170 offset:1024
	ds_read_b128 v[166:169], v170 offset:2048
	ds_read_b128 v[170:173], v170 offset:3072
	s_add_u32 s46, s46, s6
	s_addc_u32 s47, s47, s7
	s_mov_b32 m0, s50
	v_lshl_add_u64 v[222:223], s[46:47], 0, v[132:133]
	ds_read_b128 v[174:177], v149 offset:32768
	ds_read_b128 v[178:181], v149 offset:33792
	ds_read_b128 v[192:195], v149 offset:34816
	ds_read_b128 v[196:199], v149 offset:35840
	ds_read_b128 v[200:203], v149 offset:36864
	ds_read_b128 v[204:207], v149 offset:37888
	ds_read_b128 v[210:213], v149 offset:38912
	ds_read_b128 v[214:217], v149 offset:39936
	global_load_lds_dwordx4 v[222:223], off
	v_lshl_add_u64 v[222:223], s[46:47], 0, v[130:131]
	s_mov_b32 m0, s51
	s_nop 0
	global_load_lds_dwordx4 v[222:223], off
	s_waitcnt vmcnt(8)
	s_waitcnt lgkmcnt(0)
	s_barrier
	s_setprio 1
	s_waitcnt lgkmcnt(0)
	v_mfma_f32_16x16x32_bf16 v[124:127], v[138:141], v[174:177], v[124:127]
	v_mfma_f32_16x16x32_bf16 v[120:123], v[150:153], v[174:177], v[120:123]
	v_mfma_f32_16x16x32_bf16 v[104:107], v[150:153], v[192:195], v[104:107]
	v_mfma_f32_16x16x32_bf16 v[108:111], v[138:141], v[192:195], v[108:111]
	v_mfma_f32_16x16x32_bf16 v[92:95], v[138:141], v[200:203], v[92:95]
	v_mfma_f32_16x16x32_bf16 v[88:91], v[150:153], v[200:203], v[88:91]
	v_mfma_f32_16x16x32_bf16 v[72:75], v[150:153], v[210:213], v[72:75]
	v_mfma_f32_16x16x32_bf16 v[76:79], v[138:141], v[210:213], v[76:79]
	v_mfma_f32_16x16x32_bf16 v[124:127], v[142:145], v[178:181], v[124:127]
	v_mfma_f32_16x16x32_bf16 v[120:123], v[154:157], v[178:181], v[120:123]
	v_mfma_f32_16x16x32_bf16 v[104:107], v[154:157], v[196:199], v[104:107]
	v_mfma_f32_16x16x32_bf16 v[108:111], v[142:145], v[196:199], v[108:111]
	v_mfma_f32_16x16x32_bf16 v[92:95], v[142:145], v[204:207], v[92:95]
	v_mfma_f32_16x16x32_bf16 v[88:91], v[154:157], v[204:207], v[88:91]
	v_mfma_f32_16x16x32_bf16 v[72:75], v[154:157], v[214:217], v[72:75]
	v_mfma_f32_16x16x32_bf16 v[76:79], v[142:145], v[214:217], v[76:79]
	s_setprio 0
	s_setprio 1
	v_mfma_f32_16x16x32_bf16 v[116:119], v[158:161], v[174:177], v[116:119]
	v_mfma_f32_16x16x32_bf16 v[112:115], v[166:169], v[174:177], v[112:115]
	v_mfma_f32_16x16x32_bf16 v[96:99], v[166:169], v[192:195], v[96:99]
	v_mfma_f32_16x16x32_bf16 v[100:103], v[158:161], v[192:195], v[100:103]
	v_mfma_f32_16x16x32_bf16 v[84:87], v[158:161], v[200:203], v[84:87]
	v_mfma_f32_16x16x32_bf16 v[80:83], v[166:169], v[200:203], v[80:83]
	v_mfma_f32_16x16x32_bf16 v[64:67], v[166:169], v[210:213], v[64:67]
	v_mfma_f32_16x16x32_bf16 v[68:71], v[158:161], v[210:213], v[68:71]
	v_mfma_f32_16x16x32_bf16 v[116:119], v[162:165], v[178:181], v[116:119]
	v_mfma_f32_16x16x32_bf16 v[112:115], v[170:173], v[178:181], v[112:115]
	v_mfma_f32_16x16x32_bf16 v[96:99], v[170:173], v[196:199], v[96:99]
	v_mfma_f32_16x16x32_bf16 v[100:103], v[162:165], v[196:199], v[100:103]
	v_mfma_f32_16x16x32_bf16 v[84:87], v[162:165], v[204:207], v[84:87]
	v_mfma_f32_16x16x32_bf16 v[80:83], v[170:173], v[204:207], v[80:83]
	v_mfma_f32_16x16x32_bf16 v[64:67], v[170:173], v[214:217], v[64:67]
	v_mfma_f32_16x16x32_bf16 v[68:71], v[162:165], v[214:217], v[68:71]
	s_setprio 0
	s_barrier
; #define PG8_STAGE(bufoff, gbase, voff) do { _Pragma("unroll") for (int _i = 0; _i < 2; ++_i) \
;         __builtin_amdgcn_global_load_lds((const unsigned*)((const char*)(gbase) + (voff)[_i]), (LAS unsigned*)(lds + (bufoff) + ldsw + _i * 8192), 16, 0, 0); } while (0)
; #define PG8_LDA(dst, b, h) do { _Pragma("unroll") for (int m = 0; m < 4; ++m) _Pragma("unroll") for (int k = 0; k < 2; ++k) dst[m][k] = *(const LAS bf16x8*)(lds + PG8_SA(b, h) + aoff + m * 2048 + k * 1024); } while (0)
; #define PG8_MMA(ai, bj, At, Bt) do { __builtin_amdgcn_s_setprio(1); _Pragma("unroll") for (int m = 0; m < 4; ++m) _Pragma("unroll") for (int n = 0; n < 2; ++n) _Pragma("unroll") for (int k = 0; k < 2; ++k) \
;         acc[ai][bj][m][n] = __builtin_amdgcn_mfma_f32_16x16x32_bf16(Bt[n][k], At[m][k], acc[ai][bj][m][n], 0, 0, 0); __builtin_amdgcn_s_setprio(0); } while (0)
; #define PG8_WAIT_V(n) asm volatile("s_waitcnt vmcnt(" #n ")" ::: "memory")
; #define PG8_WAIT_L(n) asm volatile("s_waitcnt lgkmcnt(" #n ")" ::: "memory")
; #define PG8_BAR __builtin_amdgcn_s_barrier()
; #define PG8_SCHED __builtin_amdgcn_sched_barrier(0)
; template <class Epi, bool ALIGN_EPI>
; __device__ __forceinline__ void gemm_phase(LAS unsigned char* lds, const Gemm g, const StaticOrder& S, const Epi& E, const int wave_s) {
;     ...
;             PG8_LDA(At, 1, 1); PG8_STAGE(PG8_SB(1, 0), b3, voffB); PG8_STAGE(PG8_SB(1, 1), b3 + hstepB, voffB); PG8_STAGE(PG8_SA(1, 0), a3, voffA);
;             PG8_WAIT_V(8); PG8_WAIT_L(0); PG8_BAR; PG8_MMA(1, 0, At, B0); PG8_MMA(1, 1, At, B1); PG8_BAR; PG8_SCHED;
;         }
	s_add_i32 s46, s67, s25
	v_lshl_add_u64 v[182:183], v[182:183], 0, s[64:65]
	s_mov_b32 m0, s46
	ds_read_b128 v[174:177], v149 offset:49152
	ds_read_b128 v[178:181], v149 offset:50176
	ds_read_b128 v[192:195], v149 offset:51200
	ds_read_b128 v[196:199], v149 offset:52224
	ds_read_b128 v[200:203], v149 offset:53248
	ds_read_b128 v[204:207], v149 offset:54272
	ds_read_b128 v[210:213], v149 offset:55296
	ds_read_b128 v[214:217], v149 offset:56320
	global_load_lds_dwordx4 v[182:183], off
	v_lshl_add_u64 v[182:183], v[188:189], 0, s[64:65]
	s_add_i32 m0, s46, 0x2000
	s_add_i32 s46, s68, s25
	global_load_lds_dwordx4 v[182:183], off
	v_lshl_add_u64 v[182:183], v[190:191], 0, s[64:65]
	s_mov_b32 m0, s46
	s_nop 0
	global_load_lds_dwordx4 v[182:183], off
	v_lshl_add_u64 v[182:183], v[208:209], 0, s[64:65]
	s_add_i32 m0, s46, 0x2000
	s_nop 0
	global_load_lds_dwordx4 v[182:183], off
	v_lshl_add_u64 v[182:183], v[218:219], 0, s[64:65]
	s_mov_b32 m0, s53
	s_nop 0
	global_load_lds_dwordx4 v[182:183], off
	v_lshl_add_u64 v[182:183], v[220:221], 0, s[64:65]
	s_mov_b32 m0, s54
	s_nop 0
	global_load_lds_dwordx4 v[182:183], off
	s_waitcnt vmcnt(8)
	s_waitcnt lgkmcnt(0)
	s_barrier
	s_setprio 1
	s_waitcnt lgkmcnt(0)
	v_mfma_f32_16x16x32_bf16 v[60:63], v[138:141], v[174:177], v[60:63]
	v_mfma_f32_16x16x32_bf16 v[56:59], v[150:153], v[174:177], v[56:59]
	v_mfma_f32_16x16x32_bf16 v[40:43], v[150:153], v[192:195], v[40:43]
	v_mfma_f32_16x16x32_bf16 v[44:47], v[138:141], v[192:195], v[44:47]
	v_mfma_f32_16x16x32_bf16 v[28:31], v[138:141], v[200:203], v[28:31]
	v_mfma_f32_16x16x32_bf16 v[24:27], v[150:153], v[200:203], v[24:27]
	v_mfma_f32_16x16x32_bf16 v[8:11], v[150:153], v[210:213], v[8:11]
	v_mfma_f32_16x16x32_bf16 v[12:15], v[138:141], v[210:213], v[12:15]
	v_mfma_f32_16x16x32_bf16 v[60:63], v[142:145], v[178:181], v[60:63]
	v_mfma_f32_16x16x32_bf16 v[56:59], v[154:157], v[178:181], v[56:59]
	v_mfma_f32_16x16x32_bf16 v[40:43], v[154:157], v[196:199], v[40:43]
	v_mfma_f32_16x16x32_bf16 v[44:47], v[142:145], v[196:199], v[44:47]
	v_mfma_f32_16x16x32_bf16 v[28:31], v[142:145], v[204:207], v[28:31]
	v_mfma_f32_16x16x32_bf16 v[24:27], v[154:157], v[204:207], v[24:27]
	v_mfma_f32_16x16x32_bf16 v[8:11], v[154:157], v[214:217], v[8:11]
	v_mfma_f32_16x16x32_bf16 v[12:15], v[142:145], v[214:217], v[12:15]
	s_setprio 0
	s_setprio 1
	v_mfma_f32_16x16x32_bf16 v[52:55], v[158:161], v[174:177], v[52:55]
	v_mfma_f32_16x16x32_bf16 v[48:51], v[166:169], v[174:177], v[48:51]
	v_mfma_f32_16x16x32_bf16 v[32:35], v[166:169], v[192:195], v[32:35]
	v_mfma_f32_16x16x32_bf16 v[36:39], v[158:161], v[192:195], v[36:39]
	v_mfma_f32_16x16x32_bf16 v[20:23], v[158:161], v[200:203], v[20:23]
	v_mfma_f32_16x16x32_bf16 v[16:19], v[166:169], v[200:203], v[16:19]
	v_mfma_f32_16x16x32_bf16 v[0:3], v[166:169], v[210:213], v[0:3]
	v_mfma_f32_16x16x32_bf16 v[4:7], v[158:161], v[210:213], v[4:7]
	v_mfma_f32_16x16x32_bf16 v[52:55], v[162:165], v[178:181], v[52:55]
	v_mfma_f32_16x16x32_bf16 v[48:51], v[170:173], v[178:181], v[48:51]
	v_mfma_f32_16x16x32_bf16 v[32:35], v[170:173], v[196:199], v[32:35]
	v_mfma_f32_16x16x32_bf16 v[36:39], v[162:165], v[196:199], v[36:39]
	v_mfma_f32_16x16x32_bf16 v[20:23], v[162:165], v[204:207], v[20:23]
	v_mfma_f32_16x16x32_bf16 v[16:19], v[170:173], v[204:207], v[16:19]
	v_mfma_f32_16x16x32_bf16 v[0:3], v[170:173], v[214:217], v[0:3]
	v_mfma_f32_16x16x32_bf16 v[4:7], v[162:165], v[214:217], v[4:7]
	s_setprio 0
	s_barrier
	s_add_u32 s61, s61, 0x100
	s_addc_u32 s63, s63, 0
	s_add_u32 s38, s38, 0x100
	s_addc_u32 s39, s39, 0
	s_cmp_ge_i32 s66, s52
	s_mov_b32 s46, s66
	s_cbranch_scc0 .LBB0_598
	s_and_b64 vcc, exec, s[20:21]
	s_cbranch_vccz .LBB0_601

; #define PG8_STAGE(bufoff, gbase, voff) do { _Pragma("unroll") for (int _i = 0; _i < 2; ++_i) \
;         __builtin_amdgcn_global_load_lds((const unsigned*)((const char*)(gbase) + (voff)[_i]), (LAS unsigned*)(lds + (bufoff) + ldsw + _i * 8192), 16, 0, 0); } while (0)
; #define PG8_LDA(dst, b, h) do { _Pragma("unroll") for (int m = 0; m < 4; ++m) _Pragma("unroll") for (int k = 0; k < 2; ++k) dst[m][k] = *(const LAS bf16x8*)(lds + PG8_SA(b, h) + aoff + m * 2048 + k * 1024); } while (0)
; #define PG8_LDB(dst, b, h) do { _Pragma("unroll") for (int n = 0; n < 2; ++n) _Pragma("unroll") for (int k = 0; k < 2; ++k) dst[n][k] = *(const LAS bf16x8*)(lds + PG8_SB(b, h) + boff + n * 2048 + k * 1024); } while (0)
; #define PG8_MMA(ai, bj, At, Bt) do { __builtin_amdgcn_s_setprio(1); _Pragma("unroll") for (int m = 0; m < 4; ++m) _Pragma("unroll") for (int n = 0; n < 2; ++n) _Pragma("unroll") for (int k = 0; k < 2; ++k) \
;         acc[ai][bj][m][n] = __builtin_amdgcn_mfma_f32_16x16x32_bf16(Bt[n][k], At[m][k], acc[ai][bj][m][n], 0, 0, 0); __builtin_amdgcn_s_setprio(0); } while (0)
; #define PG8_WAIT_V(n) asm volatile("s_waitcnt vmcnt(" #n ")" ::: "memory")
; #define PG8_WAIT_L(n) asm volatile("s_waitcnt lgkmcnt(" #n ")" ::: "memory")
; #define PG8_BAR __builtin_amdgcn_s_barrier()
; #define PG8_SCHED __builtin_amdgcn_sched_barrier(0)
; template <class Epi, bool ALIGN_EPI>
; __device__ __forceinline__ void gemm_phase(LAS unsigned char* lds, const Gemm g, const StaticOrder& S, const Epi& E, const int wave_s) {
;     ...
;         for (int t = 0; t < nt; t += 2) {
;             const bool last = (t == nt - 2);
;             const char* a1 = cA + (size_t)(t + 1) * kstep;
;             const char* a2 = last ? nA : cA + (size_t)(t + 2) * kstep; const char* b2 = last ? nB : cB + (size_t)(t + 2) * kstep;
;             const char* a3 = a2 + kstep; const char* b3 = b2 + kstep;
;             PG8_LDB(B0, 0, 0); PG8_LDB(B1, 0, 1); PG8_SCHED; PG8_LDA(At, 0, 0); PG8_STAGE(PG8_SA(1, 1), a1 + hstepA, voffA);
;             PG8_WAIT_V(8); PG8_WAIT_L(0); PG8_BAR; PG8_MMA(0, 0, At, B0); PG8_MMA(0, 1, At, B1); PG8_BAR; PG8_SCHED;
;             PG8_LDA(At, 0, 1); PG8_STAGE(PG8_SB(0, 0), b2, voffB); PG8_STAGE(PG8_SB(0, 1), b2 + hstepB, voffB); PG8_STAGE(PG8_SA(0, 0), a2, voffA);
;             PG8_WAIT_V(8); PG8_WAIT_L(0); PG8_BAR; PG8_MMA(1, 0, At, B0); PG8_MMA(1, 1, At, B1); PG8_BAR; PG8_SCHED;
.LBB0_641:
	s_add_i32 s59, s40, 2
	s_add_u32 s60, s38, 0x80
	s_addc_u32 s41, s39, 0
	s_add_i32 s63, 0, 0x10000
	s_cmp_eq_u32 s51, s40
	s_cselect_b32 s41, s1, s41
	s_cselect_b32 s40, s0, s60
	s_cselect_b32 s61, s29, s58
	s_cselect_b32 s60, s28, s57
	s_add_i32 s66, 0, 0x14000
	v_add_u32_e32 v154, s63, v147
	v_add_u32_e32 v170, s66, v147
	ds_read_b128 v[138:141], v154
	ds_read_b128 v[142:145], v154 offset:1024
	ds_read_b128 v[150:153], v154 offset:2048
	ds_read_b128 v[154:157], v154 offset:3072
	ds_read_b128 v[158:161], v170
	ds_read_b128 v[162:165], v170 offset:1024
	ds_read_b128 v[166:169], v170 offset:2048
	ds_read_b128 v[170:173], v170 offset:3072
	v_lshl_add_u64 v[182:183], s[38:39], 0, v[136:137]
	s_add_i32 m0, s24, 0xc000
	ds_read_b128 v[174:177], v149
	ds_read_b128 v[178:181], v149 offset:1024
	ds_read_b128 v[192:195], v149 offset:2048
	ds_read_b128 v[196:199], v149 offset:3072
	ds_read_b128 v[200:203], v149 offset:4096
	ds_read_b128 v[204:207], v149 offset:5120
	ds_read_b128 v[210:213], v149 offset:6144
	ds_read_b128 v[214:217], v149 offset:7168
	global_load_lds_dwordx4 v[182:183], off
	v_lshl_add_u64 v[182:183], s[38:39], 0, v[134:135]
	s_add_i32 m0, s24, 0xe000
	s_nop 0
	global_load_lds_dwordx4 v[182:183], off
	s_waitcnt vmcnt(8)
	s_waitcnt lgkmcnt(0)
	s_barrier
	s_setprio 1
	s_waitcnt lgkmcnt(0)
	v_mfma_f32_16x16x32_bf16 v[124:127], v[138:141], v[174:177], v[124:127]
	v_mfma_f32_16x16x32_bf16 v[120:123], v[150:153], v[174:177], v[120:123]
	v_mfma_f32_16x16x32_bf16 v[104:107], v[150:153], v[192:195], v[104:107]
	v_mfma_f32_16x16x32_bf16 v[108:111], v[138:141], v[192:195], v[108:111]
	v_mfma_f32_16x16x32_bf16 v[92:95], v[138:141], v[200:203], v[92:95]
	v_mfma_f32_16x16x32_bf16 v[88:91], v[150:153], v[200:203], v[88:91]
	v_mfma_f32_16x16x32_bf16 v[72:75], v[150:153], v[210:213], v[72:75]
	v_mfma_f32_16x16x32_bf16 v[76:79], v[138:141], v[210:213], v[76:79]
	v_mfma_f32_16x16x32_bf16 v[124:127], v[142:145], v[178:181], v[124:127]
	v_mfma_f32_16x16x32_bf16 v[120:123], v[154:157], v[178:181], v[120:123]
	v_mfma_f32_16x16x32_bf16 v[104:107], v[154:157], v[196:199], v[104:107]
	v_mfma_f32_16x16x32_bf16 v[108:111], v[142:145], v[196:199], v[108:111]
	v_mfma_f32_16x16x32_bf16 v[92:95], v[142:145], v[204:207], v[92:95]
	v_mfma_f32_16x16x32_bf16 v[88:91], v[154:157], v[204:207], v[88:91]
	v_mfma_f32_16x16x32_bf16 v[72:75], v[154:157], v[214:217], v[72:75]
	v_mfma_f32_16x16x32_bf16 v[76:79], v[142:145], v[214:217], v[76:79]
	s_setprio 0
	s_setprio 1
	v_mfma_f32_16x16x32_bf16 v[116:119], v[158:161], v[174:177], v[116:119]
	v_mfma_f32_16x16x32_bf16 v[112:115], v[166:169], v[174:177], v[112:115]
	v_mfma_f32_16x16x32_bf16 v[96:99], v[166:169], v[192:195], v[96:99]
	v_mfma_f32_16x16x32_bf16 v[100:103], v[158:161], v[192:195], v[100:103]
	v_mfma_f32_16x16x32_bf16 v[84:87], v[158:161], v[200:203], v[84:87]
	v_mfma_f32_16x16x32_bf16 v[80:83], v[166:169], v[200:203], v[80:83]
	v_mfma_f32_16x16x32_bf16 v[64:67], v[166:169], v[210:213], v[64:67]
	v_mfma_f32_16x16x32_bf16 v[68:71], v[158:161], v[210:213], v[68:71]
	v_mfma_f32_16x16x32_bf16 v[116:119], v[162:165], v[178:181], v[116:119]
	v_mfma_f32_16x16x32_bf16 v[112:115], v[170:173], v[178:181], v[112:115]
	v_mfma_f32_16x16x32_bf16 v[96:99], v[170:173], v[196:199], v[96:99]
	v_mfma_f32_16x16x32_bf16 v[100:103], v[162:165], v[196:199], v[100:103]
	v_mfma_f32_16x16x32_bf16 v[84:87], v[162:165], v[204:207], v[84:87]
	v_mfma_f32_16x16x32_bf16 v[80:83], v[170:173], v[204:207], v[80:83]
	v_mfma_f32_16x16x32_bf16 v[64:67], v[170:173], v[214:217], v[64:67]
	v_mfma_f32_16x16x32_bf16 v[68:71], v[162:165], v[214:217], v[68:71]
	s_setprio 0
	s_barrier
	s_add_i32 s63, s63, s4
	v_lshl_add_u64 v[182:183], s[60:61], 0, v[184:185]
	s_mov_b32 m0, s63
	ds_read_b128 v[174:177], v149 offset:16384
	ds_read_b128 v[178:181], v149 offset:17408
	ds_read_b128 v[192:195], v149 offset:18432
	ds_read_b128 v[196:199], v149 offset:19456
	ds_read_b128 v[200:203], v149 offset:20480
	ds_read_b128 v[204:207], v149 offset:21504
	ds_read_b128 v[210:213], v149 offset:22528
	ds_read_b128 v[214:217], v149 offset:23552
	global_load_lds_dwordx4 v[182:183], off
	s_add_i32 m0, s63, 0x2000
	v_lshl_add_u64 v[188:189], s[60:61], 0, v[128:129]
	s_add_u32 s60, s60, s8
	s_addc_u32 s61, s61, s9
	s_add_i32 s63, s66, s4
	global_load_lds_dwordx4 v[188:189], off
	v_lshl_add_u64 v[190:191], s[60:61], 0, v[184:185]
	s_mov_b32 m0, s63
	v_lshl_add_u64 v[208:209], s[60:61], 0, v[128:129]
	global_load_lds_dwordx4 v[190:191], off
	s_add_i32 m0, s63, 0x2000
	v_lshl_add_u64 v[218:219], s[40:41], 0, v[132:133]
	global_load_lds_dwordx4 v[208:209], off
	s_mov_b32 m0, s24
	v_lshl_add_u64 v[220:221], s[40:41], 0, v[130:131]
	global_load_lds_dwordx4 v[218:219], off
	s_mov_b32 m0, s25
	s_nop 0
	global_load_lds_dwordx4 v[220:221], off
	s_waitcnt vmcnt(8)
	s_waitcnt lgkmcnt(0)
	s_barrier
; #define PG8_STAGE(bufoff, gbase, voff) do { _Pragma("unroll") for (int _i = 0; _i < 2; ++_i) \
;         __builtin_amdgcn_global_load_lds((const unsigned*)((const char*)(gbase) + (voff)[_i]), (LAS unsigned*)(lds + (bufoff) + ldsw + _i * 8192), 16, 0, 0); } while (0)
; #define PG8_LDA(dst, b, h) do { _Pragma("unroll") for (int m = 0; m < 4; ++m) _Pragma("unroll") for (int k = 0; k < 2; ++k) dst[m][k] = *(const LAS bf16x8*)(lds + PG8_SA(b, h) + aoff + m * 2048 + k * 1024); } while (0)
; #define PG8_LDB(dst, b, h) do { _Pragma("unroll") for (int n = 0; n < 2; ++n) _Pragma("unroll") for (int k = 0; k < 2; ++k) dst[n][k] = *(const LAS bf16x8*)(lds + PG8_SB(b, h) + boff + n * 2048 + k * 1024); } while (0)
; #define PG8_MMA(ai, bj, At, Bt) do { __builtin_amdgcn_s_setprio(1); _Pragma("unroll") for (int m = 0; m < 4; ++m) _Pragma("unroll") for (int n = 0; n < 2; ++n) _Pragma("unroll") for (int k = 0; k < 2; ++k) \
;         acc[ai][bj][m][n] = __builtin_amdgcn_mfma_f32_16x16x32_bf16(Bt[n][k], At[m][k], acc[ai][bj][m][n], 0, 0, 0); __builtin_amdgcn_s_setprio(0); } while (0)
; #define PG8_WAIT_V(n) asm volatile("s_waitcnt vmcnt(" #n ")" ::: "memory")
; #define PG8_WAIT_L(n) asm volatile("s_waitcnt lgkmcnt(" #n ")" ::: "memory")
; #define PG8_BAR __builtin_amdgcn_s_barrier()
; #define PG8_SCHED __builtin_amdgcn_sched_barrier(0)
; template <class Epi, bool ALIGN_EPI>
; __device__ __forceinline__ void gemm_phase(LAS unsigned char* lds, const Gemm g, const StaticOrder& S, const Epi& E, const int wave_s) {
;     ...
;             PG8_WAIT_V(8); PG8_WAIT_L(0); PG8_BAR; PG8_MMA(1, 0, At, B0); PG8_MMA(1, 1, At, B1); PG8_BAR; PG8_SCHED;
;             PG8_LDB(B0, 1, 0); PG8_LDB(B1, 1, 1); PG8_SCHED; PG8_LDA(At, 1, 0); PG8_STAGE(PG8_SA(0, 1), a2 + hstepA, voffA);
;             PG8_WAIT_V(8); PG8_WAIT_L(0); PG8_BAR; PG8_MMA(0, 0, At, B0); PG8_MMA(0, 1, At, B1); PG8_BAR; PG8_SCHED;
	s_setprio 1
	s_waitcnt lgkmcnt(0)
	v_mfma_f32_16x16x32_bf16 v[60:63], v[138:141], v[174:177], v[60:63]
	v_mfma_f32_16x16x32_bf16 v[56:59], v[150:153], v[174:177], v[56:59]
	v_mfma_f32_16x16x32_bf16 v[40:43], v[150:153], v[192:195], v[40:43]
	v_mfma_f32_16x16x32_bf16 v[44:47], v[138:141], v[192:195], v[44:47]
	v_mfma_f32_16x16x32_bf16 v[28:31], v[138:141], v[200:203], v[28:31]
	v_mfma_f32_16x16x32_bf16 v[24:27], v[150:153], v[200:203], v[24:27]
	v_mfma_f32_16x16x32_bf16 v[8:11], v[150:153], v[210:213], v[8:11]
	v_mfma_f32_16x16x32_bf16 v[12:15], v[138:141], v[210:213], v[12:15]
	v_mfma_f32_16x16x32_bf16 v[60:63], v[142:145], v[178:181], v[60:63]
	v_mfma_f32_16x16x32_bf16 v[56:59], v[154:157], v[178:181], v[56:59]
	v_mfma_f32_16x16x32_bf16 v[40:43], v[154:157], v[196:199], v[40:43]
	v_mfma_f32_16x16x32_bf16 v[44:47], v[142:145], v[196:199], v[44:47]
	v_mfma_f32_16x16x32_bf16 v[28:31], v[142:145], v[204:207], v[28:31]
	v_mfma_f32_16x16x32_bf16 v[24:27], v[154:157], v[204:207], v[24:27]
	v_mfma_f32_16x16x32_bf16 v[8:11], v[154:157], v[214:217], v[8:11]
	v_mfma_f32_16x16x32_bf16 v[12:15], v[142:145], v[214:217], v[12:15]
	s_setprio 0
	s_setprio 1
	v_mfma_f32_16x16x32_bf16 v[52:55], v[158:161], v[174:177], v[52:55]
	v_mfma_f32_16x16x32_bf16 v[48:51], v[166:169], v[174:177], v[48:51]
	v_mfma_f32_16x16x32_bf16 v[32:35], v[166:169], v[192:195], v[32:35]
	v_mfma_f32_16x16x32_bf16 v[36:39], v[158:161], v[192:195], v[36:39]
	v_mfma_f32_16x16x32_bf16 v[20:23], v[158:161], v[200:203], v[20:23]
	v_mfma_f32_16x16x32_bf16 v[16:19], v[166:169], v[200:203], v[16:19]
	v_mfma_f32_16x16x32_bf16 v[0:3], v[166:169], v[210:213], v[0:3]
	v_mfma_f32_16x16x32_bf16 v[4:7], v[158:161], v[210:213], v[4:7]
	v_mfma_f32_16x16x32_bf16 v[52:55], v[162:165], v[178:181], v[52:55]
	v_mfma_f32_16x16x32_bf16 v[48:51], v[170:173], v[178:181], v[48:51]
	v_mfma_f32_16x16x32_bf16 v[32:35], v[170:173], v[196:199], v[32:35]
	v_mfma_f32_16x16x32_bf16 v[36:39], v[162:165], v[196:199], v[36:39]
	v_mfma_f32_16x16x32_bf16 v[20:23], v[162:165], v[204:207], v[20:23]
	v_mfma_f32_16x16x32_bf16 v[16:19], v[170:173], v[204:207], v[16:19]
	v_mfma_f32_16x16x32_bf16 v[0:3], v[170:173], v[214:217], v[0:3]
	v_mfma_f32_16x16x32_bf16 v[4:7], v[162:165], v[214:217], v[4:7]
	s_setprio 0
	s_barrier
	s_add_i32 s60, 0, 0x18000
	s_add_i32 s61, 0, 0x1c000
	v_add_u32_e32 v154, s60, v147
	v_add_u32_e32 v170, s61, v147
	ds_read_b128 v[138:141], v154
	ds_read_b128 v[142:145], v154 offset:1024
	ds_read_b128 v[150:153], v154 offset:2048
	ds_read_b128 v[154:157], v154 offset:3072
	ds_read_b128 v[158:161], v170
	ds_read_b128 v[162:165], v170 offset:1024
	ds_read_b128 v[166:169], v170 offset:2048
	ds_read_b128 v[170:173], v170 offset:3072
	s_add_u32 s40, s40, s6
	s_addc_u32 s41, s41, s7
	s_mov_b32 m0, s46
	v_lshl_add_u64 v[222:223], s[40:41], 0, v[132:133]
	ds_read_b128 v[174:177], v149 offset:32768
	ds_read_b128 v[178:181], v149 offset:33792
	ds_read_b128 v[192:195], v149 offset:34816
	ds_read_b128 v[196:199], v149 offset:35840
	ds_read_b128 v[200:203], v149 offset:36864
	ds_read_b128 v[204:207], v149 offset:37888
	ds_read_b128 v[210:213], v149 offset:38912
	ds_read_b128 v[214:217], v149 offset:39936
	global_load_lds_dwordx4 v[222:223], off
	v_lshl_add_u64 v[222:223], s[40:41], 0, v[130:131]
	s_mov_b32 m0, s47
	s_nop 0
	global_load_lds_dwordx4 v[222:223], off
	s_waitcnt vmcnt(8)
	s_waitcnt lgkmcnt(0)
	s_barrier
	s_setprio 1
	s_waitcnt lgkmcnt(0)
	v_mfma_f32_16x16x32_bf16 v[124:127], v[138:141], v[174:177], v[124:127]
	v_mfma_f32_16x16x32_bf16 v[120:123], v[150:153], v[174:177], v[120:123]
	v_mfma_f32_16x16x32_bf16 v[104:107], v[150:153], v[192:195], v[104:107]
	v_mfma_f32_16x16x32_bf16 v[108:111], v[138:141], v[192:195], v[108:111]
	v_mfma_f32_16x16x32_bf16 v[92:95], v[138:141], v[200:203], v[92:95]
	v_mfma_f32_16x16x32_bf16 v[88:91], v[150:153], v[200:203], v[88:91]
	v_mfma_f32_16x16x32_bf16 v[72:75], v[150:153], v[210:213], v[72:75]
	v_mfma_f32_16x16x32_bf16 v[76:79], v[138:141], v[210:213], v[76:79]
	v_mfma_f32_16x16x32_bf16 v[124:127], v[142:145], v[178:181], v[124:127]
	v_mfma_f32_16x16x32_bf16 v[120:123], v[154:157], v[178:181], v[120:123]
	v_mfma_f32_16x16x32_bf16 v[104:107], v[154:157], v[196:199], v[104:107]
	v_mfma_f32_16x16x32_bf16 v[108:111], v[142:145], v[196:199], v[108:111]
	v_mfma_f32_16x16x32_bf16 v[92:95], v[142:145], v[204:207], v[92:95]
	v_mfma_f32_16x16x32_bf16 v[88:91], v[154:157], v[204:207], v[88:91]
	v_mfma_f32_16x16x32_bf16 v[72:75], v[154:157], v[214:217], v[72:75]
	v_mfma_f32_16x16x32_bf16 v[76:79], v[142:145], v[214:217], v[76:79]
	s_setprio 0
	s_setprio 1
	v_mfma_f32_16x16x32_bf16 v[116:119], v[158:161], v[174:177], v[116:119]
	v_mfma_f32_16x16x32_bf16 v[112:115], v[166:169], v[174:177], v[112:115]
	v_mfma_f32_16x16x32_bf16 v[96:99], v[166:169], v[192:195], v[96:99]
	v_mfma_f32_16x16x32_bf16 v[100:103], v[158:161], v[192:195], v[100:103]
	v_mfma_f32_16x16x32_bf16 v[84:87], v[158:161], v[200:203], v[84:87]
	v_mfma_f32_16x16x32_bf16 v[80:83], v[166:169], v[200:203], v[80:83]
	v_mfma_f32_16x16x32_bf16 v[64:67], v[166:169], v[210:213], v[64:67]
	v_mfma_f32_16x16x32_bf16 v[68:71], v[158:161], v[210:213], v[68:71]
	v_mfma_f32_16x16x32_bf16 v[116:119], v[162:165], v[178:181], v[116:119]
	v_mfma_f32_16x16x32_bf16 v[112:115], v[170:173], v[178:181], v[112:115]
	v_mfma_f32_16x16x32_bf16 v[96:99], v[170:173], v[196:199], v[96:99]
	v_mfma_f32_16x16x32_bf16 v[100:103], v[162:165], v[196:199], v[100:103]
	v_mfma_f32_16x16x32_bf16 v[84:87], v[162:165], v[204:207], v[84:87]
	v_mfma_f32_16x16x32_bf16 v[80:83], v[170:173], v[204:207], v[80:83]
	v_mfma_f32_16x16x32_bf16 v[64:67], v[170:173], v[214:217], v[64:67]
	v_mfma_f32_16x16x32_bf16 v[68:71], v[162:165], v[214:217], v[68:71]
	s_setprio 0
	s_barrier
; #define PG8_STAGE(bufoff, gbase, voff) do { _Pragma("unroll") for (int _i = 0; _i < 2; ++_i) \
;         __builtin_amdgcn_global_load_lds((const unsigned*)((const char*)(gbase) + (voff)[_i]), (LAS unsigned*)(lds + (bufoff) + ldsw + _i * 8192), 16, 0, 0); } while (0)
; #define PG8_LDA(dst, b, h) do { _Pragma("unroll") for (int m = 0; m < 4; ++m) _Pragma("unroll") for (int k = 0; k < 2; ++k) dst[m][k] = *(const LAS bf16x8*)(lds + PG8_SA(b, h) + aoff + m * 2048 + k * 1024); } while (0)
; #define PG8_MMA(ai, bj, At, Bt) do { __builtin_amdgcn_s_setprio(1); _Pragma("unroll") for (int m = 0; m < 4; ++m) _Pragma("unroll") for (int n = 0; n < 2; ++n) _Pragma("unroll") for (int k = 0; k < 2; ++k) \
;         acc[ai][bj][m][n] = __builtin_amdgcn_mfma_f32_16x16x32_bf16(Bt[n][k], At[m][k], acc[ai][bj][m][n], 0, 0, 0); __builtin_amdgcn_s_setprio(0); } while (0)
; #define PG8_WAIT_V(n) asm volatile("s_waitcnt vmcnt(" #n ")" ::: "memory")
; #define PG8_WAIT_L(n) asm volatile("s_waitcnt lgkmcnt(" #n ")" ::: "memory")
; #define PG8_BAR __builtin_amdgcn_s_barrier()
; #define PG8_SCHED __builtin_amdgcn_sched_barrier(0)
; template <class Epi, bool ALIGN_EPI>
; __device__ __forceinline__ void gemm_phase(LAS unsigned char* lds, const Gemm g, const StaticOrder& S, const Epi& E, const int wave_s) {
;     ...
;             PG8_LDA(At, 1, 1); PG8_STAGE(PG8_SB(1, 0), b3, voffB); PG8_STAGE(PG8_SB(1, 1), b3 + hstepB, voffB); PG8_STAGE(PG8_SA(1, 0), a3, voffA);
;             PG8_WAIT_V(8); PG8_WAIT_L(0); PG8_BAR; PG8_MMA(1, 0, At, B0); PG8_MMA(1, 1, At, B1); PG8_BAR; PG8_SCHED;
;         }
	s_add_i32 s40, s60, s4
	v_lshl_add_u64 v[182:183], v[182:183], 0, s[64:65]
	s_mov_b32 m0, s40
	ds_read_b128 v[174:177], v149 offset:49152
	ds_read_b128 v[178:181], v149 offset:50176
	ds_read_b128 v[192:195], v149 offset:51200
	ds_read_b128 v[196:199], v149 offset:52224
	ds_read_b128 v[200:203], v149 offset:53248
	ds_read_b128 v[204:207], v149 offset:54272
	ds_read_b128 v[210:213], v149 offset:55296
	ds_read_b128 v[214:217], v149 offset:56320
	global_load_lds_dwordx4 v[182:183], off
	v_lshl_add_u64 v[182:183], v[188:189], 0, s[64:65]
	s_add_i32 m0, s40, 0x2000
	s_add_i32 s40, s61, s4
	global_load_lds_dwordx4 v[182:183], off
	v_lshl_add_u64 v[182:183], v[190:191], 0, s[64:65]
	s_mov_b32 m0, s40
	s_nop 0
	global_load_lds_dwordx4 v[182:183], off
	v_lshl_add_u64 v[182:183], v[208:209], 0, s[64:65]
	s_add_i32 m0, s40, 0x2000
	s_nop 0
	global_load_lds_dwordx4 v[182:183], off
	v_lshl_add_u64 v[182:183], v[218:219], 0, s[64:65]
	s_mov_b32 m0, s48
	s_nop 0
	global_load_lds_dwordx4 v[182:183], off
	v_lshl_add_u64 v[182:183], v[220:221], 0, s[64:65]
	s_mov_b32 m0, s49
	s_nop 0
	global_load_lds_dwordx4 v[182:183], off
	s_waitcnt vmcnt(8)
	s_waitcnt lgkmcnt(0)
	s_barrier
	s_setprio 1
	s_waitcnt lgkmcnt(0)
	v_mfma_f32_16x16x32_bf16 v[60:63], v[138:141], v[174:177], v[60:63]
	v_mfma_f32_16x16x32_bf16 v[56:59], v[150:153], v[174:177], v[56:59]
	v_mfma_f32_16x16x32_bf16 v[40:43], v[150:153], v[192:195], v[40:43]
	v_mfma_f32_16x16x32_bf16 v[44:47], v[138:141], v[192:195], v[44:47]
	v_mfma_f32_16x16x32_bf16 v[28:31], v[138:141], v[200:203], v[28:31]
	v_mfma_f32_16x16x32_bf16 v[24:27], v[150:153], v[200:203], v[24:27]
	v_mfma_f32_16x16x32_bf16 v[8:11], v[150:153], v[210:213], v[8:11]
	v_mfma_f32_16x16x32_bf16 v[12:15], v[138:141], v[210:213], v[12:15]
	v_mfma_f32_16x16x32_bf16 v[60:63], v[142:145], v[178:181], v[60:63]
	v_mfma_f32_16x16x32_bf16 v[56:59], v[154:157], v[178:181], v[56:59]
	v_mfma_f32_16x16x32_bf16 v[40:43], v[154:157], v[196:199], v[40:43]
	v_mfma_f32_16x16x32_bf16 v[44:47], v[142:145], v[196:199], v[44:47]
	v_mfma_f32_16x16x32_bf16 v[28:31], v[142:145], v[204:207], v[28:31]
	v_mfma_f32_16x16x32_bf16 v[24:27], v[154:157], v[204:207], v[24:27]
	v_mfma_f32_16x16x32_bf16 v[8:11], v[154:157], v[214:217], v[8:11]
	v_mfma_f32_16x16x32_bf16 v[12:15], v[142:145], v[214:217], v[12:15]
	s_setprio 0
	s_setprio 1
	v_mfma_f32_16x16x32_bf16 v[52:55], v[158:161], v[174:177], v[52:55]
	v_mfma_f32_16x16x32_bf16 v[48:51], v[166:169], v[174:177], v[48:51]
	v_mfma_f32_16x16x32_bf16 v[32:35], v[166:169], v[192:195], v[32:35]
	v_mfma_f32_16x16x32_bf16 v[36:39], v[158:161], v[192:195], v[36:39]
	v_mfma_f32_16x16x32_bf16 v[20:23], v[158:161], v[200:203], v[20:23]
	v_mfma_f32_16x16x32_bf16 v[16:19], v[166:169], v[200:203], v[16:19]
	v_mfma_f32_16x16x32_bf16 v[0:3], v[166:169], v[210:213], v[0:3]
	v_mfma_f32_16x16x32_bf16 v[4:7], v[158:161], v[210:213], v[4:7]
	v_mfma_f32_16x16x32_bf16 v[52:55], v[162:165], v[178:181], v[52:55]
	v_mfma_f32_16x16x32_bf16 v[48:51], v[170:173], v[178:181], v[48:51]
	v_mfma_f32_16x16x32_bf16 v[32:35], v[170:173], v[196:199], v[32:35]
	v_mfma_f32_16x16x32_bf16 v[36:39], v[162:165], v[196:199], v[36:39]
	v_mfma_f32_16x16x32_bf16 v[20:23], v[162:165], v[204:207], v[20:23]
	v_mfma_f32_16x16x32_bf16 v[16:19], v[170:173], v[204:207], v[16:19]
	v_mfma_f32_16x16x32_bf16 v[0:3], v[170:173], v[214:217], v[0:3]
	v_mfma_f32_16x16x32_bf16 v[4:7], v[162:165], v[214:217], v[4:7]
	s_setprio 0
	s_barrier
	s_add_u32 s57, s57, 0x100
	s_addc_u32 s58, s58, 0
	s_add_u32 s38, s38, 0x100
	s_addc_u32 s39, s39, 0
	s_cmp_ge_i32 s59, s50
	s_mov_b32 s40, s59
	s_cbranch_scc0 .LBB0_641
	v_readlane_b32 s42, v252, 12
	s_and_b64 vcc, exec, s[20:21]
	s_cbranch_vccnz .LBB0_646
	s_branch .LBB0_647

; #define PG8_STAGE(bufoff, gbase, voff) do { _Pragma("unroll") for (int _i = 0; _i < 2; ++_i) \
;         __builtin_amdgcn_global_load_lds((const unsigned*)((const char*)(gbase) + (voff)[_i]), (LAS unsigned*)(lds + (bufoff) + ldsw + _i * 8192), 16, 0, 0); } while (0)
; #define PG8_LDA(dst, b, h) do { _Pragma("unroll") for (int m = 0; m < 4; ++m) _Pragma("unroll") for (int k = 0; k < 2; ++k) dst[m][k] = *(const LAS bf16x8*)(lds + PG8_SA(b, h) + aoff + m * 2048 + k * 1024); } while (0)
; #define PG8_LDB(dst, b, h) do { _Pragma("unroll") for (int n = 0; n < 2; ++n) _Pragma("unroll") for (int k = 0; k < 2; ++k) dst[n][k] = *(const LAS bf16x8*)(lds + PG8_SB(b, h) + boff + n * 2048 + k * 1024); } while (0)
; #define PG8_MMA(ai, bj, At, Bt) do { __builtin_amdgcn_s_setprio(1); _Pragma("unroll") for (int m = 0; m < 4; ++m) _Pragma("unroll") for (int n = 0; n < 2; ++n) _Pragma("unroll") for (int k = 0; k < 2; ++k) \
;         acc[ai][bj][m][n] = __builtin_amdgcn_mfma_f32_16x16x32_bf16(Bt[n][k], At[m][k], acc[ai][bj][m][n], 0, 0, 0); __builtin_amdgcn_s_setprio(0); } while (0)
; #define PG8_WAIT_V(n) asm volatile("s_waitcnt vmcnt(" #n ")" ::: "memory")
; #define PG8_WAIT_L(n) asm volatile("s_waitcnt lgkmcnt(" #n ")" ::: "memory")
; #define PG8_BAR __builtin_amdgcn_s_barrier()
; #define PG8_SCHED __builtin_amdgcn_sched_barrier(0)
; template <class Epi, bool ALIGN_EPI>
; __device__ __forceinline__ void gemm_phase(LAS unsigned char* lds, const Gemm g, const StaticOrder& S, const Epi& E, const int wave_s) {
;     ...
;         for (int t = 0; t < nt; t += 2) {
;             const bool last = (t == nt - 2);
;             const char* a1 = cA + (size_t)(t + 1) * kstep;
;             const char* a2 = last ? nA : cA + (size_t)(t + 2) * kstep; const char* b2 = last ? nB : cB + (size_t)(t + 2) * kstep;
;             const char* a3 = a2 + kstep; const char* b3 = b2 + kstep;
;             PG8_LDB(B0, 0, 0); PG8_LDB(B1, 0, 1); PG8_SCHED; PG8_LDA(At, 0, 0); PG8_STAGE(PG8_SA(1, 1), a1 + hstepA, voffA);
;             PG8_WAIT_V(8); PG8_WAIT_L(0); PG8_BAR; PG8_MMA(0, 0, At, B0); PG8_MMA(0, 1, At, B1); PG8_BAR; PG8_SCHED;
;             PG8_LDA(At, 0, 1); PG8_STAGE(PG8_SB(0, 0), b2, voffB); PG8_STAGE(PG8_SB(0, 1), b2 + hstepB, voffB); PG8_STAGE(PG8_SA(0, 0), a2, voffA);
;             PG8_WAIT_V(8); PG8_WAIT_L(0); PG8_BAR; PG8_MMA(1, 0, At, B0); PG8_MMA(1, 1, At, B1); PG8_BAR; PG8_SCHED;
.LBB0_888:
	s_add_i32 s57, s42, 2
	s_add_u32 s58, s40, 0x80
	s_addc_u32 s43, s41, 0
	s_add_i32 s60, 0, 0x10000
	s_cmp_eq_u32 s49, s42
	s_cselect_b32 s43, s1, s43
	s_cselect_b32 s42, s0, s58
	s_cselect_b32 s59, s29, s56
	s_cselect_b32 s58, s28, s55
	s_add_i32 s61, 0, 0x14000
	v_add_u32_e32 v44, s60, v165
	v_add_u32_e32 v162, s61, v165
	ds_read_b128 v[24:27], v44
	ds_read_b128 v[28:31], v44 offset:1024
	ds_read_b128 v[40:43], v44 offset:2048
	ds_read_b128 v[44:47], v44 offset:3072
	ds_read_b128 v[154:157], v162
	ds_read_b128 v[158:161], v162 offset:1024
	ds_read_b128 v[170:173], v162 offset:2048
	ds_read_b128 v[174:177], v162 offset:3072
	v_lshl_add_u64 v[162:163], s[40:41], 0, v[152:153]
	s_add_i32 m0, s24, 0xc000
	ds_read_b128 v[178:181], v169
	ds_read_b128 v[188:191], v169 offset:1024
	ds_read_b128 v[192:195], v169 offset:2048
	ds_read_b128 v[196:199], v169 offset:3072
	ds_read_b128 v[200:203], v169 offset:4096
	ds_read_b128 v[204:207], v169 offset:5120
	ds_read_b128 v[208:211], v169 offset:6144
	ds_read_b128 v[212:215], v169 offset:7168
	global_load_lds_dwordx4 v[162:163], off
	v_lshl_add_u64 v[162:163], s[40:41], 0, v[150:151]
	s_add_i32 m0, s24, 0xe000
	s_nop 0
	global_load_lds_dwordx4 v[162:163], off
	s_waitcnt vmcnt(8)
	s_waitcnt lgkmcnt(0)
	s_barrier
	s_setprio 1
	s_waitcnt lgkmcnt(0)
	v_mfma_f32_16x16x32_bf16 v[140:143], v[24:27], v[178:181], v[140:143]
	v_mfma_f32_16x16x32_bf16 v[136:139], v[40:43], v[178:181], v[136:139]
	v_mfma_f32_16x16x32_bf16 v[120:123], v[40:43], v[192:195], v[120:123]
	v_mfma_f32_16x16x32_bf16 v[124:127], v[24:27], v[192:195], v[124:127]
	v_mfma_f32_16x16x32_bf16 v[108:111], v[24:27], v[200:203], v[108:111]
	v_mfma_f32_16x16x32_bf16 v[104:107], v[40:43], v[200:203], v[104:107]
	v_mfma_f32_16x16x32_bf16 v[88:91], v[40:43], v[208:211], v[88:91]
	v_mfma_f32_16x16x32_bf16 v[92:95], v[24:27], v[208:211], v[92:95]
	v_mfma_f32_16x16x32_bf16 v[140:143], v[28:31], v[188:191], v[140:143]
	v_mfma_f32_16x16x32_bf16 v[136:139], v[44:47], v[188:191], v[136:139]
	v_mfma_f32_16x16x32_bf16 v[120:123], v[44:47], v[196:199], v[120:123]
	v_mfma_f32_16x16x32_bf16 v[124:127], v[28:31], v[196:199], v[124:127]
	v_mfma_f32_16x16x32_bf16 v[108:111], v[28:31], v[204:207], v[108:111]
	v_mfma_f32_16x16x32_bf16 v[104:107], v[44:47], v[204:207], v[104:107]
	v_mfma_f32_16x16x32_bf16 v[88:91], v[44:47], v[212:215], v[88:91]
	v_mfma_f32_16x16x32_bf16 v[92:95], v[28:31], v[212:215], v[92:95]
	s_setprio 0
	s_setprio 1
	v_mfma_f32_16x16x32_bf16 v[132:135], v[154:157], v[178:181], v[132:135]
	v_mfma_f32_16x16x32_bf16 v[128:131], v[170:173], v[178:181], v[128:131]
	v_mfma_f32_16x16x32_bf16 v[112:115], v[170:173], v[192:195], v[112:115]
	v_mfma_f32_16x16x32_bf16 v[116:119], v[154:157], v[192:195], v[116:119]
	v_mfma_f32_16x16x32_bf16 v[100:103], v[154:157], v[200:203], v[100:103]
	v_mfma_f32_16x16x32_bf16 v[96:99], v[170:173], v[200:203], v[96:99]
	v_mfma_f32_16x16x32_bf16 v[80:83], v[170:173], v[208:211], v[80:83]
	v_mfma_f32_16x16x32_bf16 v[84:87], v[154:157], v[208:211], v[84:87]
	v_mfma_f32_16x16x32_bf16 v[132:135], v[158:161], v[188:191], v[132:135]
	v_mfma_f32_16x16x32_bf16 v[128:131], v[174:177], v[188:191], v[128:131]
	v_mfma_f32_16x16x32_bf16 v[112:115], v[174:177], v[196:199], v[112:115]
	v_mfma_f32_16x16x32_bf16 v[116:119], v[158:161], v[196:199], v[116:119]
	v_mfma_f32_16x16x32_bf16 v[100:103], v[158:161], v[204:207], v[100:103]
	v_mfma_f32_16x16x32_bf16 v[96:99], v[174:177], v[204:207], v[96:99]
	v_mfma_f32_16x16x32_bf16 v[80:83], v[174:177], v[212:215], v[80:83]
	v_mfma_f32_16x16x32_bf16 v[84:87], v[158:161], v[212:215], v[84:87]
	s_setprio 0
	s_barrier
	s_add_i32 s60, s60, s4
	v_lshl_add_u64 v[162:163], s[58:59], 0, v[184:185]
	s_mov_b32 m0, s60
	ds_read_b128 v[178:181], v169 offset:16384
	ds_read_b128 v[188:191], v169 offset:17408
	ds_read_b128 v[192:195], v169 offset:18432
	ds_read_b128 v[196:199], v169 offset:19456
	ds_read_b128 v[200:203], v169 offset:20480
	ds_read_b128 v[204:207], v169 offset:21504
	ds_read_b128 v[208:211], v169 offset:22528
	ds_read_b128 v[212:215], v169 offset:23552
	global_load_lds_dwordx4 v[162:163], off
	s_add_i32 m0, s60, 0x2000
	v_lshl_add_u64 v[182:183], s[58:59], 0, v[144:145]
	s_add_u32 s58, s58, s8
	s_addc_u32 s59, s59, s9
	s_add_i32 s60, s61, s4
	global_load_lds_dwordx4 v[182:183], off
	v_lshl_add_u64 v[216:217], s[58:59], 0, v[184:185]
	s_mov_b32 m0, s60
	v_lshl_add_u64 v[218:219], s[58:59], 0, v[144:145]
	global_load_lds_dwordx4 v[216:217], off
	s_add_i32 m0, s60, 0x2000
	v_lshl_add_u64 v[220:221], s[42:43], 0, v[148:149]
	global_load_lds_dwordx4 v[218:219], off
	s_mov_b32 m0, s24
	v_lshl_add_u64 v[222:223], s[42:43], 0, v[146:147]
	global_load_lds_dwordx4 v[220:221], off
	s_mov_b32 m0, s25
	s_nop 0
	global_load_lds_dwordx4 v[222:223], off
	s_waitcnt vmcnt(8)
	s_waitcnt lgkmcnt(0)
	s_barrier
; #define PG8_STAGE(bufoff, gbase, voff) do { _Pragma("unroll") for (int _i = 0; _i < 2; ++_i) \
;         __builtin_amdgcn_global_load_lds((const unsigned*)((const char*)(gbase) + (voff)[_i]), (LAS unsigned*)(lds + (bufoff) + ldsw + _i * 8192), 16, 0, 0); } while (0)
; #define PG8_LDA(dst, b, h) do { _Pragma("unroll") for (int m = 0; m < 4; ++m) _Pragma("unroll") for (int k = 0; k < 2; ++k) dst[m][k] = *(const LAS bf16x8*)(lds + PG8_SA(b, h) + aoff + m * 2048 + k * 1024); } while (0)
; #define PG8_LDB(dst, b, h) do { _Pragma("unroll") for (int n = 0; n < 2; ++n) _Pragma("unroll") for (int k = 0; k < 2; ++k) dst[n][k] = *(const LAS bf16x8*)(lds + PG8_SB(b, h) + boff + n * 2048 + k * 1024); } while (0)
; #define PG8_MMA(ai, bj, At, Bt) do { __builtin_amdgcn_s_setprio(1); _Pragma("unroll") for (int m = 0; m < 4; ++m) _Pragma("unroll") for (int n = 0; n < 2; ++n) _Pragma("unroll") for (int k = 0; k < 2; ++k) \
;         acc[ai][bj][m][n] = __builtin_amdgcn_mfma_f32_16x16x32_bf16(Bt[n][k], At[m][k], acc[ai][bj][m][n], 0, 0, 0); __builtin_amdgcn_s_setprio(0); } while (0)
; #define PG8_WAIT_V(n) asm volatile("s_waitcnt vmcnt(" #n ")" ::: "memory")
; #define PG8_WAIT_L(n) asm volatile("s_waitcnt lgkmcnt(" #n ")" ::: "memory")
; #define PG8_BAR __builtin_amdgcn_s_barrier()
; #define PG8_SCHED __builtin_amdgcn_sched_barrier(0)
; template <class Epi, bool ALIGN_EPI>
; __device__ __forceinline__ void gemm_phase(LAS unsigned char* lds, const Gemm g, const StaticOrder& S, const Epi& E, const int wave_s) {
;     ...
;             PG8_WAIT_V(8); PG8_WAIT_L(0); PG8_BAR; PG8_MMA(1, 0, At, B0); PG8_MMA(1, 1, At, B1); PG8_BAR; PG8_SCHED;
;             PG8_LDB(B0, 1, 0); PG8_LDB(B1, 1, 1); PG8_SCHED; PG8_LDA(At, 1, 0); PG8_STAGE(PG8_SA(0, 1), a2 + hstepA, voffA);
;             PG8_WAIT_V(8); PG8_WAIT_L(0); PG8_BAR; PG8_MMA(0, 0, At, B0); PG8_MMA(0, 1, At, B1); PG8_BAR; PG8_SCHED;
	s_setprio 1
	s_waitcnt lgkmcnt(0)
	v_mfma_f32_16x16x32_bf16 v[76:79], v[24:27], v[178:181], v[76:79]
	v_mfma_f32_16x16x32_bf16 v[72:75], v[40:43], v[178:181], v[72:75]
	v_mfma_f32_16x16x32_bf16 v[56:59], v[40:43], v[192:195], v[56:59]
	v_mfma_f32_16x16x32_bf16 v[60:63], v[24:27], v[192:195], v[60:63]
	v_mfma_f32_16x16x32_bf16 v[36:39], v[24:27], v[200:203], v[36:39]
	v_mfma_f32_16x16x32_bf16 v[32:35], v[40:43], v[200:203], v[32:35]
	v_mfma_f32_16x16x32_bf16 v[8:11], v[40:43], v[208:211], v[8:11]
	v_mfma_f32_16x16x32_bf16 v[12:15], v[24:27], v[208:211], v[12:15]
	v_mfma_f32_16x16x32_bf16 v[76:79], v[28:31], v[188:191], v[76:79]
	v_mfma_f32_16x16x32_bf16 v[72:75], v[44:47], v[188:191], v[72:75]
	v_mfma_f32_16x16x32_bf16 v[56:59], v[44:47], v[196:199], v[56:59]
	v_mfma_f32_16x16x32_bf16 v[60:63], v[28:31], v[196:199], v[60:63]
	v_mfma_f32_16x16x32_bf16 v[36:39], v[28:31], v[204:207], v[36:39]
	v_mfma_f32_16x16x32_bf16 v[32:35], v[44:47], v[204:207], v[32:35]
	v_mfma_f32_16x16x32_bf16 v[8:11], v[44:47], v[212:215], v[8:11]
	v_mfma_f32_16x16x32_bf16 v[12:15], v[28:31], v[212:215], v[12:15]
	s_setprio 0
	s_setprio 1
	v_mfma_f32_16x16x32_bf16 v[20:23], v[154:157], v[200:203], v[20:23]
	v_mfma_f32_16x16x32_bf16 v[16:19], v[170:173], v[200:203], v[16:19]
	v_mfma_f32_16x16x32_bf16 v[0:3], v[170:173], v[208:211], v[0:3]
	v_mfma_f32_16x16x32_bf16 v[4:7], v[154:157], v[208:211], v[4:7]
	v_mfma_f32_16x16x32_bf16 v[24:27], v[154:157], v[178:181], v[68:71]
	v_mfma_f32_16x16x32_bf16 v[28:31], v[170:173], v[178:181], v[64:67]
	v_mfma_f32_16x16x32_bf16 v[44:47], v[170:173], v[192:195], v[48:51]
	v_mfma_f32_16x16x32_bf16 v[40:43], v[154:157], v[192:195], v[52:55]
	v_mfma_f32_16x16x32_bf16 v[20:23], v[158:161], v[204:207], v[20:23]
	v_mfma_f32_16x16x32_bf16 v[16:19], v[174:177], v[204:207], v[16:19]
	v_mfma_f32_16x16x32_bf16 v[0:3], v[174:177], v[212:215], v[0:3]
	v_mfma_f32_16x16x32_bf16 v[4:7], v[158:161], v[212:215], v[4:7]
	v_mfma_f32_16x16x32_bf16 v[24:27], v[158:161], v[188:191], v[24:27]
	v_mfma_f32_16x16x32_bf16 v[28:31], v[174:177], v[188:191], v[28:31]
	v_mfma_f32_16x16x32_bf16 v[44:47], v[174:177], v[196:199], v[44:47]
	v_mfma_f32_16x16x32_bf16 v[40:43], v[158:161], v[196:199], v[40:43]
	s_setprio 0
	s_barrier
	s_add_i32 s58, 0, 0x18000
	s_add_i32 s59, 0, 0x1c000
	v_add_u32_e32 v68, s58, v165
	v_add_u32_e32 v174, s59, v165
	ds_read_b128 v[48:51], v68
	ds_read_b128 v[52:55], v68 offset:1024
	ds_read_b128 v[64:67], v68 offset:2048
	ds_read_b128 v[68:71], v68 offset:3072
	ds_read_b128 v[154:157], v174
	ds_read_b128 v[158:161], v174 offset:1024
	ds_read_b128 v[170:173], v174 offset:2048
	ds_read_b128 v[174:177], v174 offset:3072
	s_add_u32 s42, s42, s6
	s_addc_u32 s43, s43, s7
	s_mov_b32 m0, s44
	v_lshl_add_u64 v[224:225], s[42:43], 0, v[148:149]
	ds_read_b128 v[178:181], v169 offset:32768
	ds_read_b128 v[188:191], v169 offset:33792
	ds_read_b128 v[192:195], v169 offset:34816
	ds_read_b128 v[196:199], v169 offset:35840
	ds_read_b128 v[200:203], v169 offset:36864
	ds_read_b128 v[204:207], v169 offset:37888
	ds_read_b128 v[208:211], v169 offset:38912
	ds_read_b128 v[212:215], v169 offset:39936
	global_load_lds_dwordx4 v[224:225], off
	v_lshl_add_u64 v[224:225], s[42:43], 0, v[146:147]
	s_mov_b32 m0, s45
	s_nop 0
	global_load_lds_dwordx4 v[224:225], off
	s_waitcnt vmcnt(8)
	s_waitcnt lgkmcnt(0)
	s_barrier
	s_setprio 1
	s_waitcnt lgkmcnt(0)
	v_mfma_f32_16x16x32_bf16 v[140:143], v[48:51], v[178:181], v[140:143]
	v_mfma_f32_16x16x32_bf16 v[136:139], v[64:67], v[178:181], v[136:139]
	v_mfma_f32_16x16x32_bf16 v[120:123], v[64:67], v[192:195], v[120:123]
	v_mfma_f32_16x16x32_bf16 v[124:127], v[48:51], v[192:195], v[124:127]
	v_mfma_f32_16x16x32_bf16 v[108:111], v[48:51], v[200:203], v[108:111]
	v_mfma_f32_16x16x32_bf16 v[104:107], v[64:67], v[200:203], v[104:107]
	v_mfma_f32_16x16x32_bf16 v[88:91], v[64:67], v[208:211], v[88:91]
	v_mfma_f32_16x16x32_bf16 v[92:95], v[48:51], v[208:211], v[92:95]
	v_mfma_f32_16x16x32_bf16 v[140:143], v[52:55], v[188:191], v[140:143]
	v_mfma_f32_16x16x32_bf16 v[136:139], v[68:71], v[188:191], v[136:139]
	v_mfma_f32_16x16x32_bf16 v[120:123], v[68:71], v[196:199], v[120:123]
	v_mfma_f32_16x16x32_bf16 v[124:127], v[52:55], v[196:199], v[124:127]
	v_mfma_f32_16x16x32_bf16 v[108:111], v[52:55], v[204:207], v[108:111]
	v_mfma_f32_16x16x32_bf16 v[104:107], v[68:71], v[204:207], v[104:107]
	v_mfma_f32_16x16x32_bf16 v[88:91], v[68:71], v[212:215], v[88:91]
	v_mfma_f32_16x16x32_bf16 v[92:95], v[52:55], v[212:215], v[92:95]
	s_setprio 0
	s_setprio 1
	v_mfma_f32_16x16x32_bf16 v[132:135], v[154:157], v[178:181], v[132:135]
	v_mfma_f32_16x16x32_bf16 v[128:131], v[170:173], v[178:181], v[128:131]
	v_mfma_f32_16x16x32_bf16 v[112:115], v[170:173], v[192:195], v[112:115]
	v_mfma_f32_16x16x32_bf16 v[116:119], v[154:157], v[192:195], v[116:119]
	v_mfma_f32_16x16x32_bf16 v[100:103], v[154:157], v[200:203], v[100:103]
	v_mfma_f32_16x16x32_bf16 v[96:99], v[170:173], v[200:203], v[96:99]
	v_mfma_f32_16x16x32_bf16 v[80:83], v[170:173], v[208:211], v[80:83]
	v_mfma_f32_16x16x32_bf16 v[84:87], v[154:157], v[208:211], v[84:87]
	v_mfma_f32_16x16x32_bf16 v[132:135], v[158:161], v[188:191], v[132:135]
	v_mfma_f32_16x16x32_bf16 v[128:131], v[174:177], v[188:191], v[128:131]
	v_mfma_f32_16x16x32_bf16 v[112:115], v[174:177], v[196:199], v[112:115]
	v_mfma_f32_16x16x32_bf16 v[116:119], v[158:161], v[196:199], v[116:119]
	v_mfma_f32_16x16x32_bf16 v[100:103], v[158:161], v[204:207], v[100:103]
	v_mfma_f32_16x16x32_bf16 v[96:99], v[174:177], v[204:207], v[96:99]
	v_mfma_f32_16x16x32_bf16 v[80:83], v[174:177], v[212:215], v[80:83]
	v_mfma_f32_16x16x32_bf16 v[84:87], v[158:161], v[212:215], v[84:87]
	s_setprio 0
	s_barrier
; #define PG8_STAGE(bufoff, gbase, voff) do { _Pragma("unroll") for (int _i = 0; _i < 2; ++_i) \
;         __builtin_amdgcn_global_load_lds((const unsigned*)((const char*)(gbase) + (voff)[_i]), (LAS unsigned*)(lds + (bufoff) + ldsw + _i * 8192), 16, 0, 0); } while (0)
; #define PG8_LDA(dst, b, h) do { _Pragma("unroll") for (int m = 0; m < 4; ++m) _Pragma("unroll") for (int k = 0; k < 2; ++k) dst[m][k] = *(const LAS bf16x8*)(lds + PG8_SA(b, h) + aoff + m * 2048 + k * 1024); } while (0)
; #define PG8_MMA(ai, bj, At, Bt) do { __builtin_amdgcn_s_setprio(1); _Pragma("unroll") for (int m = 0; m < 4; ++m) _Pragma("unroll") for (int n = 0; n < 2; ++n) _Pragma("unroll") for (int k = 0; k < 2; ++k) \
;         acc[ai][bj][m][n] = __builtin_amdgcn_mfma_f32_16x16x32_bf16(Bt[n][k], At[m][k], acc[ai][bj][m][n], 0, 0, 0); __builtin_amdgcn_s_setprio(0); } while (0)
; #define PG8_WAIT_V(n) asm volatile("s_waitcnt vmcnt(" #n ")" ::: "memory")
; #define PG8_WAIT_L(n) asm volatile("s_waitcnt lgkmcnt(" #n ")" ::: "memory")
; #define PG8_BAR __builtin_amdgcn_s_barrier()
; #define PG8_SCHED __builtin_amdgcn_sched_barrier(0)
; template <class Epi, bool ALIGN_EPI>
; __device__ __forceinline__ void gemm_phase(LAS unsigned char* lds, const Gemm g, const StaticOrder& S, const Epi& E, const int wave_s) {
;     ...
;             PG8_LDA(At, 1, 1); PG8_STAGE(PG8_SB(1, 0), b3, voffB); PG8_STAGE(PG8_SB(1, 1), b3 + hstepB, voffB); PG8_STAGE(PG8_SA(1, 0), a3, voffA);
;             PG8_WAIT_V(8); PG8_WAIT_L(0); PG8_BAR; PG8_MMA(1, 0, At, B0); PG8_MMA(1, 1, At, B1); PG8_BAR; PG8_SCHED;
;         }
	s_add_i32 s42, s58, s4
	v_lshl_add_u64 v[162:163], v[162:163], 0, s[64:65]
	s_mov_b32 m0, s42
	ds_read_b128 v[178:181], v169 offset:49152
	ds_read_b128 v[188:191], v169 offset:50176
	ds_read_b128 v[192:195], v169 offset:51200
	ds_read_b128 v[196:199], v169 offset:52224
	ds_read_b128 v[200:203], v169 offset:53248
	ds_read_b128 v[204:207], v169 offset:54272
	ds_read_b128 v[208:211], v169 offset:55296
	ds_read_b128 v[212:215], v169 offset:56320
	global_load_lds_dwordx4 v[162:163], off
	v_lshl_add_u64 v[162:163], v[182:183], 0, s[64:65]
	s_add_i32 m0, s42, 0x2000
	s_add_i32 s42, s59, s4
	global_load_lds_dwordx4 v[162:163], off
	v_lshl_add_u64 v[162:163], v[216:217], 0, s[64:65]
	s_mov_b32 m0, s42
	s_nop 0
	global_load_lds_dwordx4 v[162:163], off
	v_lshl_add_u64 v[162:163], v[218:219], 0, s[64:65]
	s_add_i32 m0, s42, 0x2000
	s_nop 0
	global_load_lds_dwordx4 v[162:163], off
	v_lshl_add_u64 v[162:163], v[220:221], 0, s[64:65]
	s_mov_b32 m0, s46
	s_nop 0
	global_load_lds_dwordx4 v[162:163], off
	v_lshl_add_u64 v[162:163], v[222:223], 0, s[64:65]
	s_mov_b32 m0, s47
	s_nop 0
	global_load_lds_dwordx4 v[162:163], off
	s_waitcnt vmcnt(8)
	s_waitcnt lgkmcnt(0)
	s_barrier
	s_setprio 1
	s_waitcnt lgkmcnt(0)
	v_mfma_f32_16x16x32_bf16 v[76:79], v[48:51], v[178:181], v[76:79]
	v_mfma_f32_16x16x32_bf16 v[72:75], v[64:67], v[178:181], v[72:75]
	v_mfma_f32_16x16x32_bf16 v[56:59], v[64:67], v[192:195], v[56:59]
	v_mfma_f32_16x16x32_bf16 v[60:63], v[48:51], v[192:195], v[60:63]
	v_mfma_f32_16x16x32_bf16 v[36:39], v[48:51], v[200:203], v[36:39]
	v_mfma_f32_16x16x32_bf16 v[32:35], v[64:67], v[200:203], v[32:35]
	v_mfma_f32_16x16x32_bf16 v[8:11], v[64:67], v[208:211], v[8:11]
	v_mfma_f32_16x16x32_bf16 v[12:15], v[48:51], v[208:211], v[12:15]
	v_mfma_f32_16x16x32_bf16 v[76:79], v[52:55], v[188:191], v[76:79]
	v_mfma_f32_16x16x32_bf16 v[72:75], v[68:71], v[188:191], v[72:75]
	v_mfma_f32_16x16x32_bf16 v[56:59], v[68:71], v[196:199], v[56:59]
	v_mfma_f32_16x16x32_bf16 v[60:63], v[52:55], v[196:199], v[60:63]
	v_mfma_f32_16x16x32_bf16 v[36:39], v[52:55], v[204:207], v[36:39]
	v_mfma_f32_16x16x32_bf16 v[32:35], v[68:71], v[204:207], v[32:35]
	v_mfma_f32_16x16x32_bf16 v[8:11], v[68:71], v[212:215], v[8:11]
	v_mfma_f32_16x16x32_bf16 v[12:15], v[52:55], v[212:215], v[12:15]
	s_setprio 0
	s_setprio 1
	v_mfma_f32_16x16x32_bf16 v[24:27], v[154:157], v[178:181], v[24:27]
	v_mfma_f32_16x16x32_bf16 v[68:71], v[158:161], v[188:191], v[24:27]
	v_mfma_f32_16x16x32_bf16 v[24:27], v[170:173], v[178:181], v[28:31]
	v_mfma_f32_16x16x32_bf16 v[64:67], v[174:177], v[188:191], v[24:27]
	v_mfma_f32_16x16x32_bf16 v[24:27], v[154:157], v[192:195], v[40:43]
	v_mfma_f32_16x16x32_bf16 v[52:55], v[158:161], v[196:199], v[24:27]
	v_mfma_f32_16x16x32_bf16 v[24:27], v[170:173], v[192:195], v[44:47]
	v_mfma_f32_16x16x32_bf16 v[20:23], v[154:157], v[200:203], v[20:23]
	v_mfma_f32_16x16x32_bf16 v[16:19], v[170:173], v[200:203], v[16:19]
	v_mfma_f32_16x16x32_bf16 v[4:7], v[154:157], v[208:211], v[4:7]
	v_mfma_f32_16x16x32_bf16 v[0:3], v[170:173], v[208:211], v[0:3]
	v_mfma_f32_16x16x32_bf16 v[48:51], v[174:177], v[196:199], v[24:27]
	v_mfma_f32_16x16x32_bf16 v[20:23], v[158:161], v[204:207], v[20:23]
	v_mfma_f32_16x16x32_bf16 v[16:19], v[174:177], v[204:207], v[16:19]
	v_mfma_f32_16x16x32_bf16 v[0:3], v[174:177], v[212:215], v[0:3]
	v_mfma_f32_16x16x32_bf16 v[4:7], v[158:161], v[212:215], v[4:7]
	s_setprio 0
	s_barrier
	s_add_u32 s55, s55, 0x100
	s_addc_u32 s56, s56, 0
	s_add_u32 s40, s40, 0x100
	s_addc_u32 s41, s41, 0
	s_cmp_ge_i32 s57, s48
	s_mov_b32 s42, s57
	s_cbranch_scc0 .LBB0_888
	s_mov_b64 s[58:59], 0x90000
	v_readlane_b32 s60, v252, 12
	s_and_b64 vcc, exec, s[20:21]
	s_cbranch_vccnz .LBB0_893
	s_branch .LBB0_894
